# PV-MFMA hoist + GEMM loops wait vmcnt(6) instead of vmcnt(8) before each barrier (stricter counted wait)
# baseline (speedup 1.0000x reference)
; #define PG8_STAGE(bufoff, gbase, voff) do { _Pragma("unroll") for (int _i = 0; _i < 2; ++_i) \
;         __builtin_amdgcn_global_load_lds((const unsigned*)((const char*)(gbase) + (voff)[_i]), (PG8_LAS unsigned*)(lds + (bufoff) + ldsw + _i * 8192), 16, 0, 0); } while (0)
; #define PG8_LDA(dst, b, h) do { _Pragma("unroll") for (int m = 0; m < 4; ++m) _Pragma("unroll") for (int k = 0; k < 2; ++k) dst[m][k] = *(const PG8_LAS bf16x8*)(lds + PG8_SA(b, h) + aoff + m * 2048 + k * 1024); } while (0)
; #define PG8_LDB(dst, b, h) do { _Pragma("unroll") for (int n = 0; n < 2; ++n) _Pragma("unroll") for (int k = 0; k < 2; ++k) dst[n][k] = *(const PG8_LAS bf16x8*)(lds + PG8_SB(b, h) + boff + n * 2048 + k * 1024); } while (0)
; #define PG8_MMA(ai, bj, At, Bt) do { __builtin_amdgcn_s_setprio(1); _Pragma("unroll") for (int m = 0; m < 4; ++m) _Pragma("unroll") for (int n = 0; n < 2; ++n) _Pragma("unroll") for (int k = 0; k < 2; ++k) \
;         acc[ai][bj][m][n] = __builtin_amdgcn_mfma_f32_16x16x32_bf16(Bt[n][k], At[m][k], acc[ai][bj][m][n], 0, 0, 0); __builtin_amdgcn_s_setprio(0); } while (0)
; #define PG8_WAIT_V(n) asm volatile("s_waitcnt vmcnt(" #n ")" ::: "memory")
; #define PG8_WAIT_L(n) asm volatile("s_waitcnt lgkmcnt(" #n ")" ::: "memory")
; #define PG8_BAR __builtin_amdgcn_s_barrier()
; #define PG8_SCHED __builtin_amdgcn_sched_barrier(0)
; template <class Epi, class Sched, bool ALIGN_EPI = false, bool SP2 = false>
; __device__ __forceinline__ void gemm_phase(PG8_LAS unsigned char* lds, const Gemm g, const Sched& S, const Epi& E) {
;     ...
;         for (int t = 0; t < nt; t += 2) {
;             const bool last = (t == nt - 2);
;             const char* a1 = cA + (size_t)(t + 1) * kstep;
;             const char* a2 = last ? nA : cA + (size_t)(t + 2) * kstep; const char* b2 = last ? nB : cB + (size_t)(t + 2) * kstep;
;             const char* a3 = a2 + kstep; const char* b3 = b2 + kstep;
;             if (last && has_next) S.a_ready(nxt);
;             if constexpr (SP2) {
;             PG8_LDB(B0, 0, 0); PG8_LDB(B1, 0, 1); PG8_SCHED; PG8_LDA(At, 0, 0); PG8_STAGE(PG8_SA(1, 1), a1 + hstep, voffA);
;             PG8_WAIT_V(8); PG8_WAIT_L(0); PG8_BAR; PG8_MMA(0, 0, At, B0); PG8_MMA(0, 1, At, B1); PG8_BAR; PG8_SCHED;
;             PG8_LDA(At, 0, 1); PG8_STAGE(PG8_SB(0, 0), b2, voffB); PG8_STAGE(PG8_SB(0, 1), b2 + hstep, voffB); PG8_STAGE(PG8_SA(0, 0), a2, voffA);
.LBB0_124:
	ds_read_b128 v[144:147], v151
	ds_read_b128 v[154:157], v151 offset:1024
	ds_read_b128 v[158:161], v151 offset:2048
	ds_read_b128 v[162:165], v151 offset:3072
	ds_read_b128 v[166:169], v152
	ds_read_b128 v[170:173], v152 offset:1024
	ds_read_b128 v[174:177], v152 offset:2048
	ds_read_b128 v[178:181], v152 offset:3072
	s_add_u32 s22, s20, 0xfffc0080
	s_addc_u32 s23, s21, -1
	s_cmp_eq_u32 s49, 12
	s_cselect_b32 s25, s13, s23
	s_cselect_b32 s24, s45, s22
	s_cselect_b32 s23, s11, s48
	s_cselect_b32 s22, s46, s47
	v_lshl_add_u64 v[182:183], s[20:21], 0, v[138:139]
	s_add_i32 m0, s19, 0xc000
	ds_read_b128 v[186:189], v153
	ds_read_b128 v[190:193], v153 offset:1024
	ds_read_b128 v[194:197], v153 offset:2048
	ds_read_b128 v[198:201], v153 offset:3072
	ds_read_b128 v[202:205], v153 offset:4096
	ds_read_b128 v[206:209], v153 offset:5120
	ds_read_b128 v[210:213], v153 offset:6144
	ds_read_b128 v[214:217], v153 offset:7168
	global_load_lds_dwordx4 v[182:183], off
	v_lshl_add_u64 v[182:183], s[20:21], 0, v[136:137]
	s_add_i32 m0, s19, 0xe000
	s_nop 0
	global_load_lds_dwordx4 v[182:183], off
	s_waitcnt vmcnt(6)
	s_waitcnt lgkmcnt(0)
	s_barrier
	s_setprio 1
	s_waitcnt lgkmcnt(0)
	v_mfma_f32_16x16x32_bf16 v[124:127], v[144:147], v[186:189], v[124:127]
	v_mfma_f32_16x16x32_bf16 v[116:119], v[158:161], v[186:189], v[116:119]
	v_mfma_f32_16x16x32_bf16 v[108:111], v[144:147], v[194:197], v[108:111]
	v_mfma_f32_16x16x32_bf16 v[100:103], v[158:161], v[194:197], v[100:103]
	v_mfma_f32_16x16x32_bf16 v[92:95], v[144:147], v[202:205], v[92:95]
	v_mfma_f32_16x16x32_bf16 v[84:87], v[158:161], v[202:205], v[84:87]
	v_mfma_f32_16x16x32_bf16 v[76:79], v[144:147], v[210:213], v[76:79]
	v_mfma_f32_16x16x32_bf16 v[68:71], v[158:161], v[210:213], v[68:71]
	v_mfma_f32_16x16x32_bf16 v[124:127], v[154:157], v[190:193], v[124:127]
	v_mfma_f32_16x16x32_bf16 v[116:119], v[162:165], v[190:193], v[116:119]
	v_mfma_f32_16x16x32_bf16 v[108:111], v[154:157], v[198:201], v[108:111]
	v_mfma_f32_16x16x32_bf16 v[100:103], v[162:165], v[198:201], v[100:103]
	v_mfma_f32_16x16x32_bf16 v[92:95], v[154:157], v[206:209], v[92:95]
	v_mfma_f32_16x16x32_bf16 v[84:87], v[162:165], v[206:209], v[84:87]
	v_mfma_f32_16x16x32_bf16 v[76:79], v[154:157], v[214:217], v[76:79]
	v_mfma_f32_16x16x32_bf16 v[68:71], v[162:165], v[214:217], v[68:71]
	s_setprio 0
	s_setprio 1
	v_mfma_f32_16x16x32_bf16 v[120:123], v[166:169], v[186:189], v[120:123]
	v_mfma_f32_16x16x32_bf16 v[112:115], v[174:177], v[186:189], v[112:115]
	v_mfma_f32_16x16x32_bf16 v[104:107], v[166:169], v[194:197], v[104:107]
	v_mfma_f32_16x16x32_bf16 v[96:99], v[174:177], v[194:197], v[96:99]
	v_mfma_f32_16x16x32_bf16 v[88:91], v[166:169], v[202:205], v[88:91]
	v_mfma_f32_16x16x32_bf16 v[80:83], v[174:177], v[202:205], v[80:83]
	v_mfma_f32_16x16x32_bf16 v[72:75], v[166:169], v[210:213], v[72:75]
	v_mfma_f32_16x16x32_bf16 v[64:67], v[174:177], v[210:213], v[64:67]
	v_mfma_f32_16x16x32_bf16 v[120:123], v[170:173], v[190:193], v[120:123]
	v_mfma_f32_16x16x32_bf16 v[112:115], v[178:181], v[190:193], v[112:115]
	v_mfma_f32_16x16x32_bf16 v[104:107], v[170:173], v[198:201], v[104:107]
	v_mfma_f32_16x16x32_bf16 v[96:99], v[178:181], v[198:201], v[96:99]
	v_mfma_f32_16x16x32_bf16 v[88:91], v[170:173], v[206:209], v[88:91]
	v_mfma_f32_16x16x32_bf16 v[80:83], v[178:181], v[206:209], v[80:83]
	v_mfma_f32_16x16x32_bf16 v[72:75], v[170:173], v[214:217], v[72:75]
	v_mfma_f32_16x16x32_bf16 v[64:67], v[178:181], v[214:217], v[64:67]
	s_setprio 0
	s_barrier
	s_add_i32 s50, s41, s31
	v_lshl_add_u64 v[182:183], s[22:23], 0, v[130:131]
	s_mov_b32 m0, s50
	ds_read_b128 v[186:189], v153 offset:16384
	ds_read_b128 v[190:193], v153 offset:17408
	ds_read_b128 v[194:197], v153 offset:18432
	ds_read_b128 v[198:201], v153 offset:19456
	ds_read_b128 v[202:205], v153 offset:20480
	ds_read_b128 v[206:209], v153 offset:21504
	ds_read_b128 v[210:213], v153 offset:22528
	ds_read_b128 v[214:217], v153 offset:23552
	global_load_lds_dwordx4 v[182:183], off
	s_add_i32 m0, s50, 0x2000
	s_add_u32 s50, s22, 0x40000
	v_lshl_add_u64 v[218:219], s[22:23], 0, v[134:135]
	s_addc_u32 s51, s23, 0
	s_add_i32 s52, s42, s31
	global_load_lds_dwordx4 v[218:219], off
	v_lshl_add_u64 v[220:221], s[50:51], 0, v[130:131]
	s_mov_b32 m0, s52
	v_lshl_add_u64 v[222:223], s[24:25], 0, v[132:133]
	global_load_lds_dwordx4 v[220:221], off
	v_lshl_add_u64 v[220:221], s[50:51], 0, v[134:135]
	s_add_i32 m0, s52, 0x2000
	s_nop 0
	global_load_lds_dwordx4 v[220:221], off
	v_lshl_add_u64 v[220:221], s[24:25], 0, v[128:129]
	s_mov_b32 m0, s19
	s_nop 0
	global_load_lds_dwordx4 v[220:221], off
	s_mov_b32 m0, s33
	s_nop 0
	global_load_lds_dwordx4 v[222:223], off
	s_waitcnt vmcnt(6)
	s_waitcnt lgkmcnt(0)
	s_barrier
; #define PG8_STAGE(bufoff, gbase, voff) do { _Pragma("unroll") for (int _i = 0; _i < 2; ++_i) \
;         __builtin_amdgcn_global_load_lds((const unsigned*)((const char*)(gbase) + (voff)[_i]), (PG8_LAS unsigned*)(lds + (bufoff) + ldsw + _i * 8192), 16, 0, 0); } while (0)
; #define PG8_LDA(dst, b, h) do { _Pragma("unroll") for (int m = 0; m < 4; ++m) _Pragma("unroll") for (int k = 0; k < 2; ++k) dst[m][k] = *(const PG8_LAS bf16x8*)(lds + PG8_SA(b, h) + aoff + m * 2048 + k * 1024); } while (0)
; #define PG8_LDB(dst, b, h) do { _Pragma("unroll") for (int n = 0; n < 2; ++n) _Pragma("unroll") for (int k = 0; k < 2; ++k) dst[n][k] = *(const PG8_LAS bf16x8*)(lds + PG8_SB(b, h) + boff + n * 2048 + k * 1024); } while (0)
; #define PG8_MMA(ai, bj, At, Bt) do { __builtin_amdgcn_s_setprio(1); _Pragma("unroll") for (int m = 0; m < 4; ++m) _Pragma("unroll") for (int n = 0; n < 2; ++n) _Pragma("unroll") for (int k = 0; k < 2; ++k) \
;         acc[ai][bj][m][n] = __builtin_amdgcn_mfma_f32_16x16x32_bf16(Bt[n][k], At[m][k], acc[ai][bj][m][n], 0, 0, 0); __builtin_amdgcn_s_setprio(0); } while (0)
; #define PG8_WAIT_V(n) asm volatile("s_waitcnt vmcnt(" #n ")" ::: "memory")
; #define PG8_WAIT_L(n) asm volatile("s_waitcnt lgkmcnt(" #n ")" ::: "memory")
; #define PG8_BAR __builtin_amdgcn_s_barrier()
; #define PG8_SCHED __builtin_amdgcn_sched_barrier(0)
; template <class Epi, class Sched, bool ALIGN_EPI = false, bool SP2 = false>
; __device__ __forceinline__ void gemm_phase(PG8_LAS unsigned char* lds, const Gemm g, const Sched& S, const Epi& E) {
;     ...
;             PG8_WAIT_V(8); PG8_WAIT_L(0); PG8_BAR; PG8_MMA(1, 0, At, B0); PG8_MMA(1, 1, At, B1); PG8_BAR; PG8_SCHED;
;             PG8_LDB(B0, 1, 0); PG8_LDB(B1, 1, 1); PG8_SCHED; PG8_LDA(At, 1, 0); PG8_STAGE(PG8_SA(0, 1), a2 + hstep, voffA);
;             PG8_WAIT_V(8); PG8_WAIT_L(0); PG8_BAR; PG8_MMA(0, 0, At, B0); PG8_MMA(0, 1, At, B1); PG8_BAR; PG8_SCHED;
	s_setprio 1
	s_waitcnt lgkmcnt(0)
	v_mfma_f32_16x16x32_bf16 v[60:63], v[144:147], v[186:189], v[60:63]
	v_mfma_f32_16x16x32_bf16 v[52:55], v[158:161], v[186:189], v[52:55]
	v_mfma_f32_16x16x32_bf16 v[44:47], v[144:147], v[194:197], v[44:47]
	v_mfma_f32_16x16x32_bf16 v[36:39], v[158:161], v[194:197], v[36:39]
	v_mfma_f32_16x16x32_bf16 v[28:31], v[144:147], v[202:205], v[28:31]
	v_mfma_f32_16x16x32_bf16 v[20:23], v[158:161], v[202:205], v[20:23]
	v_mfma_f32_16x16x32_bf16 v[12:15], v[144:147], v[210:213], v[12:15]
	v_mfma_f32_16x16x32_bf16 v[4:7], v[158:161], v[210:213], v[4:7]
	v_mfma_f32_16x16x32_bf16 v[60:63], v[154:157], v[190:193], v[60:63]
	v_mfma_f32_16x16x32_bf16 v[52:55], v[162:165], v[190:193], v[52:55]
	v_mfma_f32_16x16x32_bf16 v[44:47], v[154:157], v[198:201], v[44:47]
	v_mfma_f32_16x16x32_bf16 v[36:39], v[162:165], v[198:201], v[36:39]
	v_mfma_f32_16x16x32_bf16 v[28:31], v[154:157], v[206:209], v[28:31]
	v_mfma_f32_16x16x32_bf16 v[20:23], v[162:165], v[206:209], v[20:23]
	v_mfma_f32_16x16x32_bf16 v[12:15], v[154:157], v[214:217], v[12:15]
	v_mfma_f32_16x16x32_bf16 v[4:7], v[162:165], v[214:217], v[4:7]
	s_setprio 0
	s_setprio 1
	v_mfma_f32_16x16x32_bf16 v[56:59], v[166:169], v[186:189], v[56:59]
	v_mfma_f32_16x16x32_bf16 v[48:51], v[174:177], v[186:189], v[48:51]
	v_mfma_f32_16x16x32_bf16 v[40:43], v[166:169], v[194:197], v[40:43]
	v_mfma_f32_16x16x32_bf16 v[32:35], v[174:177], v[194:197], v[32:35]
	v_mfma_f32_16x16x32_bf16 v[24:27], v[166:169], v[202:205], v[24:27]
	v_mfma_f32_16x16x32_bf16 v[16:19], v[174:177], v[202:205], v[16:19]
	v_mfma_f32_16x16x32_bf16 v[8:11], v[166:169], v[210:213], v[8:11]
	v_mfma_f32_16x16x32_bf16 v[0:3], v[174:177], v[210:213], v[0:3]
	v_mfma_f32_16x16x32_bf16 v[56:59], v[170:173], v[190:193], v[56:59]
	v_mfma_f32_16x16x32_bf16 v[48:51], v[178:181], v[190:193], v[48:51]
	v_mfma_f32_16x16x32_bf16 v[40:43], v[170:173], v[198:201], v[40:43]
	v_mfma_f32_16x16x32_bf16 v[32:35], v[178:181], v[198:201], v[32:35]
	v_mfma_f32_16x16x32_bf16 v[24:27], v[170:173], v[206:209], v[24:27]
	v_mfma_f32_16x16x32_bf16 v[16:19], v[178:181], v[206:209], v[16:19]
	v_mfma_f32_16x16x32_bf16 v[8:11], v[170:173], v[214:217], v[8:11]
	v_mfma_f32_16x16x32_bf16 v[0:3], v[178:181], v[214:217], v[0:3]
	s_setprio 0
	s_barrier
	s_add_i32 s50, 0, 0x18000
	s_add_i32 s51, 0, 0x1c000
	v_add_u32_e32 v162, s50, v149
	v_add_u32_e32 v178, s51, v149
	ds_read_b128 v[144:147], v162
	ds_read_b128 v[154:157], v162 offset:1024
	ds_read_b128 v[158:161], v162 offset:2048
	ds_read_b128 v[162:165], v162 offset:3072
	ds_read_b128 v[166:169], v178
	ds_read_b128 v[170:173], v178 offset:1024
	ds_read_b128 v[174:177], v178 offset:2048
	ds_read_b128 v[178:181], v178 offset:3072
	s_add_u32 s24, s24, 0x40000
	s_addc_u32 s25, s25, 0
	s_mov_b32 m0, s34
	v_lshl_add_u64 v[224:225], s[24:25], 0, v[128:129]
	ds_read_b128 v[186:189], v153 offset:32768
	ds_read_b128 v[190:193], v153 offset:33792
	ds_read_b128 v[194:197], v153 offset:34816
	ds_read_b128 v[198:201], v153 offset:35840
	ds_read_b128 v[202:205], v153 offset:36864
	ds_read_b128 v[206:209], v153 offset:37888
	ds_read_b128 v[210:213], v153 offset:38912
	ds_read_b128 v[214:217], v153 offset:39936
	global_load_lds_dwordx4 v[224:225], off
	v_lshl_add_u64 v[224:225], s[24:25], 0, v[132:133]
	s_mov_b32 m0, s35
	s_nop 0
	global_load_lds_dwordx4 v[224:225], off
	s_waitcnt vmcnt(6)
	s_waitcnt lgkmcnt(0)
	s_barrier
	s_setprio 1
	s_waitcnt lgkmcnt(0)
	v_mfma_f32_16x16x32_bf16 v[124:127], v[144:147], v[186:189], v[124:127]
	v_mfma_f32_16x16x32_bf16 v[116:119], v[158:161], v[186:189], v[116:119]
	v_mfma_f32_16x16x32_bf16 v[108:111], v[144:147], v[194:197], v[108:111]
	v_mfma_f32_16x16x32_bf16 v[100:103], v[158:161], v[194:197], v[100:103]
	v_mfma_f32_16x16x32_bf16 v[92:95], v[144:147], v[202:205], v[92:95]
	v_mfma_f32_16x16x32_bf16 v[84:87], v[158:161], v[202:205], v[84:87]
	v_mfma_f32_16x16x32_bf16 v[76:79], v[144:147], v[210:213], v[76:79]
	v_mfma_f32_16x16x32_bf16 v[68:71], v[158:161], v[210:213], v[68:71]
	v_mfma_f32_16x16x32_bf16 v[124:127], v[154:157], v[190:193], v[124:127]
	v_mfma_f32_16x16x32_bf16 v[116:119], v[162:165], v[190:193], v[116:119]
	v_mfma_f32_16x16x32_bf16 v[108:111], v[154:157], v[198:201], v[108:111]
	v_mfma_f32_16x16x32_bf16 v[100:103], v[162:165], v[198:201], v[100:103]
	v_mfma_f32_16x16x32_bf16 v[92:95], v[154:157], v[206:209], v[92:95]
	v_mfma_f32_16x16x32_bf16 v[84:87], v[162:165], v[206:209], v[84:87]
	v_mfma_f32_16x16x32_bf16 v[76:79], v[154:157], v[214:217], v[76:79]
	v_mfma_f32_16x16x32_bf16 v[68:71], v[162:165], v[214:217], v[68:71]
	s_setprio 0
	s_setprio 1
	v_mfma_f32_16x16x32_bf16 v[120:123], v[166:169], v[186:189], v[120:123]
	v_mfma_f32_16x16x32_bf16 v[112:115], v[174:177], v[186:189], v[112:115]
	v_mfma_f32_16x16x32_bf16 v[104:107], v[166:169], v[194:197], v[104:107]
	v_mfma_f32_16x16x32_bf16 v[96:99], v[174:177], v[194:197], v[96:99]
	v_mfma_f32_16x16x32_bf16 v[88:91], v[166:169], v[202:205], v[88:91]
	v_mfma_f32_16x16x32_bf16 v[80:83], v[174:177], v[202:205], v[80:83]
	v_mfma_f32_16x16x32_bf16 v[72:75], v[166:169], v[210:213], v[72:75]
	v_mfma_f32_16x16x32_bf16 v[64:67], v[174:177], v[210:213], v[64:67]
	v_mfma_f32_16x16x32_bf16 v[120:123], v[170:173], v[190:193], v[120:123]
	v_mfma_f32_16x16x32_bf16 v[112:115], v[178:181], v[190:193], v[112:115]
	v_mfma_f32_16x16x32_bf16 v[104:107], v[170:173], v[198:201], v[104:107]
	v_mfma_f32_16x16x32_bf16 v[96:99], v[178:181], v[198:201], v[96:99]
	v_mfma_f32_16x16x32_bf16 v[88:91], v[170:173], v[206:209], v[88:91]
	v_mfma_f32_16x16x32_bf16 v[80:83], v[178:181], v[206:209], v[80:83]
	v_mfma_f32_16x16x32_bf16 v[72:75], v[170:173], v[214:217], v[72:75]
	v_mfma_f32_16x16x32_bf16 v[64:67], v[178:181], v[214:217], v[64:67]
	s_setprio 0
	s_barrier
; #define PG8_STAGE(bufoff, gbase, voff) do { _Pragma("unroll") for (int _i = 0; _i < 2; ++_i) \
;         __builtin_amdgcn_global_load_lds((const unsigned*)((const char*)(gbase) + (voff)[_i]), (PG8_LAS unsigned*)(lds + (bufoff) + ldsw + _i * 8192), 16, 0, 0); } while (0)
; #define PG8_LDA(dst, b, h) do { _Pragma("unroll") for (int m = 0; m < 4; ++m) _Pragma("unroll") for (int k = 0; k < 2; ++k) dst[m][k] = *(const PG8_LAS bf16x8*)(lds + PG8_SA(b, h) + aoff + m * 2048 + k * 1024); } while (0)
; #define PG8_MMA(ai, bj, At, Bt) do { __builtin_amdgcn_s_setprio(1); _Pragma("unroll") for (int m = 0; m < 4; ++m) _Pragma("unroll") for (int n = 0; n < 2; ++n) _Pragma("unroll") for (int k = 0; k < 2; ++k) \
;         acc[ai][bj][m][n] = __builtin_amdgcn_mfma_f32_16x16x32_bf16(Bt[n][k], At[m][k], acc[ai][bj][m][n], 0, 0, 0); __builtin_amdgcn_s_setprio(0); } while (0)
; #define PG8_WAIT_V(n) asm volatile("s_waitcnt vmcnt(" #n ")" ::: "memory")
; #define PG8_WAIT_L(n) asm volatile("s_waitcnt lgkmcnt(" #n ")" ::: "memory")
; #define PG8_BAR __builtin_amdgcn_s_barrier()
; #define PG8_SCHED __builtin_amdgcn_sched_barrier(0)
; template <class Epi, class Sched, bool ALIGN_EPI = false, bool SP2 = false>
; __device__ __forceinline__ void gemm_phase(PG8_LAS unsigned char* lds, const Gemm g, const Sched& S, const Epi& E) {
;     ...
;         for (int t = 0; t < nt; t += 2) {
;             const bool last = (t == nt - 2);
;             const char* a1 = cA + (size_t)(t + 1) * kstep;
;             const char* a2 = last ? nA : cA + (size_t)(t + 2) * kstep; const char* b2 = last ? nB : cB + (size_t)(t + 2) * kstep;
;     ...
;             PG8_LDA(At, 1, 1); PG8_STAGE(PG8_SB(1, 0), b3, voffB); PG8_STAGE(PG8_SB(1, 1), b3 + hstep, voffB); PG8_STAGE(PG8_SA(1, 0), a3, voffA);
;             PG8_WAIT_V(8); PG8_WAIT_L(0); PG8_BAR; PG8_MMA(1, 0, At, B0); PG8_MMA(1, 1, At, B1); PG8_BAR; PG8_SCHED;
	s_add_i32 s24, s50, s31
	v_lshl_add_u64 v[182:183], v[182:183], 0, s[6:7]
	s_mov_b32 m0, s24
	ds_read_b128 v[186:189], v153 offset:49152
	ds_read_b128 v[190:193], v153 offset:50176
	ds_read_b128 v[194:197], v153 offset:51200
	ds_read_b128 v[198:201], v153 offset:52224
	ds_read_b128 v[202:205], v153 offset:53248
	ds_read_b128 v[206:209], v153 offset:54272
	ds_read_b128 v[210:213], v153 offset:55296
	ds_read_b128 v[214:217], v153 offset:56320
	global_load_lds_dwordx4 v[182:183], off
	s_add_i32 m0, s24, 0x2000
	s_add_u32 s22, s22, 0x40080
	v_lshl_add_u64 v[182:183], v[218:219], 0, s[6:7]
	s_addc_u32 s23, s23, 0
	s_add_i32 s24, s51, s31
	global_load_lds_dwordx4 v[182:183], off
	v_lshl_add_u64 v[182:183], s[22:23], 0, v[130:131]
	s_mov_b32 m0, s24
	s_nop 0
	global_load_lds_dwordx4 v[182:183], off
	v_lshl_add_u64 v[182:183], s[22:23], 0, v[134:135]
	s_add_i32 m0, s24, 0x2000
	s_nop 0
	global_load_lds_dwordx4 v[182:183], off
	v_lshl_add_u64 v[182:183], v[220:221], 0, s[6:7]
	s_mov_b32 m0, s37
	s_nop 0
	global_load_lds_dwordx4 v[182:183], off
	v_lshl_add_u64 v[182:183], v[222:223], 0, s[6:7]
	s_mov_b32 m0, s38
	s_nop 0
	global_load_lds_dwordx4 v[182:183], off
	s_waitcnt vmcnt(6)
	s_waitcnt lgkmcnt(0)
	s_barrier
	s_setprio 1
	s_waitcnt lgkmcnt(0)
	v_mfma_f32_16x16x32_bf16 v[60:63], v[144:147], v[186:189], v[60:63]
	v_mfma_f32_16x16x32_bf16 v[52:55], v[158:161], v[186:189], v[52:55]
	v_mfma_f32_16x16x32_bf16 v[44:47], v[144:147], v[194:197], v[44:47]
	v_mfma_f32_16x16x32_bf16 v[36:39], v[158:161], v[194:197], v[36:39]
	v_mfma_f32_16x16x32_bf16 v[28:31], v[144:147], v[202:205], v[28:31]
	v_mfma_f32_16x16x32_bf16 v[20:23], v[158:161], v[202:205], v[20:23]
	v_mfma_f32_16x16x32_bf16 v[12:15], v[144:147], v[210:213], v[12:15]
	v_mfma_f32_16x16x32_bf16 v[4:7], v[158:161], v[210:213], v[4:7]
	v_mfma_f32_16x16x32_bf16 v[60:63], v[154:157], v[190:193], v[60:63]
	v_mfma_f32_16x16x32_bf16 v[52:55], v[162:165], v[190:193], v[52:55]
	v_mfma_f32_16x16x32_bf16 v[44:47], v[154:157], v[198:201], v[44:47]
	v_mfma_f32_16x16x32_bf16 v[36:39], v[162:165], v[198:201], v[36:39]
	v_mfma_f32_16x16x32_bf16 v[28:31], v[154:157], v[206:209], v[28:31]
	v_mfma_f32_16x16x32_bf16 v[20:23], v[162:165], v[206:209], v[20:23]
	v_mfma_f32_16x16x32_bf16 v[12:15], v[154:157], v[214:217], v[12:15]
	v_mfma_f32_16x16x32_bf16 v[4:7], v[162:165], v[214:217], v[4:7]
	s_setprio 0
	s_setprio 1
	v_mfma_f32_16x16x32_bf16 v[56:59], v[166:169], v[186:189], v[56:59]
	v_mfma_f32_16x16x32_bf16 v[48:51], v[174:177], v[186:189], v[48:51]
	v_mfma_f32_16x16x32_bf16 v[40:43], v[166:169], v[194:197], v[40:43]
	v_mfma_f32_16x16x32_bf16 v[32:35], v[174:177], v[194:197], v[32:35]
	v_mfma_f32_16x16x32_bf16 v[24:27], v[166:169], v[202:205], v[24:27]
	v_mfma_f32_16x16x32_bf16 v[16:19], v[174:177], v[202:205], v[16:19]
	v_mfma_f32_16x16x32_bf16 v[8:11], v[166:169], v[210:213], v[8:11]
	v_mfma_f32_16x16x32_bf16 v[0:3], v[174:177], v[210:213], v[0:3]
	v_mfma_f32_16x16x32_bf16 v[56:59], v[170:173], v[190:193], v[56:59]
	v_mfma_f32_16x16x32_bf16 v[48:51], v[178:181], v[190:193], v[48:51]
	v_mfma_f32_16x16x32_bf16 v[40:43], v[170:173], v[198:201], v[40:43]
	v_mfma_f32_16x16x32_bf16 v[32:35], v[178:181], v[198:201], v[32:35]
	v_mfma_f32_16x16x32_bf16 v[24:27], v[170:173], v[206:209], v[24:27]
	v_mfma_f32_16x16x32_bf16 v[16:19], v[178:181], v[206:209], v[16:19]
	v_mfma_f32_16x16x32_bf16 v[8:11], v[170:173], v[214:217], v[8:11]
	v_mfma_f32_16x16x32_bf16 v[0:3], v[178:181], v[214:217], v[0:3]
	s_setprio 0
	s_barrier
	s_add_i32 s49, s49, 2
	s_add_u32 s47, s47, 0x100
	s_addc_u32 s48, s48, 0
	s_add_u32 s20, s20, 0x100
	s_addc_u32 s21, s21, 0
	s_cmp_gt_u32 s49, 13
	s_cbranch_scc0 .LBB0_124
	s_and_b64 vcc, exec, s[8:9]
	s_cbranch_vccz .LBB0_127
	s_barrier

; #define PG8_STAGE(bufoff, gbase, voff) do { _Pragma("unroll") for (int _i = 0; _i < 2; ++_i) \
;         __builtin_amdgcn_global_load_lds((const unsigned*)((const char*)(gbase) + (voff)[_i]), (PG8_LAS unsigned*)(lds + (bufoff) + ldsw + _i * 8192), 16, 0, 0); } while (0)
; #define PG8_LDA(dst, b, h) do { _Pragma("unroll") for (int m = 0; m < 4; ++m) _Pragma("unroll") for (int k = 0; k < 2; ++k) dst[m][k] = *(const PG8_LAS bf16x8*)(lds + PG8_SA(b, h) + aoff + m * 2048 + k * 1024); } while (0)
; #define PG8_LDB(dst, b, h) do { _Pragma("unroll") for (int n = 0; n < 2; ++n) _Pragma("unroll") for (int k = 0; k < 2; ++k) dst[n][k] = *(const PG8_LAS bf16x8*)(lds + PG8_SB(b, h) + boff + n * 2048 + k * 1024); } while (0)
; #define PG8_MMA(ai, bj, At, Bt) do { __builtin_amdgcn_s_setprio(1); _Pragma("unroll") for (int m = 0; m < 4; ++m) _Pragma("unroll") for (int n = 0; n < 2; ++n) _Pragma("unroll") for (int k = 0; k < 2; ++k) \
;         acc[ai][bj][m][n] = __builtin_amdgcn_mfma_f32_16x16x32_bf16(Bt[n][k], At[m][k], acc[ai][bj][m][n], 0, 0, 0); __builtin_amdgcn_s_setprio(0); } while (0)
; #define PG8_WAIT_V(n) asm volatile("s_waitcnt vmcnt(" #n ")" ::: "memory")
; #define PG8_WAIT_L(n) asm volatile("s_waitcnt lgkmcnt(" #n ")" ::: "memory")
; #define PG8_BAR __builtin_amdgcn_s_barrier()
; #define PG8_SCHED __builtin_amdgcn_sched_barrier(0)
; template <class Epi, class Sched, bool ALIGN_EPI = false, bool SP2 = false>
; __device__ __forceinline__ void gemm_phase(PG8_LAS unsigned char* lds, const Gemm g, const Sched& S, const Epi& E) {
;     ...
;         for (int t = 0; t < nt; t += 2) {
;             const bool last = (t == nt - 2);
;             const char* a1 = cA + (size_t)(t + 1) * kstep;
;             const char* a2 = last ? nA : cA + (size_t)(t + 2) * kstep; const char* b2 = last ? nB : cB + (size_t)(t + 2) * kstep;
;             const char* a3 = a2 + kstep; const char* b3 = b2 + kstep;
;             if (last && has_next) S.a_ready(nxt);
;             if constexpr (SP2) {
;             PG8_LDB(B0, 0, 0); PG8_LDB(B1, 0, 1); PG8_SCHED; PG8_LDA(At, 0, 0); PG8_STAGE(PG8_SA(1, 1), a1 + hstep, voffA);
;             PG8_WAIT_V(8); PG8_WAIT_L(0); PG8_BAR; PG8_MMA(0, 0, At, B0); PG8_MMA(0, 1, At, B1); PG8_BAR; PG8_SCHED;
;             PG8_LDA(At, 0, 1); PG8_STAGE(PG8_SB(0, 0), b2, voffB); PG8_STAGE(PG8_SB(0, 1), b2 + hstep, voffB); PG8_STAGE(PG8_SA(0, 0), a2, voffA);
.LBB0_196:
	ds_read_b128 v[152:155], v149
	ds_read_b128 v[156:159], v149 offset:1024
	ds_read_b128 v[160:163], v149 offset:2048
	ds_read_b128 v[164:167], v149 offset:3072
	ds_read_b128 v[168:171], v150
	ds_read_b128 v[172:175], v150 offset:1024
	ds_read_b128 v[176:179], v150 offset:2048
	ds_read_b128 v[180:183], v150 offset:3072
	s_add_u32 s24, s22, 0x100
	s_addc_u32 s25, s23, 0
	s_cmp_eq_u32 s58, 40
	s_cselect_b32 s29, s5, s25
	s_cselect_b32 s28, s4, s24
	s_cselect_b32 s27, s21, s57
	s_cselect_b32 s26, s20, s56
	v_lshl_add_u64 v[144:145], s[22:23], 0, v[138:139]
	s_add_i32 m0, s37, 0xc000
	ds_read_b128 v[186:189], v151
	ds_read_b128 v[190:193], v151 offset:1024
	ds_read_b128 v[194:197], v151 offset:2048
	ds_read_b128 v[198:201], v151 offset:3072
	ds_read_b128 v[202:205], v151 offset:4096
	ds_read_b128 v[206:209], v151 offset:5120
	ds_read_b128 v[210:213], v151 offset:6144
	ds_read_b128 v[214:217], v151 offset:7168
	global_load_lds_dwordx4 v[144:145], off
	v_lshl_add_u64 v[144:145], s[22:23], 0, v[136:137]
	s_add_i32 m0, s37, 0xe000
	s_nop 0
	global_load_lds_dwordx4 v[144:145], off
	s_waitcnt vmcnt(6)
	s_waitcnt lgkmcnt(0)
	s_barrier
	s_setprio 1
	s_waitcnt lgkmcnt(0)
	v_mfma_f32_16x16x32_bf16 v[124:127], v[152:155], v[186:189], v[124:127]
	v_mfma_f32_16x16x32_bf16 v[120:123], v[160:163], v[186:189], v[120:123]
	v_mfma_f32_16x16x32_bf16 v[116:119], v[152:155], v[194:197], v[116:119]
	v_mfma_f32_16x16x32_bf16 v[108:111], v[160:163], v[194:197], v[108:111]
	v_mfma_f32_16x16x32_bf16 v[100:103], v[152:155], v[202:205], v[100:103]
	v_mfma_f32_16x16x32_bf16 v[92:95], v[160:163], v[202:205], v[92:95]
	v_mfma_f32_16x16x32_bf16 v[84:87], v[152:155], v[210:213], v[84:87]
	v_mfma_f32_16x16x32_bf16 v[76:79], v[160:163], v[210:213], v[76:79]
	v_mfma_f32_16x16x32_bf16 v[124:127], v[156:159], v[190:193], v[124:127]
	v_mfma_f32_16x16x32_bf16 v[120:123], v[164:167], v[190:193], v[120:123]
	v_mfma_f32_16x16x32_bf16 v[116:119], v[156:159], v[198:201], v[116:119]
	v_mfma_f32_16x16x32_bf16 v[108:111], v[164:167], v[198:201], v[108:111]
	v_mfma_f32_16x16x32_bf16 v[100:103], v[156:159], v[206:209], v[100:103]
	v_mfma_f32_16x16x32_bf16 v[92:95], v[164:167], v[206:209], v[92:95]
	v_mfma_f32_16x16x32_bf16 v[84:87], v[156:159], v[214:217], v[84:87]
	v_mfma_f32_16x16x32_bf16 v[76:79], v[164:167], v[214:217], v[76:79]
	s_setprio 0
	s_setprio 1
	v_mfma_f32_16x16x32_bf16 v[112:115], v[168:171], v[186:189], v[112:115]
	v_mfma_f32_16x16x32_bf16 v[104:107], v[176:179], v[186:189], v[104:107]
	v_mfma_f32_16x16x32_bf16 v[96:99], v[168:171], v[194:197], v[96:99]
	v_mfma_f32_16x16x32_bf16 v[88:91], v[176:179], v[194:197], v[88:91]
	v_mfma_f32_16x16x32_bf16 v[80:83], v[168:171], v[202:205], v[80:83]
	v_mfma_f32_16x16x32_bf16 v[72:75], v[176:179], v[202:205], v[72:75]
	v_mfma_f32_16x16x32_bf16 v[68:71], v[168:171], v[210:213], v[68:71]
	v_mfma_f32_16x16x32_bf16 v[64:67], v[176:179], v[210:213], v[64:67]
	v_mfma_f32_16x16x32_bf16 v[112:115], v[172:175], v[190:193], v[112:115]
	v_mfma_f32_16x16x32_bf16 v[104:107], v[180:183], v[190:193], v[104:107]
	v_mfma_f32_16x16x32_bf16 v[96:99], v[172:175], v[198:201], v[96:99]
	v_mfma_f32_16x16x32_bf16 v[88:91], v[180:183], v[198:201], v[88:91]
	v_mfma_f32_16x16x32_bf16 v[80:83], v[172:175], v[206:209], v[80:83]
	v_mfma_f32_16x16x32_bf16 v[72:75], v[180:183], v[206:209], v[72:75]
	v_mfma_f32_16x16x32_bf16 v[68:71], v[172:175], v[214:217], v[68:71]
	v_mfma_f32_16x16x32_bf16 v[64:67], v[180:183], v[214:217], v[64:67]
	s_setprio 0
	s_barrier
	s_add_i32 s22, s46, s36
	v_lshl_add_u64 v[144:145], s[26:27], 0, v[130:131]
	s_mov_b32 m0, s22
	ds_read_b128 v[186:189], v151 offset:16384
	ds_read_b128 v[190:193], v151 offset:17408
	ds_read_b128 v[194:197], v151 offset:18432
	ds_read_b128 v[198:201], v151 offset:19456
	ds_read_b128 v[202:205], v151 offset:20480
	ds_read_b128 v[206:209], v151 offset:21504
	ds_read_b128 v[210:213], v151 offset:22528
	ds_read_b128 v[214:217], v151 offset:23552
	global_load_lds_dwordx4 v[144:145], off
	s_add_i32 m0, s22, 0x2000
	s_add_u32 s22, s26, 0xb0000
	v_lshl_add_u64 v[218:219], s[26:27], 0, v[134:135]
	s_addc_u32 s23, s27, 0
	s_add_i32 s59, s47, s36
	global_load_lds_dwordx4 v[218:219], off
	v_lshl_add_u64 v[220:221], s[22:23], 0, v[130:131]
	s_mov_b32 m0, s59
	v_lshl_add_u64 v[222:223], s[28:29], 0, v[132:133]
	global_load_lds_dwordx4 v[220:221], off
	v_lshl_add_u64 v[220:221], s[22:23], 0, v[134:135]
	s_add_i32 m0, s59, 0x2000
	s_nop 0
	global_load_lds_dwordx4 v[220:221], off
	v_lshl_add_u64 v[220:221], s[28:29], 0, v[128:129]
	s_mov_b32 m0, s37
	s_nop 0
	global_load_lds_dwordx4 v[220:221], off
	s_mov_b32 m0, s38
	s_nop 0
	global_load_lds_dwordx4 v[222:223], off
	s_waitcnt vmcnt(6)
	s_waitcnt lgkmcnt(0)
	s_barrier
; #define PG8_STAGE(bufoff, gbase, voff) do { _Pragma("unroll") for (int _i = 0; _i < 2; ++_i) \
;         __builtin_amdgcn_global_load_lds((const unsigned*)((const char*)(gbase) + (voff)[_i]), (PG8_LAS unsigned*)(lds + (bufoff) + ldsw + _i * 8192), 16, 0, 0); } while (0)
; #define PG8_LDA(dst, b, h) do { _Pragma("unroll") for (int m = 0; m < 4; ++m) _Pragma("unroll") for (int k = 0; k < 2; ++k) dst[m][k] = *(const PG8_LAS bf16x8*)(lds + PG8_SA(b, h) + aoff + m * 2048 + k * 1024); } while (0)
; #define PG8_LDB(dst, b, h) do { _Pragma("unroll") for (int n = 0; n < 2; ++n) _Pragma("unroll") for (int k = 0; k < 2; ++k) dst[n][k] = *(const PG8_LAS bf16x8*)(lds + PG8_SB(b, h) + boff + n * 2048 + k * 1024); } while (0)
; #define PG8_MMA(ai, bj, At, Bt) do { __builtin_amdgcn_s_setprio(1); _Pragma("unroll") for (int m = 0; m < 4; ++m) _Pragma("unroll") for (int n = 0; n < 2; ++n) _Pragma("unroll") for (int k = 0; k < 2; ++k) \
;         acc[ai][bj][m][n] = __builtin_amdgcn_mfma_f32_16x16x32_bf16(Bt[n][k], At[m][k], acc[ai][bj][m][n], 0, 0, 0); __builtin_amdgcn_s_setprio(0); } while (0)
; #define PG8_WAIT_V(n) asm volatile("s_waitcnt vmcnt(" #n ")" ::: "memory")
; #define PG8_WAIT_L(n) asm volatile("s_waitcnt lgkmcnt(" #n ")" ::: "memory")
; #define PG8_BAR __builtin_amdgcn_s_barrier()
; #define PG8_SCHED __builtin_amdgcn_sched_barrier(0)
; template <class Epi, class Sched, bool ALIGN_EPI = false, bool SP2 = false>
; __device__ __forceinline__ void gemm_phase(PG8_LAS unsigned char* lds, const Gemm g, const Sched& S, const Epi& E) {
;     ...
;             PG8_WAIT_V(8); PG8_WAIT_L(0); PG8_BAR; PG8_MMA(1, 0, At, B0); PG8_MMA(1, 1, At, B1); PG8_BAR; PG8_SCHED;
;             PG8_LDB(B0, 1, 0); PG8_LDB(B1, 1, 1); PG8_SCHED; PG8_LDA(At, 1, 0); PG8_STAGE(PG8_SA(0, 1), a2 + hstep, voffA);
;             PG8_WAIT_V(8); PG8_WAIT_L(0); PG8_BAR; PG8_MMA(0, 0, At, B0); PG8_MMA(0, 1, At, B1); PG8_BAR; PG8_SCHED;
	s_setprio 1
	s_waitcnt lgkmcnt(0)
	v_mfma_f32_16x16x32_bf16 v[60:63], v[152:155], v[186:189], v[60:63]
	v_mfma_f32_16x16x32_bf16 v[56:59], v[160:163], v[186:189], v[56:59]
	v_mfma_f32_16x16x32_bf16 v[52:55], v[152:155], v[194:197], v[52:55]
	v_mfma_f32_16x16x32_bf16 v[44:47], v[160:163], v[194:197], v[44:47]
	v_mfma_f32_16x16x32_bf16 v[36:39], v[152:155], v[202:205], v[36:39]
	v_mfma_f32_16x16x32_bf16 v[28:31], v[160:163], v[202:205], v[28:31]
	v_mfma_f32_16x16x32_bf16 v[20:23], v[152:155], v[210:213], v[20:23]
	v_mfma_f32_16x16x32_bf16 v[12:15], v[160:163], v[210:213], v[12:15]
	v_mfma_f32_16x16x32_bf16 v[60:63], v[156:159], v[190:193], v[60:63]
	v_mfma_f32_16x16x32_bf16 v[56:59], v[164:167], v[190:193], v[56:59]
	v_mfma_f32_16x16x32_bf16 v[52:55], v[156:159], v[198:201], v[52:55]
	v_mfma_f32_16x16x32_bf16 v[44:47], v[164:167], v[198:201], v[44:47]
	v_mfma_f32_16x16x32_bf16 v[36:39], v[156:159], v[206:209], v[36:39]
	v_mfma_f32_16x16x32_bf16 v[28:31], v[164:167], v[206:209], v[28:31]
	v_mfma_f32_16x16x32_bf16 v[20:23], v[156:159], v[214:217], v[20:23]
	v_mfma_f32_16x16x32_bf16 v[12:15], v[164:167], v[214:217], v[12:15]
	s_setprio 0
	s_setprio 1
	v_mfma_f32_16x16x32_bf16 v[48:51], v[168:171], v[186:189], v[48:51]
	v_mfma_f32_16x16x32_bf16 v[40:43], v[176:179], v[186:189], v[40:43]
	v_mfma_f32_16x16x32_bf16 v[32:35], v[168:171], v[194:197], v[32:35]
	v_mfma_f32_16x16x32_bf16 v[24:27], v[176:179], v[194:197], v[24:27]
	v_mfma_f32_16x16x32_bf16 v[16:19], v[168:171], v[202:205], v[16:19]
	v_mfma_f32_16x16x32_bf16 v[8:11], v[176:179], v[202:205], v[8:11]
	v_mfma_f32_16x16x32_bf16 v[4:7], v[168:171], v[210:213], v[4:7]
	v_mfma_f32_16x16x32_bf16 v[0:3], v[176:179], v[210:213], v[0:3]
	v_mfma_f32_16x16x32_bf16 v[48:51], v[172:175], v[190:193], v[48:51]
	v_mfma_f32_16x16x32_bf16 v[40:43], v[180:183], v[190:193], v[40:43]
	v_mfma_f32_16x16x32_bf16 v[32:35], v[172:175], v[198:201], v[32:35]
	v_mfma_f32_16x16x32_bf16 v[24:27], v[180:183], v[198:201], v[24:27]
	v_mfma_f32_16x16x32_bf16 v[16:19], v[172:175], v[206:209], v[16:19]
	v_mfma_f32_16x16x32_bf16 v[8:11], v[180:183], v[206:209], v[8:11]
	v_mfma_f32_16x16x32_bf16 v[4:7], v[172:175], v[214:217], v[4:7]
	v_mfma_f32_16x16x32_bf16 v[0:3], v[180:183], v[214:217], v[0:3]
	s_setprio 0
	s_barrier
	s_add_i32 s59, 0, 0x18000
	s_add_i32 s60, 0, 0x1c000
	v_add_u32_e32 v164, s59, v147
	v_add_u32_e32 v180, s60, v147
	ds_read_b128 v[152:155], v164
	ds_read_b128 v[156:159], v164 offset:1024
	ds_read_b128 v[160:163], v164 offset:2048
	ds_read_b128 v[164:167], v164 offset:3072
	ds_read_b128 v[168:171], v180
	ds_read_b128 v[172:175], v180 offset:1024
	ds_read_b128 v[176:179], v180 offset:2048
	ds_read_b128 v[180:183], v180 offset:3072
	s_add_u32 s22, s28, 0xb0000
	s_addc_u32 s23, s29, 0
	s_mov_b32 m0, s39
	v_lshl_add_u64 v[224:225], s[22:23], 0, v[128:129]
	ds_read_b128 v[186:189], v151 offset:32768
	ds_read_b128 v[190:193], v151 offset:33792
	ds_read_b128 v[194:197], v151 offset:34816
	ds_read_b128 v[198:201], v151 offset:35840
	ds_read_b128 v[202:205], v151 offset:36864
	ds_read_b128 v[206:209], v151 offset:37888
	ds_read_b128 v[210:213], v151 offset:38912
	ds_read_b128 v[214:217], v151 offset:39936
	global_load_lds_dwordx4 v[224:225], off
	v_lshl_add_u64 v[224:225], s[22:23], 0, v[132:133]
	s_mov_b32 m0, s40
	s_nop 0
	global_load_lds_dwordx4 v[224:225], off
	s_waitcnt vmcnt(6)
	s_waitcnt lgkmcnt(0)
	s_barrier
	s_setprio 1
	s_waitcnt lgkmcnt(0)
	v_mfma_f32_16x16x32_bf16 v[124:127], v[152:155], v[186:189], v[124:127]
	v_mfma_f32_16x16x32_bf16 v[120:123], v[160:163], v[186:189], v[120:123]
	v_mfma_f32_16x16x32_bf16 v[116:119], v[152:155], v[194:197], v[116:119]
	v_mfma_f32_16x16x32_bf16 v[108:111], v[160:163], v[194:197], v[108:111]
	v_mfma_f32_16x16x32_bf16 v[100:103], v[152:155], v[202:205], v[100:103]
	v_mfma_f32_16x16x32_bf16 v[92:95], v[160:163], v[202:205], v[92:95]
	v_mfma_f32_16x16x32_bf16 v[84:87], v[152:155], v[210:213], v[84:87]
	v_mfma_f32_16x16x32_bf16 v[76:79], v[160:163], v[210:213], v[76:79]
	v_mfma_f32_16x16x32_bf16 v[124:127], v[156:159], v[190:193], v[124:127]
	v_mfma_f32_16x16x32_bf16 v[120:123], v[164:167], v[190:193], v[120:123]
	v_mfma_f32_16x16x32_bf16 v[116:119], v[156:159], v[198:201], v[116:119]
	v_mfma_f32_16x16x32_bf16 v[108:111], v[164:167], v[198:201], v[108:111]
	v_mfma_f32_16x16x32_bf16 v[100:103], v[156:159], v[206:209], v[100:103]
	v_mfma_f32_16x16x32_bf16 v[92:95], v[164:167], v[206:209], v[92:95]
	v_mfma_f32_16x16x32_bf16 v[84:87], v[156:159], v[214:217], v[84:87]
	v_mfma_f32_16x16x32_bf16 v[76:79], v[164:167], v[214:217], v[76:79]
	s_setprio 0
	s_setprio 1
	v_mfma_f32_16x16x32_bf16 v[112:115], v[168:171], v[186:189], v[112:115]
	v_mfma_f32_16x16x32_bf16 v[104:107], v[176:179], v[186:189], v[104:107]
	v_mfma_f32_16x16x32_bf16 v[96:99], v[168:171], v[194:197], v[96:99]
	v_mfma_f32_16x16x32_bf16 v[88:91], v[176:179], v[194:197], v[88:91]
	v_mfma_f32_16x16x32_bf16 v[80:83], v[168:171], v[202:205], v[80:83]
	v_mfma_f32_16x16x32_bf16 v[72:75], v[176:179], v[202:205], v[72:75]
	v_mfma_f32_16x16x32_bf16 v[68:71], v[168:171], v[210:213], v[68:71]
	v_mfma_f32_16x16x32_bf16 v[64:67], v[176:179], v[210:213], v[64:67]
	v_mfma_f32_16x16x32_bf16 v[112:115], v[172:175], v[190:193], v[112:115]
	v_mfma_f32_16x16x32_bf16 v[104:107], v[180:183], v[190:193], v[104:107]
	v_mfma_f32_16x16x32_bf16 v[96:99], v[172:175], v[198:201], v[96:99]
	v_mfma_f32_16x16x32_bf16 v[88:91], v[180:183], v[198:201], v[88:91]
	v_mfma_f32_16x16x32_bf16 v[80:83], v[172:175], v[206:209], v[80:83]
	v_mfma_f32_16x16x32_bf16 v[72:75], v[180:183], v[206:209], v[72:75]
	v_mfma_f32_16x16x32_bf16 v[68:71], v[172:175], v[214:217], v[68:71]
	v_mfma_f32_16x16x32_bf16 v[64:67], v[180:183], v[214:217], v[64:67]
	s_setprio 0
	s_barrier
; #define PG8_STAGE(bufoff, gbase, voff) do { _Pragma("unroll") for (int _i = 0; _i < 2; ++_i) \
;         __builtin_amdgcn_global_load_lds((const unsigned*)((const char*)(gbase) + (voff)[_i]), (PG8_LAS unsigned*)(lds + (bufoff) + ldsw + _i * 8192), 16, 0, 0); } while (0)
; #define PG8_LDA(dst, b, h) do { _Pragma("unroll") for (int m = 0; m < 4; ++m) _Pragma("unroll") for (int k = 0; k < 2; ++k) dst[m][k] = *(const PG8_LAS bf16x8*)(lds + PG8_SA(b, h) + aoff + m * 2048 + k * 1024); } while (0)
; #define PG8_MMA(ai, bj, At, Bt) do { __builtin_amdgcn_s_setprio(1); _Pragma("unroll") for (int m = 0; m < 4; ++m) _Pragma("unroll") for (int n = 0; n < 2; ++n) _Pragma("unroll") for (int k = 0; k < 2; ++k) \
;         acc[ai][bj][m][n] = __builtin_amdgcn_mfma_f32_16x16x32_bf16(Bt[n][k], At[m][k], acc[ai][bj][m][n], 0, 0, 0); __builtin_amdgcn_s_setprio(0); } while (0)
; #define PG8_WAIT_V(n) asm volatile("s_waitcnt vmcnt(" #n ")" ::: "memory")
; #define PG8_WAIT_L(n) asm volatile("s_waitcnt lgkmcnt(" #n ")" ::: "memory")
; #define PG8_BAR __builtin_amdgcn_s_barrier()
; #define PG8_SCHED __builtin_amdgcn_sched_barrier(0)
; template <class Epi, class Sched, bool ALIGN_EPI = false, bool SP2 = false>
; __device__ __forceinline__ void gemm_phase(PG8_LAS unsigned char* lds, const Gemm g, const Sched& S, const Epi& E) {
;     ...
;         for (int t = 0; t < nt; t += 2) {
;             const bool last = (t == nt - 2);
;             const char* a1 = cA + (size_t)(t + 1) * kstep;
;             const char* a2 = last ? nA : cA + (size_t)(t + 2) * kstep; const char* b2 = last ? nB : cB + (size_t)(t + 2) * kstep;
;     ...
;             PG8_LDA(At, 1, 1); PG8_STAGE(PG8_SB(1, 0), b3, voffB); PG8_STAGE(PG8_SB(1, 1), b3 + hstep, voffB); PG8_STAGE(PG8_SA(1, 0), a3, voffA);
;             PG8_WAIT_V(8); PG8_WAIT_L(0); PG8_BAR; PG8_MMA(1, 0, At, B0); PG8_MMA(1, 1, At, B1); PG8_BAR; PG8_SCHED;
	s_add_i32 s22, s59, s36
	v_lshl_add_u64 v[144:145], v[144:145], 0, s[8:9]
	s_mov_b32 m0, s22
	ds_read_b128 v[186:189], v151 offset:49152
	ds_read_b128 v[190:193], v151 offset:50176
	ds_read_b128 v[194:197], v151 offset:51200
	ds_read_b128 v[198:201], v151 offset:52224
	ds_read_b128 v[202:205], v151 offset:53248
	ds_read_b128 v[206:209], v151 offset:54272
	ds_read_b128 v[210:213], v151 offset:55296
	ds_read_b128 v[214:217], v151 offset:56320
	global_load_lds_dwordx4 v[144:145], off
	s_add_i32 m0, s22, 0x2000
	s_add_u32 s22, s26, 0xb0080
	v_lshl_add_u64 v[144:145], v[218:219], 0, s[8:9]
	s_addc_u32 s23, s27, 0
	s_add_i32 s26, s60, s36
	global_load_lds_dwordx4 v[144:145], off
	v_lshl_add_u64 v[144:145], s[22:23], 0, v[130:131]
	s_mov_b32 m0, s26
	s_nop 0
	global_load_lds_dwordx4 v[144:145], off
	v_lshl_add_u64 v[144:145], s[22:23], 0, v[134:135]
	s_add_i32 m0, s26, 0x2000
	s_nop 0
	global_load_lds_dwordx4 v[144:145], off
	v_lshl_add_u64 v[144:145], v[220:221], 0, s[8:9]
	s_mov_b32 m0, s42
	s_nop 0
	global_load_lds_dwordx4 v[144:145], off
	v_lshl_add_u64 v[144:145], v[222:223], 0, s[8:9]
	s_mov_b32 m0, s43
	s_nop 0
	global_load_lds_dwordx4 v[144:145], off
	s_waitcnt vmcnt(6)
	s_waitcnt lgkmcnt(0)
	s_barrier
	s_setprio 1
	s_waitcnt lgkmcnt(0)
	v_mfma_f32_16x16x32_bf16 v[60:63], v[152:155], v[186:189], v[60:63]
	v_mfma_f32_16x16x32_bf16 v[56:59], v[160:163], v[186:189], v[56:59]
	v_mfma_f32_16x16x32_bf16 v[52:55], v[152:155], v[194:197], v[52:55]
	v_mfma_f32_16x16x32_bf16 v[44:47], v[160:163], v[194:197], v[44:47]
	v_mfma_f32_16x16x32_bf16 v[36:39], v[152:155], v[202:205], v[36:39]
	v_mfma_f32_16x16x32_bf16 v[28:31], v[160:163], v[202:205], v[28:31]
	v_mfma_f32_16x16x32_bf16 v[20:23], v[152:155], v[210:213], v[20:23]
	v_mfma_f32_16x16x32_bf16 v[12:15], v[160:163], v[210:213], v[12:15]
	v_mfma_f32_16x16x32_bf16 v[60:63], v[156:159], v[190:193], v[60:63]
	v_mfma_f32_16x16x32_bf16 v[56:59], v[164:167], v[190:193], v[56:59]
	v_mfma_f32_16x16x32_bf16 v[52:55], v[156:159], v[198:201], v[52:55]
	v_mfma_f32_16x16x32_bf16 v[44:47], v[164:167], v[198:201], v[44:47]
	v_mfma_f32_16x16x32_bf16 v[36:39], v[156:159], v[206:209], v[36:39]
	v_mfma_f32_16x16x32_bf16 v[28:31], v[164:167], v[206:209], v[28:31]
	v_mfma_f32_16x16x32_bf16 v[20:23], v[156:159], v[214:217], v[20:23]
	v_mfma_f32_16x16x32_bf16 v[12:15], v[164:167], v[214:217], v[12:15]
	s_setprio 0
	s_setprio 1
	v_mfma_f32_16x16x32_bf16 v[48:51], v[168:171], v[186:189], v[48:51]
	v_mfma_f32_16x16x32_bf16 v[40:43], v[176:179], v[186:189], v[40:43]
	v_mfma_f32_16x16x32_bf16 v[32:35], v[168:171], v[194:197], v[32:35]
	v_mfma_f32_16x16x32_bf16 v[24:27], v[176:179], v[194:197], v[24:27]
	v_mfma_f32_16x16x32_bf16 v[16:19], v[168:171], v[202:205], v[16:19]
	v_mfma_f32_16x16x32_bf16 v[8:11], v[176:179], v[202:205], v[8:11]
	v_mfma_f32_16x16x32_bf16 v[4:7], v[168:171], v[210:213], v[4:7]
	v_mfma_f32_16x16x32_bf16 v[0:3], v[176:179], v[210:213], v[0:3]
	v_mfma_f32_16x16x32_bf16 v[48:51], v[172:175], v[190:193], v[48:51]
	v_mfma_f32_16x16x32_bf16 v[40:43], v[180:183], v[190:193], v[40:43]
	v_mfma_f32_16x16x32_bf16 v[32:35], v[172:175], v[198:201], v[32:35]
	v_mfma_f32_16x16x32_bf16 v[24:27], v[180:183], v[198:201], v[24:27]
	v_mfma_f32_16x16x32_bf16 v[16:19], v[172:175], v[206:209], v[16:19]
	v_mfma_f32_16x16x32_bf16 v[8:11], v[180:183], v[206:209], v[8:11]
	v_mfma_f32_16x16x32_bf16 v[4:7], v[172:175], v[214:217], v[4:7]
	v_mfma_f32_16x16x32_bf16 v[0:3], v[180:183], v[214:217], v[0:3]
	s_setprio 0
	s_barrier
	s_add_i32 s58, s58, 2
	s_add_u32 s56, s56, 0x100
	s_addc_u32 s57, s57, 0
	s_cmp_gt_u32 s58, 41
	s_mov_b64 s[22:23], s[24:25]
	s_cbranch_scc0 .LBB0_196
	s_and_b64 vcc, exec, s[10:11]
	s_cbranch_vccz .LBB0_199
	s_barrier

; #define PG8_STAGE(bufoff, gbase, voff) do { _Pragma("unroll") for (int _i = 0; _i < 2; ++_i) \
;         __builtin_amdgcn_global_load_lds((const unsigned*)((const char*)(gbase) + (voff)[_i]), (PG8_LAS unsigned*)(lds + (bufoff) + ldsw + _i * 8192), 16, 0, 0); } while (0)
; #define PG8_LDA(dst, b, h) do { _Pragma("unroll") for (int m = 0; m < 4; ++m) _Pragma("unroll") for (int k = 0; k < 2; ++k) dst[m][k] = *(const PG8_LAS bf16x8*)(lds + PG8_SA(b, h) + aoff + m * 2048 + k * 1024); } while (0)
; #define PG8_LDB(dst, b, h) do { _Pragma("unroll") for (int n = 0; n < 2; ++n) _Pragma("unroll") for (int k = 0; k < 2; ++k) dst[n][k] = *(const PG8_LAS bf16x8*)(lds + PG8_SB(b, h) + boff + n * 2048 + k * 1024); } while (0)
; #define PG8_MMA(ai, bj, At, Bt) do { __builtin_amdgcn_s_setprio(1); _Pragma("unroll") for (int m = 0; m < 4; ++m) _Pragma("unroll") for (int n = 0; n < 2; ++n) _Pragma("unroll") for (int k = 0; k < 2; ++k) \
;         acc[ai][bj][m][n] = __builtin_amdgcn_mfma_f32_16x16x32_bf16(Bt[n][k], At[m][k], acc[ai][bj][m][n], 0, 0, 0); __builtin_amdgcn_s_setprio(0); } while (0)
; #define PG8_WAIT_V(n) asm volatile("s_waitcnt vmcnt(" #n ")" ::: "memory")
; #define PG8_WAIT_L(n) asm volatile("s_waitcnt lgkmcnt(" #n ")" ::: "memory")
; #define PG8_BAR __builtin_amdgcn_s_barrier()
; #define PG8_SCHED __builtin_amdgcn_sched_barrier(0)
; template <class Epi, class Sched, bool ALIGN_EPI = false, bool SP2 = false>
; __device__ __forceinline__ void gemm_phase(PG8_LAS unsigned char* lds, const Gemm g, const Sched& S, const Epi& E) {
;     ...
;         for (int t = 0; t < nt; t += 2) {
;             const bool last = (t == nt - 2);
;             const char* a1 = cA + (size_t)(t + 1) * kstep;
;             const char* a2 = last ? nA : cA + (size_t)(t + 2) * kstep; const char* b2 = last ? nB : cB + (size_t)(t + 2) * kstep;
;             const char* a3 = a2 + kstep; const char* b3 = b2 + kstep;
;             if (last && has_next) S.a_ready(nxt);
;             if constexpr (SP2) {
;             PG8_LDB(B0, 0, 0); PG8_LDB(B1, 0, 1); PG8_SCHED; PG8_LDA(At, 0, 0); PG8_STAGE(PG8_SA(1, 1), a1 + hstep, voffA);
;             PG8_WAIT_V(8); PG8_WAIT_L(0); PG8_BAR; PG8_MMA(0, 0, At, B0); PG8_MMA(0, 1, At, B1); PG8_BAR; PG8_SCHED;
;             PG8_LDA(At, 0, 1); PG8_STAGE(PG8_SB(0, 0), b2, voffB); PG8_STAGE(PG8_SB(0, 1), b2 + hstep, voffB); PG8_STAGE(PG8_SA(0, 0), a2, voffA);
.LBB0_269:
	ds_read_b128 v[148:151], v145
	ds_read_b128 v[152:155], v145 offset:1024
	ds_read_b128 v[156:159], v145 offset:2048
	ds_read_b128 v[160:163], v145 offset:3072
	ds_read_b128 v[164:167], v146
	ds_read_b128 v[168:171], v146 offset:1024
	ds_read_b128 v[172:175], v146 offset:2048
	ds_read_b128 v[176:179], v146 offset:3072
	s_add_u32 s26, s24, 0x100
	s_addc_u32 s27, s25, 0
	s_cmp_eq_u32 s57, 40
	s_cselect_b32 s31, s21, s27
	s_cselect_b32 s30, s20, s26
	s_cselect_b32 s29, s23, s56
	s_cselect_b32 s28, s22, s55
	v_lshl_add_u64 v[140:141], s[24:25], 0, v[138:139]
	s_add_i32 m0, s36, 0xc000
	ds_read_b128 v[180:183], v147
	ds_read_b128 v[186:189], v147 offset:1024
	ds_read_b128 v[190:193], v147 offset:2048
	ds_read_b128 v[194:197], v147 offset:3072
	ds_read_b128 v[198:201], v147 offset:4096
	ds_read_b128 v[202:205], v147 offset:5120
	ds_read_b128 v[206:209], v147 offset:6144
	ds_read_b128 v[210:213], v147 offset:7168
	global_load_lds_dwordx4 v[140:141], off
	v_lshl_add_u64 v[140:141], s[24:25], 0, v[136:137]
	s_add_i32 m0, s36, 0xe000
	s_nop 0
	global_load_lds_dwordx4 v[140:141], off
	s_waitcnt vmcnt(6)
	s_waitcnt lgkmcnt(0)
	s_barrier
	s_setprio 1
	s_waitcnt lgkmcnt(0)
	v_mfma_f32_16x16x32_bf16 v[124:127], v[148:151], v[180:183], v[124:127]
	v_mfma_f32_16x16x32_bf16 v[120:123], v[156:159], v[180:183], v[120:123]
	v_mfma_f32_16x16x32_bf16 v[116:119], v[148:151], v[190:193], v[116:119]
	v_mfma_f32_16x16x32_bf16 v[108:111], v[156:159], v[190:193], v[108:111]
	v_mfma_f32_16x16x32_bf16 v[100:103], v[148:151], v[198:201], v[100:103]
	v_mfma_f32_16x16x32_bf16 v[92:95], v[156:159], v[198:201], v[92:95]
	v_mfma_f32_16x16x32_bf16 v[84:87], v[148:151], v[206:209], v[84:87]
	v_mfma_f32_16x16x32_bf16 v[76:79], v[156:159], v[206:209], v[76:79]
	v_mfma_f32_16x16x32_bf16 v[124:127], v[152:155], v[186:189], v[124:127]
	v_mfma_f32_16x16x32_bf16 v[120:123], v[160:163], v[186:189], v[120:123]
	v_mfma_f32_16x16x32_bf16 v[116:119], v[152:155], v[194:197], v[116:119]
	v_mfma_f32_16x16x32_bf16 v[108:111], v[160:163], v[194:197], v[108:111]
	v_mfma_f32_16x16x32_bf16 v[100:103], v[152:155], v[202:205], v[100:103]
	v_mfma_f32_16x16x32_bf16 v[92:95], v[160:163], v[202:205], v[92:95]
	v_mfma_f32_16x16x32_bf16 v[84:87], v[152:155], v[210:213], v[84:87]
	v_mfma_f32_16x16x32_bf16 v[76:79], v[160:163], v[210:213], v[76:79]
	s_setprio 0
	s_setprio 1
	v_mfma_f32_16x16x32_bf16 v[112:115], v[164:167], v[180:183], v[112:115]
	v_mfma_f32_16x16x32_bf16 v[104:107], v[172:175], v[180:183], v[104:107]
	v_mfma_f32_16x16x32_bf16 v[96:99], v[164:167], v[190:193], v[96:99]
	v_mfma_f32_16x16x32_bf16 v[88:91], v[172:175], v[190:193], v[88:91]
	v_mfma_f32_16x16x32_bf16 v[80:83], v[164:167], v[198:201], v[80:83]
	v_mfma_f32_16x16x32_bf16 v[72:75], v[172:175], v[198:201], v[72:75]
	v_mfma_f32_16x16x32_bf16 v[68:71], v[164:167], v[206:209], v[68:71]
	v_mfma_f32_16x16x32_bf16 v[64:67], v[172:175], v[206:209], v[64:67]
	v_mfma_f32_16x16x32_bf16 v[112:115], v[168:171], v[186:189], v[112:115]
	v_mfma_f32_16x16x32_bf16 v[104:107], v[176:179], v[186:189], v[104:107]
	v_mfma_f32_16x16x32_bf16 v[96:99], v[168:171], v[194:197], v[96:99]
	v_mfma_f32_16x16x32_bf16 v[88:91], v[176:179], v[194:197], v[88:91]
	v_mfma_f32_16x16x32_bf16 v[80:83], v[168:171], v[202:205], v[80:83]
	v_mfma_f32_16x16x32_bf16 v[72:75], v[176:179], v[202:205], v[72:75]
	v_mfma_f32_16x16x32_bf16 v[68:71], v[168:171], v[210:213], v[68:71]
	v_mfma_f32_16x16x32_bf16 v[64:67], v[176:179], v[210:213], v[64:67]
	s_setprio 0
	s_barrier
	s_add_i32 s24, s44, s35
	v_lshl_add_u64 v[140:141], s[28:29], 0, v[130:131]
	s_mov_b32 m0, s24
	ds_read_b128 v[180:183], v147 offset:16384
	ds_read_b128 v[186:189], v147 offset:17408
	ds_read_b128 v[190:193], v147 offset:18432
	ds_read_b128 v[194:197], v147 offset:19456
	ds_read_b128 v[198:201], v147 offset:20480
	ds_read_b128 v[202:205], v147 offset:21504
	ds_read_b128 v[206:209], v147 offset:22528
	ds_read_b128 v[210:213], v147 offset:23552
	global_load_lds_dwordx4 v[140:141], off
	s_add_i32 m0, s24, 0x2000
	s_add_u32 s24, s28, 0xb0000
	v_lshl_add_u64 v[214:215], s[28:29], 0, v[134:135]
	s_addc_u32 s25, s29, 0
	s_add_i32 s58, s45, s35
	global_load_lds_dwordx4 v[214:215], off
	v_lshl_add_u64 v[216:217], s[24:25], 0, v[130:131]
	s_mov_b32 m0, s58
	v_lshl_add_u64 v[218:219], s[30:31], 0, v[132:133]
	global_load_lds_dwordx4 v[216:217], off
	v_lshl_add_u64 v[216:217], s[24:25], 0, v[134:135]
	s_add_i32 m0, s58, 0x2000
	s_nop 0
	global_load_lds_dwordx4 v[216:217], off
	v_lshl_add_u64 v[216:217], s[30:31], 0, v[128:129]
	s_mov_b32 m0, s36
	s_nop 0
	global_load_lds_dwordx4 v[216:217], off
	s_mov_b32 m0, s37
	s_nop 0
	global_load_lds_dwordx4 v[218:219], off
	s_waitcnt vmcnt(6)
	s_waitcnt lgkmcnt(0)
	s_barrier
; #define PG8_STAGE(bufoff, gbase, voff) do { _Pragma("unroll") for (int _i = 0; _i < 2; ++_i) \
;         __builtin_amdgcn_global_load_lds((const unsigned*)((const char*)(gbase) + (voff)[_i]), (PG8_LAS unsigned*)(lds + (bufoff) + ldsw + _i * 8192), 16, 0, 0); } while (0)
; #define PG8_LDA(dst, b, h) do { _Pragma("unroll") for (int m = 0; m < 4; ++m) _Pragma("unroll") for (int k = 0; k < 2; ++k) dst[m][k] = *(const PG8_LAS bf16x8*)(lds + PG8_SA(b, h) + aoff + m * 2048 + k * 1024); } while (0)
; #define PG8_LDB(dst, b, h) do { _Pragma("unroll") for (int n = 0; n < 2; ++n) _Pragma("unroll") for (int k = 0; k < 2; ++k) dst[n][k] = *(const PG8_LAS bf16x8*)(lds + PG8_SB(b, h) + boff + n * 2048 + k * 1024); } while (0)
; #define PG8_MMA(ai, bj, At, Bt) do { __builtin_amdgcn_s_setprio(1); _Pragma("unroll") for (int m = 0; m < 4; ++m) _Pragma("unroll") for (int n = 0; n < 2; ++n) _Pragma("unroll") for (int k = 0; k < 2; ++k) \
;         acc[ai][bj][m][n] = __builtin_amdgcn_mfma_f32_16x16x32_bf16(Bt[n][k], At[m][k], acc[ai][bj][m][n], 0, 0, 0); __builtin_amdgcn_s_setprio(0); } while (0)
; #define PG8_WAIT_V(n) asm volatile("s_waitcnt vmcnt(" #n ")" ::: "memory")
; #define PG8_WAIT_L(n) asm volatile("s_waitcnt lgkmcnt(" #n ")" ::: "memory")
; #define PG8_BAR __builtin_amdgcn_s_barrier()
; #define PG8_SCHED __builtin_amdgcn_sched_barrier(0)
; template <class Epi, class Sched, bool ALIGN_EPI = false, bool SP2 = false>
; __device__ __forceinline__ void gemm_phase(PG8_LAS unsigned char* lds, const Gemm g, const Sched& S, const Epi& E) {
;     ...
;             PG8_WAIT_V(8); PG8_WAIT_L(0); PG8_BAR; PG8_MMA(1, 0, At, B0); PG8_MMA(1, 1, At, B1); PG8_BAR; PG8_SCHED;
;             PG8_LDB(B0, 1, 0); PG8_LDB(B1, 1, 1); PG8_SCHED; PG8_LDA(At, 1, 0); PG8_STAGE(PG8_SA(0, 1), a2 + hstep, voffA);
;             PG8_WAIT_V(8); PG8_WAIT_L(0); PG8_BAR; PG8_MMA(0, 0, At, B0); PG8_MMA(0, 1, At, B1); PG8_BAR; PG8_SCHED;
	s_setprio 1
	s_waitcnt lgkmcnt(0)
	v_mfma_f32_16x16x32_bf16 v[60:63], v[148:151], v[180:183], v[60:63]
	v_mfma_f32_16x16x32_bf16 v[56:59], v[156:159], v[180:183], v[56:59]
	v_mfma_f32_16x16x32_bf16 v[52:55], v[148:151], v[190:193], v[52:55]
	v_mfma_f32_16x16x32_bf16 v[44:47], v[156:159], v[190:193], v[44:47]
	v_mfma_f32_16x16x32_bf16 v[36:39], v[148:151], v[198:201], v[36:39]
	v_mfma_f32_16x16x32_bf16 v[28:31], v[156:159], v[198:201], v[28:31]
	v_mfma_f32_16x16x32_bf16 v[20:23], v[148:151], v[206:209], v[20:23]
	v_mfma_f32_16x16x32_bf16 v[12:15], v[156:159], v[206:209], v[12:15]
	v_mfma_f32_16x16x32_bf16 v[60:63], v[152:155], v[186:189], v[60:63]
	v_mfma_f32_16x16x32_bf16 v[56:59], v[160:163], v[186:189], v[56:59]
	v_mfma_f32_16x16x32_bf16 v[52:55], v[152:155], v[194:197], v[52:55]
	v_mfma_f32_16x16x32_bf16 v[44:47], v[160:163], v[194:197], v[44:47]
	v_mfma_f32_16x16x32_bf16 v[36:39], v[152:155], v[202:205], v[36:39]
	v_mfma_f32_16x16x32_bf16 v[28:31], v[160:163], v[202:205], v[28:31]
	v_mfma_f32_16x16x32_bf16 v[20:23], v[152:155], v[210:213], v[20:23]
	v_mfma_f32_16x16x32_bf16 v[12:15], v[160:163], v[210:213], v[12:15]
	s_setprio 0
	s_setprio 1
	v_mfma_f32_16x16x32_bf16 v[48:51], v[164:167], v[180:183], v[48:51]
	v_mfma_f32_16x16x32_bf16 v[40:43], v[172:175], v[180:183], v[40:43]
	v_mfma_f32_16x16x32_bf16 v[32:35], v[164:167], v[190:193], v[32:35]
	v_mfma_f32_16x16x32_bf16 v[24:27], v[172:175], v[190:193], v[24:27]
	v_mfma_f32_16x16x32_bf16 v[16:19], v[164:167], v[198:201], v[16:19]
	v_mfma_f32_16x16x32_bf16 v[8:11], v[172:175], v[198:201], v[8:11]
	v_mfma_f32_16x16x32_bf16 v[4:7], v[164:167], v[206:209], v[4:7]
	v_mfma_f32_16x16x32_bf16 v[0:3], v[172:175], v[206:209], v[0:3]
	v_mfma_f32_16x16x32_bf16 v[48:51], v[168:171], v[186:189], v[48:51]
	v_mfma_f32_16x16x32_bf16 v[40:43], v[176:179], v[186:189], v[40:43]
	v_mfma_f32_16x16x32_bf16 v[32:35], v[168:171], v[194:197], v[32:35]
	v_mfma_f32_16x16x32_bf16 v[24:27], v[176:179], v[194:197], v[24:27]
	v_mfma_f32_16x16x32_bf16 v[16:19], v[168:171], v[202:205], v[16:19]
	v_mfma_f32_16x16x32_bf16 v[8:11], v[176:179], v[202:205], v[8:11]
	v_mfma_f32_16x16x32_bf16 v[4:7], v[168:171], v[210:213], v[4:7]
	v_mfma_f32_16x16x32_bf16 v[0:3], v[176:179], v[210:213], v[0:3]
	s_setprio 0
	s_barrier
	s_add_i32 s58, 0, 0x18000
	s_add_i32 s59, 0, 0x1c000
	v_add_u32_e32 v160, s58, v143
	v_add_u32_e32 v176, s59, v143
	ds_read_b128 v[148:151], v160
	ds_read_b128 v[152:155], v160 offset:1024
	ds_read_b128 v[156:159], v160 offset:2048
	ds_read_b128 v[160:163], v160 offset:3072
	ds_read_b128 v[164:167], v176
	ds_read_b128 v[168:171], v176 offset:1024
	ds_read_b128 v[172:175], v176 offset:2048
	ds_read_b128 v[176:179], v176 offset:3072
	s_add_u32 s24, s30, 0xb0000
	s_addc_u32 s25, s31, 0
	s_mov_b32 m0, s38
	v_lshl_add_u64 v[220:221], s[24:25], 0, v[128:129]
	ds_read_b128 v[180:183], v147 offset:32768
	ds_read_b128 v[186:189], v147 offset:33792
	ds_read_b128 v[190:193], v147 offset:34816
	ds_read_b128 v[194:197], v147 offset:35840
	ds_read_b128 v[198:201], v147 offset:36864
	ds_read_b128 v[202:205], v147 offset:37888
	ds_read_b128 v[206:209], v147 offset:38912
	ds_read_b128 v[210:213], v147 offset:39936
	global_load_lds_dwordx4 v[220:221], off
	v_lshl_add_u64 v[220:221], s[24:25], 0, v[132:133]
	s_mov_b32 m0, s39
	s_nop 0
	global_load_lds_dwordx4 v[220:221], off
	s_waitcnt vmcnt(6)
	s_waitcnt lgkmcnt(0)
	s_barrier
	s_setprio 1
	s_waitcnt lgkmcnt(0)
	v_mfma_f32_16x16x32_bf16 v[124:127], v[148:151], v[180:183], v[124:127]
	v_mfma_f32_16x16x32_bf16 v[120:123], v[156:159], v[180:183], v[120:123]
	v_mfma_f32_16x16x32_bf16 v[116:119], v[148:151], v[190:193], v[116:119]
	v_mfma_f32_16x16x32_bf16 v[108:111], v[156:159], v[190:193], v[108:111]
	v_mfma_f32_16x16x32_bf16 v[100:103], v[148:151], v[198:201], v[100:103]
	v_mfma_f32_16x16x32_bf16 v[92:95], v[156:159], v[198:201], v[92:95]
	v_mfma_f32_16x16x32_bf16 v[84:87], v[148:151], v[206:209], v[84:87]
	v_mfma_f32_16x16x32_bf16 v[76:79], v[156:159], v[206:209], v[76:79]
	v_mfma_f32_16x16x32_bf16 v[124:127], v[152:155], v[186:189], v[124:127]
	v_mfma_f32_16x16x32_bf16 v[120:123], v[160:163], v[186:189], v[120:123]
	v_mfma_f32_16x16x32_bf16 v[116:119], v[152:155], v[194:197], v[116:119]
	v_mfma_f32_16x16x32_bf16 v[108:111], v[160:163], v[194:197], v[108:111]
	v_mfma_f32_16x16x32_bf16 v[100:103], v[152:155], v[202:205], v[100:103]
	v_mfma_f32_16x16x32_bf16 v[92:95], v[160:163], v[202:205], v[92:95]
	v_mfma_f32_16x16x32_bf16 v[84:87], v[152:155], v[210:213], v[84:87]
	v_mfma_f32_16x16x32_bf16 v[76:79], v[160:163], v[210:213], v[76:79]
	s_setprio 0
	s_setprio 1
	v_mfma_f32_16x16x32_bf16 v[112:115], v[164:167], v[180:183], v[112:115]
	v_mfma_f32_16x16x32_bf16 v[104:107], v[172:175], v[180:183], v[104:107]
	v_mfma_f32_16x16x32_bf16 v[96:99], v[164:167], v[190:193], v[96:99]
	v_mfma_f32_16x16x32_bf16 v[88:91], v[172:175], v[190:193], v[88:91]
	v_mfma_f32_16x16x32_bf16 v[80:83], v[164:167], v[198:201], v[80:83]
	v_mfma_f32_16x16x32_bf16 v[72:75], v[172:175], v[198:201], v[72:75]
	v_mfma_f32_16x16x32_bf16 v[68:71], v[164:167], v[206:209], v[68:71]
	v_mfma_f32_16x16x32_bf16 v[64:67], v[172:175], v[206:209], v[64:67]
	v_mfma_f32_16x16x32_bf16 v[112:115], v[168:171], v[186:189], v[112:115]
	v_mfma_f32_16x16x32_bf16 v[104:107], v[176:179], v[186:189], v[104:107]
	v_mfma_f32_16x16x32_bf16 v[96:99], v[168:171], v[194:197], v[96:99]
	v_mfma_f32_16x16x32_bf16 v[88:91], v[176:179], v[194:197], v[88:91]
	v_mfma_f32_16x16x32_bf16 v[80:83], v[168:171], v[202:205], v[80:83]
	v_mfma_f32_16x16x32_bf16 v[72:75], v[176:179], v[202:205], v[72:75]
	v_mfma_f32_16x16x32_bf16 v[68:71], v[168:171], v[210:213], v[68:71]
	v_mfma_f32_16x16x32_bf16 v[64:67], v[176:179], v[210:213], v[64:67]
	s_setprio 0
	s_barrier
; #define PG8_STAGE(bufoff, gbase, voff) do { _Pragma("unroll") for (int _i = 0; _i < 2; ++_i) \
;         __builtin_amdgcn_global_load_lds((const unsigned*)((const char*)(gbase) + (voff)[_i]), (PG8_LAS unsigned*)(lds + (bufoff) + ldsw + _i * 8192), 16, 0, 0); } while (0)
; #define PG8_LDA(dst, b, h) do { _Pragma("unroll") for (int m = 0; m < 4; ++m) _Pragma("unroll") for (int k = 0; k < 2; ++k) dst[m][k] = *(const PG8_LAS bf16x8*)(lds + PG8_SA(b, h) + aoff + m * 2048 + k * 1024); } while (0)
; #define PG8_MMA(ai, bj, At, Bt) do { __builtin_amdgcn_s_setprio(1); _Pragma("unroll") for (int m = 0; m < 4; ++m) _Pragma("unroll") for (int n = 0; n < 2; ++n) _Pragma("unroll") for (int k = 0; k < 2; ++k) \
;         acc[ai][bj][m][n] = __builtin_amdgcn_mfma_f32_16x16x32_bf16(Bt[n][k], At[m][k], acc[ai][bj][m][n], 0, 0, 0); __builtin_amdgcn_s_setprio(0); } while (0)
; #define PG8_WAIT_V(n) asm volatile("s_waitcnt vmcnt(" #n ")" ::: "memory")
; #define PG8_WAIT_L(n) asm volatile("s_waitcnt lgkmcnt(" #n ")" ::: "memory")
; #define PG8_BAR __builtin_amdgcn_s_barrier()
; #define PG8_SCHED __builtin_amdgcn_sched_barrier(0)
; template <class Epi, class Sched, bool ALIGN_EPI = false, bool SP2 = false>
; __device__ __forceinline__ void gemm_phase(PG8_LAS unsigned char* lds, const Gemm g, const Sched& S, const Epi& E) {
;     ...
;         for (int t = 0; t < nt; t += 2) {
;             const bool last = (t == nt - 2);
;             const char* a1 = cA + (size_t)(t + 1) * kstep;
;             const char* a2 = last ? nA : cA + (size_t)(t + 2) * kstep; const char* b2 = last ? nB : cB + (size_t)(t + 2) * kstep;
;     ...
;             PG8_LDA(At, 1, 1); PG8_STAGE(PG8_SB(1, 0), b3, voffB); PG8_STAGE(PG8_SB(1, 1), b3 + hstep, voffB); PG8_STAGE(PG8_SA(1, 0), a3, voffA);
;             PG8_WAIT_V(8); PG8_WAIT_L(0); PG8_BAR; PG8_MMA(1, 0, At, B0); PG8_MMA(1, 1, At, B1); PG8_BAR; PG8_SCHED;
	s_add_i32 s24, s58, s35
	v_lshl_add_u64 v[140:141], v[140:141], 0, s[8:9]
	s_mov_b32 m0, s24
	ds_read_b128 v[180:183], v147 offset:49152
	ds_read_b128 v[186:189], v147 offset:50176
	ds_read_b128 v[190:193], v147 offset:51200
	ds_read_b128 v[194:197], v147 offset:52224
	ds_read_b128 v[198:201], v147 offset:53248
	ds_read_b128 v[202:205], v147 offset:54272
	ds_read_b128 v[206:209], v147 offset:55296
	ds_read_b128 v[210:213], v147 offset:56320
	global_load_lds_dwordx4 v[140:141], off
	s_add_i32 m0, s24, 0x2000
	s_add_u32 s24, s28, 0xb0080
	v_lshl_add_u64 v[140:141], v[214:215], 0, s[8:9]
	s_addc_u32 s25, s29, 0
	s_add_i32 s28, s59, s35
	global_load_lds_dwordx4 v[140:141], off
	v_lshl_add_u64 v[140:141], s[24:25], 0, v[130:131]
	s_mov_b32 m0, s28
	s_nop 0
	global_load_lds_dwordx4 v[140:141], off
	v_lshl_add_u64 v[140:141], s[24:25], 0, v[134:135]
	s_add_i32 m0, s28, 0x2000
	s_nop 0
	global_load_lds_dwordx4 v[140:141], off
	v_lshl_add_u64 v[140:141], v[216:217], 0, s[8:9]
	s_mov_b32 m0, s40
	s_nop 0
	global_load_lds_dwordx4 v[140:141], off
	v_lshl_add_u64 v[140:141], v[218:219], 0, s[8:9]
	s_mov_b32 m0, s41
	s_nop 0
	global_load_lds_dwordx4 v[140:141], off
	s_waitcnt vmcnt(6)
	s_waitcnt lgkmcnt(0)
	s_barrier
	s_setprio 1
	s_waitcnt lgkmcnt(0)
	v_mfma_f32_16x16x32_bf16 v[60:63], v[148:151], v[180:183], v[60:63]
	v_mfma_f32_16x16x32_bf16 v[56:59], v[156:159], v[180:183], v[56:59]
	v_mfma_f32_16x16x32_bf16 v[52:55], v[148:151], v[190:193], v[52:55]
	v_mfma_f32_16x16x32_bf16 v[44:47], v[156:159], v[190:193], v[44:47]
	v_mfma_f32_16x16x32_bf16 v[36:39], v[148:151], v[198:201], v[36:39]
	v_mfma_f32_16x16x32_bf16 v[28:31], v[156:159], v[198:201], v[28:31]
	v_mfma_f32_16x16x32_bf16 v[20:23], v[148:151], v[206:209], v[20:23]
	v_mfma_f32_16x16x32_bf16 v[12:15], v[156:159], v[206:209], v[12:15]
	v_mfma_f32_16x16x32_bf16 v[60:63], v[152:155], v[186:189], v[60:63]
	v_mfma_f32_16x16x32_bf16 v[56:59], v[160:163], v[186:189], v[56:59]
	v_mfma_f32_16x16x32_bf16 v[52:55], v[152:155], v[194:197], v[52:55]
	v_mfma_f32_16x16x32_bf16 v[44:47], v[160:163], v[194:197], v[44:47]
	v_mfma_f32_16x16x32_bf16 v[36:39], v[152:155], v[202:205], v[36:39]
	v_mfma_f32_16x16x32_bf16 v[28:31], v[160:163], v[202:205], v[28:31]
	v_mfma_f32_16x16x32_bf16 v[20:23], v[152:155], v[210:213], v[20:23]
	v_mfma_f32_16x16x32_bf16 v[12:15], v[160:163], v[210:213], v[12:15]
	s_setprio 0
	s_setprio 1
	v_mfma_f32_16x16x32_bf16 v[48:51], v[164:167], v[180:183], v[48:51]
	v_mfma_f32_16x16x32_bf16 v[40:43], v[172:175], v[180:183], v[40:43]
	v_mfma_f32_16x16x32_bf16 v[32:35], v[164:167], v[190:193], v[32:35]
	v_mfma_f32_16x16x32_bf16 v[24:27], v[172:175], v[190:193], v[24:27]
	v_mfma_f32_16x16x32_bf16 v[16:19], v[164:167], v[198:201], v[16:19]
	v_mfma_f32_16x16x32_bf16 v[8:11], v[172:175], v[198:201], v[8:11]
	v_mfma_f32_16x16x32_bf16 v[4:7], v[164:167], v[206:209], v[4:7]
	v_mfma_f32_16x16x32_bf16 v[0:3], v[172:175], v[206:209], v[0:3]
	v_mfma_f32_16x16x32_bf16 v[48:51], v[168:171], v[186:189], v[48:51]
	v_mfma_f32_16x16x32_bf16 v[40:43], v[176:179], v[186:189], v[40:43]
	v_mfma_f32_16x16x32_bf16 v[32:35], v[168:171], v[194:197], v[32:35]
	v_mfma_f32_16x16x32_bf16 v[24:27], v[176:179], v[194:197], v[24:27]
	v_mfma_f32_16x16x32_bf16 v[16:19], v[168:171], v[202:205], v[16:19]
	v_mfma_f32_16x16x32_bf16 v[8:11], v[176:179], v[202:205], v[8:11]
	v_mfma_f32_16x16x32_bf16 v[4:7], v[168:171], v[210:213], v[4:7]
	v_mfma_f32_16x16x32_bf16 v[0:3], v[176:179], v[210:213], v[0:3]
	s_setprio 0
	s_barrier
	s_add_i32 s57, s57, 2
	s_add_u32 s55, s55, 0x100
	s_addc_u32 s56, s56, 0
	s_cmp_gt_u32 s57, 41
	s_mov_b64 s[24:25], s[26:27]
	s_cbranch_scc0 .LBB0_269
	s_and_b64 vcc, exec, s[10:11]
	s_cbranch_vccz .LBB0_272
	s_barrier

; #define PG8_STAGE(bufoff, gbase, voff) do { _Pragma("unroll") for (int _i = 0; _i < 2; ++_i) \
;         __builtin_amdgcn_global_load_lds((const unsigned*)((const char*)(gbase) + (voff)[_i]), (PG8_LAS unsigned*)(lds + (bufoff) + ldsw + _i * 8192), 16, 0, 0); } while (0)
; #define PG8_LDA(dst, b, h) do { _Pragma("unroll") for (int m = 0; m < 4; ++m) _Pragma("unroll") for (int k = 0; k < 2; ++k) dst[m][k] = *(const PG8_LAS bf16x8*)(lds + PG8_SA(b, h) + aoff + m * 2048 + k * 1024); } while (0)
; #define PG8_LDB(dst, b, h) do { _Pragma("unroll") for (int n = 0; n < 2; ++n) _Pragma("unroll") for (int k = 0; k < 2; ++k) dst[n][k] = *(const PG8_LAS bf16x8*)(lds + PG8_SB(b, h) + boff + n * 2048 + k * 1024); } while (0)
; #define PG8_MMA(ai, bj, At, Bt) do { __builtin_amdgcn_s_setprio(1); _Pragma("unroll") for (int m = 0; m < 4; ++m) _Pragma("unroll") for (int n = 0; n < 2; ++n) _Pragma("unroll") for (int k = 0; k < 2; ++k) \
;         acc[ai][bj][m][n] = __builtin_amdgcn_mfma_f32_16x16x32_bf16(Bt[n][k], At[m][k], acc[ai][bj][m][n], 0, 0, 0); __builtin_amdgcn_s_setprio(0); } while (0)
; #define PG8_WAIT_V(n) asm volatile("s_waitcnt vmcnt(" #n ")" ::: "memory")
; #define PG8_WAIT_L(n) asm volatile("s_waitcnt lgkmcnt(" #n ")" ::: "memory")
; #define PG8_BAR __builtin_amdgcn_s_barrier()
; #define PG8_SCHED __builtin_amdgcn_sched_barrier(0)
; template <class Epi, class Sched, bool ALIGN_EPI = false, bool SP2 = false>
; __device__ __forceinline__ void gemm_phase(PG8_LAS unsigned char* lds, const Gemm g, const Sched& S, const Epi& E) {
;     ...
;         for (int t = 0; t < nt; t += 2) {
;             const bool last = (t == nt - 2);
;             const char* a1 = cA + (size_t)(t + 1) * kstep;
;             const char* a2 = last ? nA : cA + (size_t)(t + 2) * kstep; const char* b2 = last ? nB : cB + (size_t)(t + 2) * kstep;
;             const char* a3 = a2 + kstep; const char* b3 = b2 + kstep;
;             if (last && has_next) S.a_ready(nxt);
;             if constexpr (SP2) {
;             PG8_LDB(B0, 0, 0); PG8_LDB(B1, 0, 1); PG8_SCHED; PG8_LDA(At, 0, 0); PG8_STAGE(PG8_SA(1, 1), a1 + hstep, voffA);
;             PG8_WAIT_V(8); PG8_WAIT_L(0); PG8_BAR; PG8_MMA(0, 0, At, B0); PG8_MMA(0, 1, At, B1); PG8_BAR; PG8_SCHED;
;             PG8_LDA(At, 0, 1); PG8_STAGE(PG8_SB(0, 0), b2, voffB); PG8_STAGE(PG8_SB(0, 1), b2 + hstep, voffB); PG8_STAGE(PG8_SA(0, 0), a2, voffA);
.LBB0_343:
	ds_read_b128 v[144:147], v151
	ds_read_b128 v[154:157], v151 offset:1024
	ds_read_b128 v[158:161], v151 offset:2048
	ds_read_b128 v[162:165], v151 offset:3072
	ds_read_b128 v[166:169], v152
	ds_read_b128 v[170:173], v152 offset:1024
	ds_read_b128 v[174:177], v152 offset:2048
	ds_read_b128 v[178:181], v152 offset:3072
	s_add_u32 s22, s20, 0xfffc0080
	s_addc_u32 s23, s21, -1
	s_cmp_eq_u32 s50, 12
	s_cselect_b32 s25, s13, s23
	s_cselect_b32 s24, s46, s22
	s_cselect_b32 s23, s11, s49
	s_cselect_b32 s22, s47, s48
	v_lshl_add_u64 v[182:183], s[20:21], 0, v[138:139]
	s_add_i32 m0, s19, 0xc000
	ds_read_b128 v[186:189], v153
	ds_read_b128 v[190:193], v153 offset:1024
	ds_read_b128 v[194:197], v153 offset:2048
	ds_read_b128 v[198:201], v153 offset:3072
	ds_read_b128 v[202:205], v153 offset:4096
	ds_read_b128 v[206:209], v153 offset:5120
	ds_read_b128 v[210:213], v153 offset:6144
	ds_read_b128 v[214:217], v153 offset:7168
	global_load_lds_dwordx4 v[182:183], off
	v_lshl_add_u64 v[182:183], s[20:21], 0, v[136:137]
	s_add_i32 m0, s19, 0xe000
	s_nop 0
	global_load_lds_dwordx4 v[182:183], off
	s_waitcnt vmcnt(6)
	s_waitcnt lgkmcnt(0)
	s_barrier
	s_setprio 1
	s_waitcnt lgkmcnt(0)
	v_mfma_f32_16x16x32_bf16 v[124:127], v[144:147], v[186:189], v[124:127]
	v_mfma_f32_16x16x32_bf16 v[120:123], v[158:161], v[186:189], v[120:123]
	v_mfma_f32_16x16x32_bf16 v[116:119], v[144:147], v[194:197], v[116:119]
	v_mfma_f32_16x16x32_bf16 v[108:111], v[158:161], v[194:197], v[108:111]
	v_mfma_f32_16x16x32_bf16 v[100:103], v[144:147], v[202:205], v[100:103]
	v_mfma_f32_16x16x32_bf16 v[92:95], v[158:161], v[202:205], v[92:95]
	v_mfma_f32_16x16x32_bf16 v[84:87], v[144:147], v[210:213], v[84:87]
	v_mfma_f32_16x16x32_bf16 v[76:79], v[158:161], v[210:213], v[76:79]
	v_mfma_f32_16x16x32_bf16 v[124:127], v[154:157], v[190:193], v[124:127]
	v_mfma_f32_16x16x32_bf16 v[120:123], v[162:165], v[190:193], v[120:123]
	v_mfma_f32_16x16x32_bf16 v[116:119], v[154:157], v[198:201], v[116:119]
	v_mfma_f32_16x16x32_bf16 v[108:111], v[162:165], v[198:201], v[108:111]
	v_mfma_f32_16x16x32_bf16 v[100:103], v[154:157], v[206:209], v[100:103]
	v_mfma_f32_16x16x32_bf16 v[92:95], v[162:165], v[206:209], v[92:95]
	v_mfma_f32_16x16x32_bf16 v[84:87], v[154:157], v[214:217], v[84:87]
	v_mfma_f32_16x16x32_bf16 v[76:79], v[162:165], v[214:217], v[76:79]
	s_setprio 0
	s_setprio 1
	v_mfma_f32_16x16x32_bf16 v[112:115], v[166:169], v[186:189], v[112:115]
	v_mfma_f32_16x16x32_bf16 v[104:107], v[174:177], v[186:189], v[104:107]
	v_mfma_f32_16x16x32_bf16 v[96:99], v[166:169], v[194:197], v[96:99]
	v_mfma_f32_16x16x32_bf16 v[88:91], v[174:177], v[194:197], v[88:91]
	v_mfma_f32_16x16x32_bf16 v[80:83], v[166:169], v[202:205], v[80:83]
	v_mfma_f32_16x16x32_bf16 v[72:75], v[174:177], v[202:205], v[72:75]
	v_mfma_f32_16x16x32_bf16 v[68:71], v[166:169], v[210:213], v[68:71]
	v_mfma_f32_16x16x32_bf16 v[64:67], v[174:177], v[210:213], v[64:67]
	v_mfma_f32_16x16x32_bf16 v[112:115], v[170:173], v[190:193], v[112:115]
	v_mfma_f32_16x16x32_bf16 v[104:107], v[178:181], v[190:193], v[104:107]
	v_mfma_f32_16x16x32_bf16 v[96:99], v[170:173], v[198:201], v[96:99]
	v_mfma_f32_16x16x32_bf16 v[88:91], v[178:181], v[198:201], v[88:91]
	v_mfma_f32_16x16x32_bf16 v[80:83], v[170:173], v[206:209], v[80:83]
	v_mfma_f32_16x16x32_bf16 v[72:75], v[178:181], v[206:209], v[72:75]
	v_mfma_f32_16x16x32_bf16 v[68:71], v[170:173], v[214:217], v[68:71]
	v_mfma_f32_16x16x32_bf16 v[64:67], v[178:181], v[214:217], v[64:67]
	s_setprio 0
	s_barrier
	s_add_i32 s51, s42, s30
	v_lshl_add_u64 v[182:183], s[22:23], 0, v[132:133]
	s_mov_b32 m0, s51
	ds_read_b128 v[186:189], v153 offset:16384
	ds_read_b128 v[190:193], v153 offset:17408
	ds_read_b128 v[194:197], v153 offset:18432
	ds_read_b128 v[198:201], v153 offset:19456
	ds_read_b128 v[202:205], v153 offset:20480
	ds_read_b128 v[206:209], v153 offset:21504
	ds_read_b128 v[210:213], v153 offset:22528
	ds_read_b128 v[214:217], v153 offset:23552
	global_load_lds_dwordx4 v[182:183], off
	s_add_i32 m0, s51, 0x2000
	s_add_u32 s52, s22, 0x40000
	v_lshl_add_u64 v[218:219], s[22:23], 0, v[128:129]
	s_addc_u32 s53, s23, 0
	s_add_i32 s51, s43, s30
	global_load_lds_dwordx4 v[218:219], off
	v_lshl_add_u64 v[220:221], s[52:53], 0, v[132:133]
	s_mov_b32 m0, s51
	v_lshl_add_u64 v[222:223], s[24:25], 0, v[130:131]
	global_load_lds_dwordx4 v[220:221], off
	v_lshl_add_u64 v[220:221], s[52:53], 0, v[128:129]
	s_add_i32 m0, s51, 0x2000
	s_nop 0
	global_load_lds_dwordx4 v[220:221], off
	v_lshl_add_u64 v[220:221], s[24:25], 0, v[134:135]
	s_mov_b32 m0, s19
	s_nop 0
	global_load_lds_dwordx4 v[220:221], off
	s_mov_b32 m0, s34
	s_nop 0
	global_load_lds_dwordx4 v[222:223], off
	s_waitcnt vmcnt(6)
	s_waitcnt lgkmcnt(0)
	s_barrier
; #define PG8_STAGE(bufoff, gbase, voff) do { _Pragma("unroll") for (int _i = 0; _i < 2; ++_i) \
;         __builtin_amdgcn_global_load_lds((const unsigned*)((const char*)(gbase) + (voff)[_i]), (PG8_LAS unsigned*)(lds + (bufoff) + ldsw + _i * 8192), 16, 0, 0); } while (0)
; #define PG8_LDA(dst, b, h) do { _Pragma("unroll") for (int m = 0; m < 4; ++m) _Pragma("unroll") for (int k = 0; k < 2; ++k) dst[m][k] = *(const PG8_LAS bf16x8*)(lds + PG8_SA(b, h) + aoff + m * 2048 + k * 1024); } while (0)
; #define PG8_LDB(dst, b, h) do { _Pragma("unroll") for (int n = 0; n < 2; ++n) _Pragma("unroll") for (int k = 0; k < 2; ++k) dst[n][k] = *(const PG8_LAS bf16x8*)(lds + PG8_SB(b, h) + boff + n * 2048 + k * 1024); } while (0)
; #define PG8_MMA(ai, bj, At, Bt) do { __builtin_amdgcn_s_setprio(1); _Pragma("unroll") for (int m = 0; m < 4; ++m) _Pragma("unroll") for (int n = 0; n < 2; ++n) _Pragma("unroll") for (int k = 0; k < 2; ++k) \
;         acc[ai][bj][m][n] = __builtin_amdgcn_mfma_f32_16x16x32_bf16(Bt[n][k], At[m][k], acc[ai][bj][m][n], 0, 0, 0); __builtin_amdgcn_s_setprio(0); } while (0)
; #define PG8_WAIT_V(n) asm volatile("s_waitcnt vmcnt(" #n ")" ::: "memory")
; #define PG8_WAIT_L(n) asm volatile("s_waitcnt lgkmcnt(" #n ")" ::: "memory")
; #define PG8_BAR __builtin_amdgcn_s_barrier()
; #define PG8_SCHED __builtin_amdgcn_sched_barrier(0)
; template <class Epi, class Sched, bool ALIGN_EPI = false, bool SP2 = false>
; __device__ __forceinline__ void gemm_phase(PG8_LAS unsigned char* lds, const Gemm g, const Sched& S, const Epi& E) {
;     ...
;             PG8_WAIT_V(8); PG8_WAIT_L(0); PG8_BAR; PG8_MMA(1, 0, At, B0); PG8_MMA(1, 1, At, B1); PG8_BAR; PG8_SCHED;
;             PG8_LDB(B0, 1, 0); PG8_LDB(B1, 1, 1); PG8_SCHED; PG8_LDA(At, 1, 0); PG8_STAGE(PG8_SA(0, 1), a2 + hstep, voffA);
;             PG8_WAIT_V(8); PG8_WAIT_L(0); PG8_BAR; PG8_MMA(0, 0, At, B0); PG8_MMA(0, 1, At, B1); PG8_BAR; PG8_SCHED;
	s_setprio 1
	s_waitcnt lgkmcnt(0)
	v_mfma_f32_16x16x32_bf16 v[60:63], v[144:147], v[186:189], v[60:63]
	v_mfma_f32_16x16x32_bf16 v[56:59], v[158:161], v[186:189], v[56:59]
	v_mfma_f32_16x16x32_bf16 v[52:55], v[144:147], v[194:197], v[52:55]
	v_mfma_f32_16x16x32_bf16 v[44:47], v[158:161], v[194:197], v[44:47]
	v_mfma_f32_16x16x32_bf16 v[36:39], v[144:147], v[202:205], v[36:39]
	v_mfma_f32_16x16x32_bf16 v[28:31], v[158:161], v[202:205], v[28:31]
	v_mfma_f32_16x16x32_bf16 v[20:23], v[144:147], v[210:213], v[20:23]
	v_mfma_f32_16x16x32_bf16 v[12:15], v[158:161], v[210:213], v[12:15]
	v_mfma_f32_16x16x32_bf16 v[60:63], v[154:157], v[190:193], v[60:63]
	v_mfma_f32_16x16x32_bf16 v[56:59], v[162:165], v[190:193], v[56:59]
	v_mfma_f32_16x16x32_bf16 v[52:55], v[154:157], v[198:201], v[52:55]
	v_mfma_f32_16x16x32_bf16 v[44:47], v[162:165], v[198:201], v[44:47]
	v_mfma_f32_16x16x32_bf16 v[36:39], v[154:157], v[206:209], v[36:39]
	v_mfma_f32_16x16x32_bf16 v[28:31], v[162:165], v[206:209], v[28:31]
	v_mfma_f32_16x16x32_bf16 v[20:23], v[154:157], v[214:217], v[20:23]
	v_mfma_f32_16x16x32_bf16 v[12:15], v[162:165], v[214:217], v[12:15]
	s_setprio 0
	s_setprio 1
	v_mfma_f32_16x16x32_bf16 v[48:51], v[166:169], v[186:189], v[48:51]
	v_mfma_f32_16x16x32_bf16 v[40:43], v[174:177], v[186:189], v[40:43]
	v_mfma_f32_16x16x32_bf16 v[32:35], v[166:169], v[194:197], v[32:35]
	v_mfma_f32_16x16x32_bf16 v[24:27], v[174:177], v[194:197], v[24:27]
	v_mfma_f32_16x16x32_bf16 v[16:19], v[166:169], v[202:205], v[16:19]
	v_mfma_f32_16x16x32_bf16 v[8:11], v[174:177], v[202:205], v[8:11]
	v_mfma_f32_16x16x32_bf16 v[4:7], v[166:169], v[210:213], v[4:7]
	v_mfma_f32_16x16x32_bf16 v[0:3], v[174:177], v[210:213], v[0:3]
	v_mfma_f32_16x16x32_bf16 v[48:51], v[170:173], v[190:193], v[48:51]
	v_mfma_f32_16x16x32_bf16 v[40:43], v[178:181], v[190:193], v[40:43]
	v_mfma_f32_16x16x32_bf16 v[32:35], v[170:173], v[198:201], v[32:35]
	v_mfma_f32_16x16x32_bf16 v[24:27], v[178:181], v[198:201], v[24:27]
	v_mfma_f32_16x16x32_bf16 v[16:19], v[170:173], v[206:209], v[16:19]
	v_mfma_f32_16x16x32_bf16 v[8:11], v[178:181], v[206:209], v[8:11]
	v_mfma_f32_16x16x32_bf16 v[4:7], v[170:173], v[214:217], v[4:7]
	v_mfma_f32_16x16x32_bf16 v[0:3], v[178:181], v[214:217], v[0:3]
	s_setprio 0
	s_barrier
	s_add_i32 s51, 0, 0x18000
	s_add_i32 s52, 0, 0x1c000
	v_add_u32_e32 v162, s51, v149
	v_add_u32_e32 v178, s52, v149
	ds_read_b128 v[144:147], v162
	ds_read_b128 v[154:157], v162 offset:1024
	ds_read_b128 v[158:161], v162 offset:2048
	ds_read_b128 v[162:165], v162 offset:3072
	ds_read_b128 v[166:169], v178
	ds_read_b128 v[170:173], v178 offset:1024
	ds_read_b128 v[174:177], v178 offset:2048
	ds_read_b128 v[178:181], v178 offset:3072
	s_add_u32 s24, s24, 0x40000
	s_addc_u32 s25, s25, 0
	s_mov_b32 m0, s35
	v_lshl_add_u64 v[224:225], s[24:25], 0, v[134:135]
	ds_read_b128 v[186:189], v153 offset:32768
	ds_read_b128 v[190:193], v153 offset:33792
	ds_read_b128 v[194:197], v153 offset:34816
	ds_read_b128 v[198:201], v153 offset:35840
	ds_read_b128 v[202:205], v153 offset:36864
	ds_read_b128 v[206:209], v153 offset:37888
	ds_read_b128 v[210:213], v153 offset:38912
	ds_read_b128 v[214:217], v153 offset:39936
	global_load_lds_dwordx4 v[224:225], off
	v_lshl_add_u64 v[224:225], s[24:25], 0, v[130:131]
	s_mov_b32 m0, s36
	s_nop 0
	global_load_lds_dwordx4 v[224:225], off
	s_waitcnt vmcnt(6)
	s_waitcnt lgkmcnt(0)
	s_barrier
	s_setprio 1
	s_waitcnt lgkmcnt(0)
	v_mfma_f32_16x16x32_bf16 v[124:127], v[144:147], v[186:189], v[124:127]
	v_mfma_f32_16x16x32_bf16 v[120:123], v[158:161], v[186:189], v[120:123]
	v_mfma_f32_16x16x32_bf16 v[116:119], v[144:147], v[194:197], v[116:119]
	v_mfma_f32_16x16x32_bf16 v[108:111], v[158:161], v[194:197], v[108:111]
	v_mfma_f32_16x16x32_bf16 v[100:103], v[144:147], v[202:205], v[100:103]
	v_mfma_f32_16x16x32_bf16 v[92:95], v[158:161], v[202:205], v[92:95]
	v_mfma_f32_16x16x32_bf16 v[84:87], v[144:147], v[210:213], v[84:87]
	v_mfma_f32_16x16x32_bf16 v[76:79], v[158:161], v[210:213], v[76:79]
	v_mfma_f32_16x16x32_bf16 v[124:127], v[154:157], v[190:193], v[124:127]
	v_mfma_f32_16x16x32_bf16 v[120:123], v[162:165], v[190:193], v[120:123]
	v_mfma_f32_16x16x32_bf16 v[116:119], v[154:157], v[198:201], v[116:119]
	v_mfma_f32_16x16x32_bf16 v[108:111], v[162:165], v[198:201], v[108:111]
	v_mfma_f32_16x16x32_bf16 v[100:103], v[154:157], v[206:209], v[100:103]
	v_mfma_f32_16x16x32_bf16 v[92:95], v[162:165], v[206:209], v[92:95]
	v_mfma_f32_16x16x32_bf16 v[84:87], v[154:157], v[214:217], v[84:87]
	v_mfma_f32_16x16x32_bf16 v[76:79], v[162:165], v[214:217], v[76:79]
	s_setprio 0
	s_setprio 1
	v_mfma_f32_16x16x32_bf16 v[112:115], v[166:169], v[186:189], v[112:115]
	v_mfma_f32_16x16x32_bf16 v[104:107], v[174:177], v[186:189], v[104:107]
	v_mfma_f32_16x16x32_bf16 v[96:99], v[166:169], v[194:197], v[96:99]
	v_mfma_f32_16x16x32_bf16 v[88:91], v[174:177], v[194:197], v[88:91]
	v_mfma_f32_16x16x32_bf16 v[80:83], v[166:169], v[202:205], v[80:83]
	v_mfma_f32_16x16x32_bf16 v[72:75], v[174:177], v[202:205], v[72:75]
	v_mfma_f32_16x16x32_bf16 v[68:71], v[166:169], v[210:213], v[68:71]
	v_mfma_f32_16x16x32_bf16 v[64:67], v[174:177], v[210:213], v[64:67]
	v_mfma_f32_16x16x32_bf16 v[112:115], v[170:173], v[190:193], v[112:115]
	v_mfma_f32_16x16x32_bf16 v[104:107], v[178:181], v[190:193], v[104:107]
	v_mfma_f32_16x16x32_bf16 v[96:99], v[170:173], v[198:201], v[96:99]
	v_mfma_f32_16x16x32_bf16 v[88:91], v[178:181], v[198:201], v[88:91]
	v_mfma_f32_16x16x32_bf16 v[80:83], v[170:173], v[206:209], v[80:83]
	v_mfma_f32_16x16x32_bf16 v[72:75], v[178:181], v[206:209], v[72:75]
	v_mfma_f32_16x16x32_bf16 v[68:71], v[170:173], v[214:217], v[68:71]
	v_mfma_f32_16x16x32_bf16 v[64:67], v[178:181], v[214:217], v[64:67]
	s_setprio 0
	s_barrier
; #define PG8_STAGE(bufoff, gbase, voff) do { _Pragma("unroll") for (int _i = 0; _i < 2; ++_i) \
;         __builtin_amdgcn_global_load_lds((const unsigned*)((const char*)(gbase) + (voff)[_i]), (PG8_LAS unsigned*)(lds + (bufoff) + ldsw + _i * 8192), 16, 0, 0); } while (0)
; #define PG8_LDA(dst, b, h) do { _Pragma("unroll") for (int m = 0; m < 4; ++m) _Pragma("unroll") for (int k = 0; k < 2; ++k) dst[m][k] = *(const PG8_LAS bf16x8*)(lds + PG8_SA(b, h) + aoff + m * 2048 + k * 1024); } while (0)
; #define PG8_MMA(ai, bj, At, Bt) do { __builtin_amdgcn_s_setprio(1); _Pragma("unroll") for (int m = 0; m < 4; ++m) _Pragma("unroll") for (int n = 0; n < 2; ++n) _Pragma("unroll") for (int k = 0; k < 2; ++k) \
;         acc[ai][bj][m][n] = __builtin_amdgcn_mfma_f32_16x16x32_bf16(Bt[n][k], At[m][k], acc[ai][bj][m][n], 0, 0, 0); __builtin_amdgcn_s_setprio(0); } while (0)
; #define PG8_WAIT_V(n) asm volatile("s_waitcnt vmcnt(" #n ")" ::: "memory")
; #define PG8_WAIT_L(n) asm volatile("s_waitcnt lgkmcnt(" #n ")" ::: "memory")
; #define PG8_BAR __builtin_amdgcn_s_barrier()
; #define PG8_SCHED __builtin_amdgcn_sched_barrier(0)
; template <class Epi, class Sched, bool ALIGN_EPI = false, bool SP2 = false>
; __device__ __forceinline__ void gemm_phase(PG8_LAS unsigned char* lds, const Gemm g, const Sched& S, const Epi& E) {
;     ...
;         for (int t = 0; t < nt; t += 2) {
;             const bool last = (t == nt - 2);
;             const char* a1 = cA + (size_t)(t + 1) * kstep;
;             const char* a2 = last ? nA : cA + (size_t)(t + 2) * kstep; const char* b2 = last ? nB : cB + (size_t)(t + 2) * kstep;
;     ...
;             PG8_LDA(At, 1, 1); PG8_STAGE(PG8_SB(1, 0), b3, voffB); PG8_STAGE(PG8_SB(1, 1), b3 + hstep, voffB); PG8_STAGE(PG8_SA(1, 0), a3, voffA);
;             PG8_WAIT_V(8); PG8_WAIT_L(0); PG8_BAR; PG8_MMA(1, 0, At, B0); PG8_MMA(1, 1, At, B1); PG8_BAR; PG8_SCHED;
	s_add_i32 s24, s51, s30
	v_lshl_add_u64 v[182:183], v[182:183], 0, s[6:7]
	s_mov_b32 m0, s24
	ds_read_b128 v[186:189], v153 offset:49152
	ds_read_b128 v[190:193], v153 offset:50176
	ds_read_b128 v[194:197], v153 offset:51200
	ds_read_b128 v[198:201], v153 offset:52224
	ds_read_b128 v[202:205], v153 offset:53248
	ds_read_b128 v[206:209], v153 offset:54272
	ds_read_b128 v[210:213], v153 offset:55296
	ds_read_b128 v[214:217], v153 offset:56320
	global_load_lds_dwordx4 v[182:183], off
	s_add_i32 m0, s24, 0x2000
	s_add_u32 s22, s22, 0x40080
	v_lshl_add_u64 v[182:183], v[218:219], 0, s[6:7]
	s_addc_u32 s23, s23, 0
	s_add_i32 s24, s52, s30
	global_load_lds_dwordx4 v[182:183], off
	v_lshl_add_u64 v[182:183], s[22:23], 0, v[132:133]
	s_mov_b32 m0, s24
	s_nop 0
	global_load_lds_dwordx4 v[182:183], off
	v_lshl_add_u64 v[182:183], s[22:23], 0, v[128:129]
	s_add_i32 m0, s24, 0x2000
	s_nop 0
	global_load_lds_dwordx4 v[182:183], off
	v_lshl_add_u64 v[182:183], v[220:221], 0, s[6:7]
	s_mov_b32 m0, s37
	s_nop 0
	global_load_lds_dwordx4 v[182:183], off
	v_lshl_add_u64 v[182:183], v[222:223], 0, s[6:7]
	s_mov_b32 m0, s38
	s_nop 0
	global_load_lds_dwordx4 v[182:183], off
	s_waitcnt vmcnt(6)
	s_waitcnt lgkmcnt(0)
	s_barrier
	s_setprio 1
	s_waitcnt lgkmcnt(0)
	v_mfma_f32_16x16x32_bf16 v[60:63], v[144:147], v[186:189], v[60:63]
	v_mfma_f32_16x16x32_bf16 v[56:59], v[158:161], v[186:189], v[56:59]
	v_mfma_f32_16x16x32_bf16 v[52:55], v[144:147], v[194:197], v[52:55]
	v_mfma_f32_16x16x32_bf16 v[44:47], v[158:161], v[194:197], v[44:47]
	v_mfma_f32_16x16x32_bf16 v[36:39], v[144:147], v[202:205], v[36:39]
	v_mfma_f32_16x16x32_bf16 v[28:31], v[158:161], v[202:205], v[28:31]
	v_mfma_f32_16x16x32_bf16 v[20:23], v[144:147], v[210:213], v[20:23]
	v_mfma_f32_16x16x32_bf16 v[12:15], v[158:161], v[210:213], v[12:15]
	v_mfma_f32_16x16x32_bf16 v[60:63], v[154:157], v[190:193], v[60:63]
	v_mfma_f32_16x16x32_bf16 v[56:59], v[162:165], v[190:193], v[56:59]
	v_mfma_f32_16x16x32_bf16 v[52:55], v[154:157], v[198:201], v[52:55]
	v_mfma_f32_16x16x32_bf16 v[44:47], v[162:165], v[198:201], v[44:47]
	v_mfma_f32_16x16x32_bf16 v[36:39], v[154:157], v[206:209], v[36:39]
	v_mfma_f32_16x16x32_bf16 v[28:31], v[162:165], v[206:209], v[28:31]
	v_mfma_f32_16x16x32_bf16 v[20:23], v[154:157], v[214:217], v[20:23]
	v_mfma_f32_16x16x32_bf16 v[12:15], v[162:165], v[214:217], v[12:15]
	s_setprio 0
	s_setprio 1
	v_mfma_f32_16x16x32_bf16 v[48:51], v[166:169], v[186:189], v[48:51]
	v_mfma_f32_16x16x32_bf16 v[40:43], v[174:177], v[186:189], v[40:43]
	v_mfma_f32_16x16x32_bf16 v[32:35], v[166:169], v[194:197], v[32:35]
	v_mfma_f32_16x16x32_bf16 v[24:27], v[174:177], v[194:197], v[24:27]
	v_mfma_f32_16x16x32_bf16 v[16:19], v[166:169], v[202:205], v[16:19]
	v_mfma_f32_16x16x32_bf16 v[8:11], v[174:177], v[202:205], v[8:11]
	v_mfma_f32_16x16x32_bf16 v[4:7], v[166:169], v[210:213], v[4:7]
	v_mfma_f32_16x16x32_bf16 v[0:3], v[174:177], v[210:213], v[0:3]
	v_mfma_f32_16x16x32_bf16 v[48:51], v[170:173], v[190:193], v[48:51]
	v_mfma_f32_16x16x32_bf16 v[40:43], v[178:181], v[190:193], v[40:43]
	v_mfma_f32_16x16x32_bf16 v[32:35], v[170:173], v[198:201], v[32:35]
	v_mfma_f32_16x16x32_bf16 v[24:27], v[178:181], v[198:201], v[24:27]
	v_mfma_f32_16x16x32_bf16 v[16:19], v[170:173], v[206:209], v[16:19]
	v_mfma_f32_16x16x32_bf16 v[8:11], v[178:181], v[206:209], v[8:11]
	v_mfma_f32_16x16x32_bf16 v[4:7], v[170:173], v[214:217], v[4:7]
	v_mfma_f32_16x16x32_bf16 v[0:3], v[178:181], v[214:217], v[0:3]
	s_setprio 0
	s_barrier
	s_add_i32 s50, s50, 2
	s_add_u32 s48, s48, 0x100
	s_addc_u32 s49, s49, 0
	s_add_u32 s20, s20, 0x100
	s_addc_u32 s21, s21, 0
	s_cmp_gt_u32 s50, 13
	s_cbranch_scc0 .LBB0_343
	s_and_b64 vcc, exec, s[8:9]
	s_cbranch_vccz .LBB0_346
	s_barrier

; #define PG8_STAGE(bufoff, gbase, voff) do { _Pragma("unroll") for (int _i = 0; _i < 2; ++_i) \
;         __builtin_amdgcn_global_load_lds((const unsigned*)((const char*)(gbase) + (voff)[_i]), (PG8_LAS unsigned*)(lds + (bufoff) + ldsw + _i * 8192), 16, 0, 0); } while (0)
; #define PG8_LDA(dst, b, h) do { _Pragma("unroll") for (int m = 0; m < 4; ++m) _Pragma("unroll") for (int k = 0; k < 2; ++k) dst[m][k] = *(const PG8_LAS bf16x8*)(lds + PG8_SA(b, h) + aoff + m * 2048 + k * 1024); } while (0)
; #define PG8_LDB(dst, b, h) do { _Pragma("unroll") for (int n = 0; n < 2; ++n) _Pragma("unroll") for (int k = 0; k < 2; ++k) dst[n][k] = *(const PG8_LAS bf16x8*)(lds + PG8_SB(b, h) + boff + n * 2048 + k * 1024); } while (0)
; #define PG8_MMA(ai, bj, At, Bt) do { __builtin_amdgcn_s_setprio(1); _Pragma("unroll") for (int m = 0; m < 4; ++m) _Pragma("unroll") for (int n = 0; n < 2; ++n) _Pragma("unroll") for (int k = 0; k < 2; ++k) \
;         acc[ai][bj][m][n] = __builtin_amdgcn_mfma_f32_16x16x32_bf16(Bt[n][k], At[m][k], acc[ai][bj][m][n], 0, 0, 0); __builtin_amdgcn_s_setprio(0); } while (0)
; #define PG8_WAIT_V(n) asm volatile("s_waitcnt vmcnt(" #n ")" ::: "memory")
; #define PG8_WAIT_L(n) asm volatile("s_waitcnt lgkmcnt(" #n ")" ::: "memory")
; #define PG8_BAR __builtin_amdgcn_s_barrier()
; #define PG8_SCHED __builtin_amdgcn_sched_barrier(0)
; template <class Epi, class Sched, bool ALIGN_EPI = false, bool SP2 = false>
; __device__ __forceinline__ void gemm_phase(PG8_LAS unsigned char* lds, const Gemm g, const Sched& S, const Epi& E) {
;     ...
;         for (int t = 0; t < nt; t += 2) {
;             const bool last = (t == nt - 2);
;             const char* a1 = cA + (size_t)(t + 1) * kstep;
;             const char* a2 = last ? nA : cA + (size_t)(t + 2) * kstep; const char* b2 = last ? nB : cB + (size_t)(t + 2) * kstep;
;             const char* a3 = a2 + kstep; const char* b3 = b2 + kstep;
;             if (last && has_next) S.a_ready(nxt);
;             if constexpr (SP2) {
;             PG8_LDB(B0, 0, 0); PG8_LDB(B1, 0, 1); PG8_SCHED; PG8_LDA(At, 0, 0); PG8_STAGE(PG8_SA(1, 1), a1 + hstep, voffA);
;             PG8_WAIT_V(8); PG8_WAIT_L(0); PG8_BAR; PG8_MMA(0, 0, At, B0); PG8_MMA(0, 1, At, B1); PG8_BAR; PG8_SCHED;
;             PG8_LDA(At, 0, 1); PG8_STAGE(PG8_SB(0, 0), b2, voffB); PG8_STAGE(PG8_SB(0, 1), b2 + hstep, voffB); PG8_STAGE(PG8_SA(0, 0), a2, voffA);
.LBB0_424:
	ds_read_b128 v[140:143], v147
	ds_read_b128 v[150:153], v147 offset:1024
	ds_read_b128 v[154:157], v147 offset:2048
	ds_read_b128 v[158:161], v147 offset:3072
	ds_read_b128 v[162:165], v148
	ds_read_b128 v[166:169], v148 offset:1024
	ds_read_b128 v[170:173], v148 offset:2048
	ds_read_b128 v[174:177], v148 offset:3072
	s_add_u32 s22, s20, 0xfffc0080
	s_addc_u32 s23, s21, -1
	s_cmp_eq_u32 s48, 12
	s_cselect_b32 s25, s15, s23
	s_cselect_b32 s24, s44, s22
	s_cselect_b32 s23, s11, s47
	s_cselect_b32 s22, s45, s46
	v_lshl_add_u64 v[182:183], s[20:21], 0, v[138:139]
	s_add_i32 m0, s29, 0xc000
	ds_read_b128 v[178:181], v149
	ds_read_b128 v[186:189], v149 offset:1024
	ds_read_b128 v[190:193], v149 offset:2048
	ds_read_b128 v[194:197], v149 offset:3072
	ds_read_b128 v[198:201], v149 offset:4096
	ds_read_b128 v[202:205], v149 offset:5120
	ds_read_b128 v[206:209], v149 offset:6144
	ds_read_b128 v[210:213], v149 offset:7168
	global_load_lds_dwordx4 v[182:183], off
	v_lshl_add_u64 v[182:183], s[20:21], 0, v[136:137]
	s_add_i32 m0, s29, 0xe000
	s_nop 0
	global_load_lds_dwordx4 v[182:183], off
	s_waitcnt vmcnt(6)
	s_waitcnt lgkmcnt(0)
	s_barrier
	s_setprio 1
	s_waitcnt lgkmcnt(0)
	v_mfma_f32_16x16x32_bf16 v[124:127], v[140:143], v[178:181], v[124:127]
	v_mfma_f32_16x16x32_bf16 v[120:123], v[154:157], v[178:181], v[120:123]
	v_mfma_f32_16x16x32_bf16 v[116:119], v[140:143], v[190:193], v[116:119]
	v_mfma_f32_16x16x32_bf16 v[108:111], v[154:157], v[190:193], v[108:111]
	v_mfma_f32_16x16x32_bf16 v[100:103], v[140:143], v[198:201], v[100:103]
	v_mfma_f32_16x16x32_bf16 v[92:95], v[154:157], v[198:201], v[92:95]
	v_mfma_f32_16x16x32_bf16 v[84:87], v[140:143], v[206:209], v[84:87]
	v_mfma_f32_16x16x32_bf16 v[76:79], v[154:157], v[206:209], v[76:79]
	v_mfma_f32_16x16x32_bf16 v[124:127], v[150:153], v[186:189], v[124:127]
	v_mfma_f32_16x16x32_bf16 v[120:123], v[158:161], v[186:189], v[120:123]
	v_mfma_f32_16x16x32_bf16 v[116:119], v[150:153], v[194:197], v[116:119]
	v_mfma_f32_16x16x32_bf16 v[108:111], v[158:161], v[194:197], v[108:111]
	v_mfma_f32_16x16x32_bf16 v[100:103], v[150:153], v[202:205], v[100:103]
	v_mfma_f32_16x16x32_bf16 v[92:95], v[158:161], v[202:205], v[92:95]
	v_mfma_f32_16x16x32_bf16 v[84:87], v[150:153], v[210:213], v[84:87]
	v_mfma_f32_16x16x32_bf16 v[76:79], v[158:161], v[210:213], v[76:79]
	s_setprio 0
	s_setprio 1
	v_mfma_f32_16x16x32_bf16 v[112:115], v[162:165], v[178:181], v[112:115]
	v_mfma_f32_16x16x32_bf16 v[104:107], v[170:173], v[178:181], v[104:107]
	v_mfma_f32_16x16x32_bf16 v[96:99], v[162:165], v[190:193], v[96:99]
	v_mfma_f32_16x16x32_bf16 v[88:91], v[170:173], v[190:193], v[88:91]
	v_mfma_f32_16x16x32_bf16 v[80:83], v[162:165], v[198:201], v[80:83]
	v_mfma_f32_16x16x32_bf16 v[72:75], v[170:173], v[198:201], v[72:75]
	v_mfma_f32_16x16x32_bf16 v[68:71], v[162:165], v[206:209], v[68:71]
	v_mfma_f32_16x16x32_bf16 v[64:67], v[170:173], v[206:209], v[64:67]
	v_mfma_f32_16x16x32_bf16 v[112:115], v[166:169], v[186:189], v[112:115]
	v_mfma_f32_16x16x32_bf16 v[104:107], v[174:177], v[186:189], v[104:107]
	v_mfma_f32_16x16x32_bf16 v[96:99], v[166:169], v[194:197], v[96:99]
	v_mfma_f32_16x16x32_bf16 v[88:91], v[174:177], v[194:197], v[88:91]
	v_mfma_f32_16x16x32_bf16 v[80:83], v[166:169], v[202:205], v[80:83]
	v_mfma_f32_16x16x32_bf16 v[72:75], v[174:177], v[202:205], v[72:75]
	v_mfma_f32_16x16x32_bf16 v[68:71], v[166:169], v[210:213], v[68:71]
	v_mfma_f32_16x16x32_bf16 v[64:67], v[174:177], v[210:213], v[64:67]
	s_setprio 0
	s_barrier
	s_add_i32 s49, s38, s28
	v_lshl_add_u64 v[182:183], s[22:23], 0, v[130:131]
	s_mov_b32 m0, s49
	ds_read_b128 v[178:181], v149 offset:16384
	ds_read_b128 v[186:189], v149 offset:17408
	ds_read_b128 v[190:193], v149 offset:18432
	ds_read_b128 v[194:197], v149 offset:19456
	ds_read_b128 v[198:201], v149 offset:20480
	ds_read_b128 v[202:205], v149 offset:21504
	ds_read_b128 v[206:209], v149 offset:22528
	ds_read_b128 v[210:213], v149 offset:23552
	global_load_lds_dwordx4 v[182:183], off
	s_add_i32 m0, s49, 0x2000
	s_add_u32 s50, s22, 0x40000
	v_lshl_add_u64 v[214:215], s[22:23], 0, v[134:135]
	s_addc_u32 s51, s23, 0
	s_add_i32 s49, s39, s28
	global_load_lds_dwordx4 v[214:215], off
	v_lshl_add_u64 v[216:217], s[50:51], 0, v[130:131]
	s_mov_b32 m0, s49
	v_lshl_add_u64 v[218:219], s[24:25], 0, v[132:133]
	global_load_lds_dwordx4 v[216:217], off
	v_lshl_add_u64 v[216:217], s[50:51], 0, v[134:135]
	s_add_i32 m0, s49, 0x2000
	s_nop 0
	global_load_lds_dwordx4 v[216:217], off
	v_lshl_add_u64 v[216:217], s[24:25], 0, v[128:129]
	s_mov_b32 m0, s29
	s_nop 0
	global_load_lds_dwordx4 v[216:217], off
	s_mov_b32 m0, s30
	s_nop 0
	global_load_lds_dwordx4 v[218:219], off
	s_waitcnt vmcnt(6)
	s_waitcnt lgkmcnt(0)
	s_barrier
; #define PG8_STAGE(bufoff, gbase, voff) do { _Pragma("unroll") for (int _i = 0; _i < 2; ++_i) \
;         __builtin_amdgcn_global_load_lds((const unsigned*)((const char*)(gbase) + (voff)[_i]), (PG8_LAS unsigned*)(lds + (bufoff) + ldsw + _i * 8192), 16, 0, 0); } while (0)
; #define PG8_LDA(dst, b, h) do { _Pragma("unroll") for (int m = 0; m < 4; ++m) _Pragma("unroll") for (int k = 0; k < 2; ++k) dst[m][k] = *(const PG8_LAS bf16x8*)(lds + PG8_SA(b, h) + aoff + m * 2048 + k * 1024); } while (0)
; #define PG8_LDB(dst, b, h) do { _Pragma("unroll") for (int n = 0; n < 2; ++n) _Pragma("unroll") for (int k = 0; k < 2; ++k) dst[n][k] = *(const PG8_LAS bf16x8*)(lds + PG8_SB(b, h) + boff + n * 2048 + k * 1024); } while (0)
; #define PG8_MMA(ai, bj, At, Bt) do { __builtin_amdgcn_s_setprio(1); _Pragma("unroll") for (int m = 0; m < 4; ++m) _Pragma("unroll") for (int n = 0; n < 2; ++n) _Pragma("unroll") for (int k = 0; k < 2; ++k) \
;         acc[ai][bj][m][n] = __builtin_amdgcn_mfma_f32_16x16x32_bf16(Bt[n][k], At[m][k], acc[ai][bj][m][n], 0, 0, 0); __builtin_amdgcn_s_setprio(0); } while (0)
; #define PG8_WAIT_V(n) asm volatile("s_waitcnt vmcnt(" #n ")" ::: "memory")
; #define PG8_WAIT_L(n) asm volatile("s_waitcnt lgkmcnt(" #n ")" ::: "memory")
; #define PG8_BAR __builtin_amdgcn_s_barrier()
; #define PG8_SCHED __builtin_amdgcn_sched_barrier(0)
; template <class Epi, class Sched, bool ALIGN_EPI = false, bool SP2 = false>
; __device__ __forceinline__ void gemm_phase(PG8_LAS unsigned char* lds, const Gemm g, const Sched& S, const Epi& E) {
;     ...
;             PG8_WAIT_V(8); PG8_WAIT_L(0); PG8_BAR; PG8_MMA(1, 0, At, B0); PG8_MMA(1, 1, At, B1); PG8_BAR; PG8_SCHED;
;             PG8_LDB(B0, 1, 0); PG8_LDB(B1, 1, 1); PG8_SCHED; PG8_LDA(At, 1, 0); PG8_STAGE(PG8_SA(0, 1), a2 + hstep, voffA);
;             PG8_WAIT_V(8); PG8_WAIT_L(0); PG8_BAR; PG8_MMA(0, 0, At, B0); PG8_MMA(0, 1, At, B1); PG8_BAR; PG8_SCHED;
	s_setprio 1
	s_waitcnt lgkmcnt(0)
	v_mfma_f32_16x16x32_bf16 v[60:63], v[140:143], v[178:181], v[60:63]
	v_mfma_f32_16x16x32_bf16 v[56:59], v[154:157], v[178:181], v[56:59]
	v_mfma_f32_16x16x32_bf16 v[52:55], v[140:143], v[190:193], v[52:55]
	v_mfma_f32_16x16x32_bf16 v[44:47], v[154:157], v[190:193], v[44:47]
	v_mfma_f32_16x16x32_bf16 v[36:39], v[140:143], v[198:201], v[36:39]
	v_mfma_f32_16x16x32_bf16 v[28:31], v[154:157], v[198:201], v[28:31]
	v_mfma_f32_16x16x32_bf16 v[20:23], v[140:143], v[206:209], v[20:23]
	v_mfma_f32_16x16x32_bf16 v[12:15], v[154:157], v[206:209], v[12:15]
	v_mfma_f32_16x16x32_bf16 v[60:63], v[150:153], v[186:189], v[60:63]
	v_mfma_f32_16x16x32_bf16 v[56:59], v[158:161], v[186:189], v[56:59]
	v_mfma_f32_16x16x32_bf16 v[52:55], v[150:153], v[194:197], v[52:55]
	v_mfma_f32_16x16x32_bf16 v[44:47], v[158:161], v[194:197], v[44:47]
	v_mfma_f32_16x16x32_bf16 v[36:39], v[150:153], v[202:205], v[36:39]
	v_mfma_f32_16x16x32_bf16 v[28:31], v[158:161], v[202:205], v[28:31]
	v_mfma_f32_16x16x32_bf16 v[20:23], v[150:153], v[210:213], v[20:23]
	v_mfma_f32_16x16x32_bf16 v[12:15], v[158:161], v[210:213], v[12:15]
	s_setprio 0
	s_setprio 1
	v_mfma_f32_16x16x32_bf16 v[48:51], v[162:165], v[178:181], v[48:51]
	v_mfma_f32_16x16x32_bf16 v[40:43], v[170:173], v[178:181], v[40:43]
	v_mfma_f32_16x16x32_bf16 v[32:35], v[162:165], v[190:193], v[32:35]
	v_mfma_f32_16x16x32_bf16 v[24:27], v[170:173], v[190:193], v[24:27]
	v_mfma_f32_16x16x32_bf16 v[16:19], v[162:165], v[198:201], v[16:19]
	v_mfma_f32_16x16x32_bf16 v[8:11], v[170:173], v[198:201], v[8:11]
	v_mfma_f32_16x16x32_bf16 v[4:7], v[162:165], v[206:209], v[4:7]
	v_mfma_f32_16x16x32_bf16 v[0:3], v[170:173], v[206:209], v[0:3]
	v_mfma_f32_16x16x32_bf16 v[48:51], v[166:169], v[186:189], v[48:51]
	v_mfma_f32_16x16x32_bf16 v[40:43], v[174:177], v[186:189], v[40:43]
	v_mfma_f32_16x16x32_bf16 v[32:35], v[166:169], v[194:197], v[32:35]
	v_mfma_f32_16x16x32_bf16 v[24:27], v[174:177], v[194:197], v[24:27]
	v_mfma_f32_16x16x32_bf16 v[16:19], v[166:169], v[202:205], v[16:19]
	v_mfma_f32_16x16x32_bf16 v[8:11], v[174:177], v[202:205], v[8:11]
	v_mfma_f32_16x16x32_bf16 v[4:7], v[166:169], v[210:213], v[4:7]
	v_mfma_f32_16x16x32_bf16 v[0:3], v[174:177], v[210:213], v[0:3]
	s_setprio 0
	s_barrier
	s_add_i32 s49, 0, 0x18000
	s_add_i32 s50, 0, 0x1c000
	v_add_u32_e32 v158, s49, v145
	v_add_u32_e32 v174, s50, v145
	ds_read_b128 v[140:143], v158
	ds_read_b128 v[150:153], v158 offset:1024
	ds_read_b128 v[154:157], v158 offset:2048
	ds_read_b128 v[158:161], v158 offset:3072
	ds_read_b128 v[162:165], v174
	ds_read_b128 v[166:169], v174 offset:1024
	ds_read_b128 v[170:173], v174 offset:2048
	ds_read_b128 v[174:177], v174 offset:3072
	s_add_u32 s24, s24, 0x40000
	s_addc_u32 s25, s25, 0
	s_mov_b32 m0, s31
	v_lshl_add_u64 v[220:221], s[24:25], 0, v[128:129]
	ds_read_b128 v[178:181], v149 offset:32768
	ds_read_b128 v[186:189], v149 offset:33792
	ds_read_b128 v[190:193], v149 offset:34816
	ds_read_b128 v[194:197], v149 offset:35840
	ds_read_b128 v[198:201], v149 offset:36864
	ds_read_b128 v[202:205], v149 offset:37888
	ds_read_b128 v[206:209], v149 offset:38912
	ds_read_b128 v[210:213], v149 offset:39936
	global_load_lds_dwordx4 v[220:221], off
	v_lshl_add_u64 v[220:221], s[24:25], 0, v[132:133]
	s_mov_b32 m0, s33
	s_nop 0
	global_load_lds_dwordx4 v[220:221], off
	s_waitcnt vmcnt(6)
	s_waitcnt lgkmcnt(0)
	s_barrier
	s_setprio 1
	s_waitcnt lgkmcnt(0)
	v_mfma_f32_16x16x32_bf16 v[124:127], v[140:143], v[178:181], v[124:127]
	v_mfma_f32_16x16x32_bf16 v[120:123], v[154:157], v[178:181], v[120:123]
	v_mfma_f32_16x16x32_bf16 v[116:119], v[140:143], v[190:193], v[116:119]
	v_mfma_f32_16x16x32_bf16 v[108:111], v[154:157], v[190:193], v[108:111]
	v_mfma_f32_16x16x32_bf16 v[100:103], v[140:143], v[198:201], v[100:103]
	v_mfma_f32_16x16x32_bf16 v[92:95], v[154:157], v[198:201], v[92:95]
	v_mfma_f32_16x16x32_bf16 v[84:87], v[140:143], v[206:209], v[84:87]
	v_mfma_f32_16x16x32_bf16 v[76:79], v[154:157], v[206:209], v[76:79]
	v_mfma_f32_16x16x32_bf16 v[124:127], v[150:153], v[186:189], v[124:127]
	v_mfma_f32_16x16x32_bf16 v[120:123], v[158:161], v[186:189], v[120:123]
	v_mfma_f32_16x16x32_bf16 v[116:119], v[150:153], v[194:197], v[116:119]
	v_mfma_f32_16x16x32_bf16 v[108:111], v[158:161], v[194:197], v[108:111]
	v_mfma_f32_16x16x32_bf16 v[100:103], v[150:153], v[202:205], v[100:103]
	v_mfma_f32_16x16x32_bf16 v[92:95], v[158:161], v[202:205], v[92:95]
	v_mfma_f32_16x16x32_bf16 v[84:87], v[150:153], v[210:213], v[84:87]
	v_mfma_f32_16x16x32_bf16 v[76:79], v[158:161], v[210:213], v[76:79]
	s_setprio 0
	s_setprio 1
	v_mfma_f32_16x16x32_bf16 v[112:115], v[162:165], v[178:181], v[112:115]
	v_mfma_f32_16x16x32_bf16 v[104:107], v[170:173], v[178:181], v[104:107]
	v_mfma_f32_16x16x32_bf16 v[96:99], v[162:165], v[190:193], v[96:99]
	v_mfma_f32_16x16x32_bf16 v[88:91], v[170:173], v[190:193], v[88:91]
	v_mfma_f32_16x16x32_bf16 v[80:83], v[162:165], v[198:201], v[80:83]
	v_mfma_f32_16x16x32_bf16 v[72:75], v[170:173], v[198:201], v[72:75]
	v_mfma_f32_16x16x32_bf16 v[68:71], v[162:165], v[206:209], v[68:71]
	v_mfma_f32_16x16x32_bf16 v[64:67], v[170:173], v[206:209], v[64:67]
	v_mfma_f32_16x16x32_bf16 v[112:115], v[166:169], v[186:189], v[112:115]
	v_mfma_f32_16x16x32_bf16 v[104:107], v[174:177], v[186:189], v[104:107]
	v_mfma_f32_16x16x32_bf16 v[96:99], v[166:169], v[194:197], v[96:99]
	v_mfma_f32_16x16x32_bf16 v[88:91], v[174:177], v[194:197], v[88:91]
	v_mfma_f32_16x16x32_bf16 v[80:83], v[166:169], v[202:205], v[80:83]
	v_mfma_f32_16x16x32_bf16 v[72:75], v[174:177], v[202:205], v[72:75]
	v_mfma_f32_16x16x32_bf16 v[68:71], v[166:169], v[210:213], v[68:71]
	v_mfma_f32_16x16x32_bf16 v[64:67], v[174:177], v[210:213], v[64:67]
	s_setprio 0
	s_barrier
; #define PG8_STAGE(bufoff, gbase, voff) do { _Pragma("unroll") for (int _i = 0; _i < 2; ++_i) \
;         __builtin_amdgcn_global_load_lds((const unsigned*)((const char*)(gbase) + (voff)[_i]), (PG8_LAS unsigned*)(lds + (bufoff) + ldsw + _i * 8192), 16, 0, 0); } while (0)
; #define PG8_LDA(dst, b, h) do { _Pragma("unroll") for (int m = 0; m < 4; ++m) _Pragma("unroll") for (int k = 0; k < 2; ++k) dst[m][k] = *(const PG8_LAS bf16x8*)(lds + PG8_SA(b, h) + aoff + m * 2048 + k * 1024); } while (0)
; #define PG8_MMA(ai, bj, At, Bt) do { __builtin_amdgcn_s_setprio(1); _Pragma("unroll") for (int m = 0; m < 4; ++m) _Pragma("unroll") for (int n = 0; n < 2; ++n) _Pragma("unroll") for (int k = 0; k < 2; ++k) \
;         acc[ai][bj][m][n] = __builtin_amdgcn_mfma_f32_16x16x32_bf16(Bt[n][k], At[m][k], acc[ai][bj][m][n], 0, 0, 0); __builtin_amdgcn_s_setprio(0); } while (0)
; #define PG8_WAIT_V(n) asm volatile("s_waitcnt vmcnt(" #n ")" ::: "memory")
; #define PG8_WAIT_L(n) asm volatile("s_waitcnt lgkmcnt(" #n ")" ::: "memory")
; #define PG8_BAR __builtin_amdgcn_s_barrier()
; #define PG8_SCHED __builtin_amdgcn_sched_barrier(0)
; template <class Epi, class Sched, bool ALIGN_EPI = false, bool SP2 = false>
; __device__ __forceinline__ void gemm_phase(PG8_LAS unsigned char* lds, const Gemm g, const Sched& S, const Epi& E) {
;     ...
;         for (int t = 0; t < nt; t += 2) {
;             const bool last = (t == nt - 2);
;             const char* a1 = cA + (size_t)(t + 1) * kstep;
;             const char* a2 = last ? nA : cA + (size_t)(t + 2) * kstep; const char* b2 = last ? nB : cB + (size_t)(t + 2) * kstep;
;     ...
;             PG8_LDA(At, 1, 1); PG8_STAGE(PG8_SB(1, 0), b3, voffB); PG8_STAGE(PG8_SB(1, 1), b3 + hstep, voffB); PG8_STAGE(PG8_SA(1, 0), a3, voffA);
;             PG8_WAIT_V(8); PG8_WAIT_L(0); PG8_BAR; PG8_MMA(1, 0, At, B0); PG8_MMA(1, 1, At, B1); PG8_BAR; PG8_SCHED;
	s_add_i32 s24, s49, s28
	v_lshl_add_u64 v[182:183], v[182:183], 0, s[6:7]
	s_mov_b32 m0, s24
	ds_read_b128 v[178:181], v149 offset:49152
	ds_read_b128 v[186:189], v149 offset:50176
	ds_read_b128 v[190:193], v149 offset:51200
	ds_read_b128 v[194:197], v149 offset:52224
	ds_read_b128 v[198:201], v149 offset:53248
	ds_read_b128 v[202:205], v149 offset:54272
	ds_read_b128 v[206:209], v149 offset:55296
	ds_read_b128 v[210:213], v149 offset:56320
	global_load_lds_dwordx4 v[182:183], off
	s_add_i32 m0, s24, 0x2000
	s_add_u32 s22, s22, 0x40080
	v_lshl_add_u64 v[182:183], v[214:215], 0, s[6:7]
	s_addc_u32 s23, s23, 0
	s_add_i32 s24, s50, s28
	global_load_lds_dwordx4 v[182:183], off
	v_lshl_add_u64 v[182:183], s[22:23], 0, v[130:131]
	s_mov_b32 m0, s24
	s_nop 0
	global_load_lds_dwordx4 v[182:183], off
	v_lshl_add_u64 v[182:183], s[22:23], 0, v[134:135]
	s_add_i32 m0, s24, 0x2000
	s_nop 0
	global_load_lds_dwordx4 v[182:183], off
	v_lshl_add_u64 v[182:183], v[216:217], 0, s[6:7]
	s_mov_b32 m0, s34
	s_nop 0
	global_load_lds_dwordx4 v[182:183], off
	v_lshl_add_u64 v[182:183], v[218:219], 0, s[6:7]
	s_mov_b32 m0, s35
	s_nop 0
	global_load_lds_dwordx4 v[182:183], off
	s_waitcnt vmcnt(6)
	s_waitcnt lgkmcnt(0)
	s_barrier
	s_setprio 1
	s_waitcnt lgkmcnt(0)
	v_mfma_f32_16x16x32_bf16 v[60:63], v[140:143], v[178:181], v[60:63]
	v_mfma_f32_16x16x32_bf16 v[56:59], v[154:157], v[178:181], v[56:59]
	v_mfma_f32_16x16x32_bf16 v[52:55], v[140:143], v[190:193], v[52:55]
	v_mfma_f32_16x16x32_bf16 v[44:47], v[154:157], v[190:193], v[44:47]
	v_mfma_f32_16x16x32_bf16 v[36:39], v[140:143], v[198:201], v[36:39]
	v_mfma_f32_16x16x32_bf16 v[28:31], v[154:157], v[198:201], v[28:31]
	v_mfma_f32_16x16x32_bf16 v[20:23], v[140:143], v[206:209], v[20:23]
	v_mfma_f32_16x16x32_bf16 v[12:15], v[154:157], v[206:209], v[12:15]
	v_mfma_f32_16x16x32_bf16 v[60:63], v[150:153], v[186:189], v[60:63]
	v_mfma_f32_16x16x32_bf16 v[56:59], v[158:161], v[186:189], v[56:59]
	v_mfma_f32_16x16x32_bf16 v[52:55], v[150:153], v[194:197], v[52:55]
	v_mfma_f32_16x16x32_bf16 v[44:47], v[158:161], v[194:197], v[44:47]
	v_mfma_f32_16x16x32_bf16 v[36:39], v[150:153], v[202:205], v[36:39]
	v_mfma_f32_16x16x32_bf16 v[28:31], v[158:161], v[202:205], v[28:31]
	v_mfma_f32_16x16x32_bf16 v[20:23], v[150:153], v[210:213], v[20:23]
	v_mfma_f32_16x16x32_bf16 v[12:15], v[158:161], v[210:213], v[12:15]
	s_setprio 0
	s_setprio 1
	v_mfma_f32_16x16x32_bf16 v[48:51], v[162:165], v[178:181], v[48:51]
	v_mfma_f32_16x16x32_bf16 v[40:43], v[170:173], v[178:181], v[40:43]
	v_mfma_f32_16x16x32_bf16 v[32:35], v[162:165], v[190:193], v[32:35]
	v_mfma_f32_16x16x32_bf16 v[24:27], v[170:173], v[190:193], v[24:27]
	v_mfma_f32_16x16x32_bf16 v[16:19], v[162:165], v[198:201], v[16:19]
	v_mfma_f32_16x16x32_bf16 v[8:11], v[170:173], v[198:201], v[8:11]
	v_mfma_f32_16x16x32_bf16 v[4:7], v[162:165], v[206:209], v[4:7]
	v_mfma_f32_16x16x32_bf16 v[0:3], v[170:173], v[206:209], v[0:3]
	v_mfma_f32_16x16x32_bf16 v[48:51], v[166:169], v[186:189], v[48:51]
	v_mfma_f32_16x16x32_bf16 v[40:43], v[174:177], v[186:189], v[40:43]
	v_mfma_f32_16x16x32_bf16 v[32:35], v[166:169], v[194:197], v[32:35]
	v_mfma_f32_16x16x32_bf16 v[24:27], v[174:177], v[194:197], v[24:27]
	v_mfma_f32_16x16x32_bf16 v[16:19], v[166:169], v[202:205], v[16:19]
	v_mfma_f32_16x16x32_bf16 v[8:11], v[174:177], v[202:205], v[8:11]
	v_mfma_f32_16x16x32_bf16 v[4:7], v[166:169], v[210:213], v[4:7]
	v_mfma_f32_16x16x32_bf16 v[0:3], v[174:177], v[210:213], v[0:3]
	s_setprio 0
	s_barrier
	s_add_i32 s48, s48, 2
	s_add_u32 s46, s46, 0x100
	s_addc_u32 s47, s47, 0
	s_add_u32 s20, s20, 0x100
	s_addc_u32 s21, s21, 0
	s_cmp_gt_u32 s48, 13
	s_cbranch_scc0 .LBB0_424
	s_and_b64 vcc, exec, s[8:9]
	s_cbranch_vccz .LBB0_427
	s_barrier

; #define PG8_STAGE(bufoff, gbase, voff) do { _Pragma("unroll") for (int _i = 0; _i < 2; ++_i) \
;         __builtin_amdgcn_global_load_lds((const unsigned*)((const char*)(gbase) + (voff)[_i]), (PG8_LAS unsigned*)(lds + (bufoff) + ldsw + _i * 8192), 16, 0, 0); } while (0)
; #define PG8_LDA(dst, b, h) do { _Pragma("unroll") for (int m = 0; m < 4; ++m) _Pragma("unroll") for (int k = 0; k < 2; ++k) dst[m][k] = *(const PG8_LAS bf16x8*)(lds + PG8_SA(b, h) + aoff + m * 2048 + k * 1024); } while (0)
; #define PG8_LDB(dst, b, h) do { _Pragma("unroll") for (int n = 0; n < 2; ++n) _Pragma("unroll") for (int k = 0; k < 2; ++k) dst[n][k] = *(const PG8_LAS bf16x8*)(lds + PG8_SB(b, h) + boff + n * 2048 + k * 1024); } while (0)
; #define PG8_MMA(ai, bj, At, Bt) do { __builtin_amdgcn_s_setprio(1); _Pragma("unroll") for (int m = 0; m < 4; ++m) _Pragma("unroll") for (int n = 0; n < 2; ++n) _Pragma("unroll") for (int k = 0; k < 2; ++k) \
;         acc[ai][bj][m][n] = __builtin_amdgcn_mfma_f32_16x16x32_bf16(Bt[n][k], At[m][k], acc[ai][bj][m][n], 0, 0, 0); __builtin_amdgcn_s_setprio(0); } while (0)
; #define PG8_WAIT_V(n) asm volatile("s_waitcnt vmcnt(" #n ")" ::: "memory")
; #define PG8_WAIT_L(n) asm volatile("s_waitcnt lgkmcnt(" #n ")" ::: "memory")
; #define PG8_BAR __builtin_amdgcn_s_barrier()
; #define PG8_SCHED __builtin_amdgcn_sched_barrier(0)
; template <class Epi, class Sched, bool ALIGN_EPI = false, bool SP2 = false>
; __device__ __forceinline__ void gemm_phase(PG8_LAS unsigned char* lds, const Gemm g, const Sched& S, const Epi& E) {
;     ...
;         for (int t = 0; t < nt; t += 2) {
;             const bool last = (t == nt - 2);
;             const char* a1 = cA + (size_t)(t + 1) * kstep;
;             const char* a2 = last ? nA : cA + (size_t)(t + 2) * kstep; const char* b2 = last ? nB : cB + (size_t)(t + 2) * kstep;
;             const char* a3 = a2 + kstep; const char* b3 = b2 + kstep;
;             if (last && has_next) S.a_ready(nxt);
;             if constexpr (SP2) {
;             PG8_LDB(B0, 0, 0); PG8_LDB(B1, 0, 1); PG8_SCHED; PG8_LDA(At, 0, 0); PG8_STAGE(PG8_SA(1, 1), a1 + hstep, voffA);
;             PG8_WAIT_V(8); PG8_WAIT_L(0); PG8_BAR; PG8_MMA(0, 0, At, B0); PG8_MMA(0, 1, At, B1); PG8_BAR; PG8_SCHED;
;             PG8_LDA(At, 0, 1); PG8_STAGE(PG8_SB(0, 0), b2, voffB); PG8_STAGE(PG8_SB(0, 1), b2 + hstep, voffB); PG8_STAGE(PG8_SA(0, 0), a2, voffA);
.LBB0_515:
	ds_read_b128 v[144:147], v151
	ds_read_b128 v[154:157], v151 offset:1024
	ds_read_b128 v[158:161], v151 offset:2048
	ds_read_b128 v[162:165], v151 offset:3072
	ds_read_b128 v[166:169], v152
	ds_read_b128 v[170:173], v152 offset:1024
	ds_read_b128 v[174:177], v152 offset:2048
	ds_read_b128 v[178:181], v152 offset:3072
	s_add_u32 s16, s14, 0x100
	s_addc_u32 s17, s15, 0
	s_cmp_eq_u32 s48, 2
	s_cselect_b32 s21, s5, s17
	s_cselect_b32 s20, s4, s16
	s_cselect_b32 s19, s13, s47
	s_cselect_b32 s18, s12, s46
	v_lshl_add_u64 v[182:183], s[14:15], 0, v[138:139]
	s_add_i32 m0, s29, 0xc000
	ds_read_b128 v[186:189], v153
	ds_read_b128 v[190:193], v153 offset:1024
	ds_read_b128 v[194:197], v153 offset:2048
	ds_read_b128 v[198:201], v153 offset:3072
	ds_read_b128 v[202:205], v153 offset:4096
	ds_read_b128 v[206:209], v153 offset:5120
	ds_read_b128 v[210:213], v153 offset:6144
	ds_read_b128 v[214:217], v153 offset:7168
	global_load_lds_dwordx4 v[182:183], off
	v_lshl_add_u64 v[182:183], s[14:15], 0, v[136:137]
	s_add_i32 m0, s29, 0xe000
	s_nop 0
	global_load_lds_dwordx4 v[182:183], off
	s_waitcnt vmcnt(6)
	s_waitcnt lgkmcnt(0)
	s_barrier
	s_setprio 1
	s_waitcnt lgkmcnt(0)
	v_mfma_f32_16x16x32_bf16 v[124:127], v[144:147], v[186:189], v[124:127]
	v_mfma_f32_16x16x32_bf16 v[120:123], v[158:161], v[186:189], v[120:123]
	v_mfma_f32_16x16x32_bf16 v[116:119], v[144:147], v[194:197], v[116:119]
	v_mfma_f32_16x16x32_bf16 v[108:111], v[158:161], v[194:197], v[108:111]
	v_mfma_f32_16x16x32_bf16 v[100:103], v[144:147], v[202:205], v[100:103]
	v_mfma_f32_16x16x32_bf16 v[92:95], v[158:161], v[202:205], v[92:95]
	v_mfma_f32_16x16x32_bf16 v[84:87], v[144:147], v[210:213], v[84:87]
	v_mfma_f32_16x16x32_bf16 v[76:79], v[158:161], v[210:213], v[76:79]
	v_mfma_f32_16x16x32_bf16 v[124:127], v[154:157], v[190:193], v[124:127]
	v_mfma_f32_16x16x32_bf16 v[120:123], v[162:165], v[190:193], v[120:123]
	v_mfma_f32_16x16x32_bf16 v[116:119], v[154:157], v[198:201], v[116:119]
	v_mfma_f32_16x16x32_bf16 v[108:111], v[162:165], v[198:201], v[108:111]
	v_mfma_f32_16x16x32_bf16 v[100:103], v[154:157], v[206:209], v[100:103]
	v_mfma_f32_16x16x32_bf16 v[92:95], v[162:165], v[206:209], v[92:95]
	v_mfma_f32_16x16x32_bf16 v[84:87], v[154:157], v[214:217], v[84:87]
	v_mfma_f32_16x16x32_bf16 v[76:79], v[162:165], v[214:217], v[76:79]
	s_setprio 0
	s_setprio 1
	v_mfma_f32_16x16x32_bf16 v[112:115], v[166:169], v[186:189], v[112:115]
	v_mfma_f32_16x16x32_bf16 v[104:107], v[174:177], v[186:189], v[104:107]
	v_mfma_f32_16x16x32_bf16 v[96:99], v[166:169], v[194:197], v[96:99]
	v_mfma_f32_16x16x32_bf16 v[88:91], v[174:177], v[194:197], v[88:91]
	v_mfma_f32_16x16x32_bf16 v[80:83], v[166:169], v[202:205], v[80:83]
	v_mfma_f32_16x16x32_bf16 v[72:75], v[174:177], v[202:205], v[72:75]
	v_mfma_f32_16x16x32_bf16 v[68:71], v[166:169], v[210:213], v[68:71]
	v_mfma_f32_16x16x32_bf16 v[64:67], v[174:177], v[210:213], v[64:67]
	v_mfma_f32_16x16x32_bf16 v[112:115], v[170:173], v[190:193], v[112:115]
	v_mfma_f32_16x16x32_bf16 v[104:107], v[178:181], v[190:193], v[104:107]
	v_mfma_f32_16x16x32_bf16 v[96:99], v[170:173], v[198:201], v[96:99]
	v_mfma_f32_16x16x32_bf16 v[88:91], v[178:181], v[198:201], v[88:91]
	v_mfma_f32_16x16x32_bf16 v[80:83], v[170:173], v[206:209], v[80:83]
	v_mfma_f32_16x16x32_bf16 v[72:75], v[178:181], v[206:209], v[72:75]
	v_mfma_f32_16x16x32_bf16 v[68:71], v[170:173], v[214:217], v[68:71]
	v_mfma_f32_16x16x32_bf16 v[64:67], v[178:181], v[214:217], v[64:67]
	s_setprio 0
	s_barrier
	s_add_i32 s14, s39, s28
	v_lshl_add_u64 v[182:183], s[18:19], 0, v[130:131]
	s_mov_b32 m0, s14
	ds_read_b128 v[186:189], v153 offset:16384
	ds_read_b128 v[190:193], v153 offset:17408
	ds_read_b128 v[194:197], v153 offset:18432
	ds_read_b128 v[198:201], v153 offset:19456
	ds_read_b128 v[202:205], v153 offset:20480
	ds_read_b128 v[206:209], v153 offset:21504
	ds_read_b128 v[210:213], v153 offset:22528
	ds_read_b128 v[214:217], v153 offset:23552
	global_load_lds_dwordx4 v[182:183], off
	s_add_i32 m0, s14, 0x2000
	s_add_u32 s14, s18, 0x18000
	v_lshl_add_u64 v[218:219], s[18:19], 0, v[134:135]
	s_addc_u32 s15, s19, 0
	s_add_i32 s49, s40, s28
	global_load_lds_dwordx4 v[218:219], off
	v_lshl_add_u64 v[220:221], s[14:15], 0, v[130:131]
	s_mov_b32 m0, s49
	v_lshl_add_u64 v[222:223], s[20:21], 0, v[132:133]
	global_load_lds_dwordx4 v[220:221], off
	v_lshl_add_u64 v[220:221], s[14:15], 0, v[134:135]
	s_add_i32 m0, s49, 0x2000
	s_nop 0
	global_load_lds_dwordx4 v[220:221], off
	v_lshl_add_u64 v[220:221], s[20:21], 0, v[128:129]
	s_mov_b32 m0, s29
	s_nop 0
	global_load_lds_dwordx4 v[220:221], off
	s_mov_b32 m0, s30
	s_nop 0
	global_load_lds_dwordx4 v[222:223], off
	s_waitcnt vmcnt(6)
	s_waitcnt lgkmcnt(0)
	s_barrier
; #define PG8_STAGE(bufoff, gbase, voff) do { _Pragma("unroll") for (int _i = 0; _i < 2; ++_i) \
;         __builtin_amdgcn_global_load_lds((const unsigned*)((const char*)(gbase) + (voff)[_i]), (PG8_LAS unsigned*)(lds + (bufoff) + ldsw + _i * 8192), 16, 0, 0); } while (0)
; #define PG8_LDA(dst, b, h) do { _Pragma("unroll") for (int m = 0; m < 4; ++m) _Pragma("unroll") for (int k = 0; k < 2; ++k) dst[m][k] = *(const PG8_LAS bf16x8*)(lds + PG8_SA(b, h) + aoff + m * 2048 + k * 1024); } while (0)
; #define PG8_LDB(dst, b, h) do { _Pragma("unroll") for (int n = 0; n < 2; ++n) _Pragma("unroll") for (int k = 0; k < 2; ++k) dst[n][k] = *(const PG8_LAS bf16x8*)(lds + PG8_SB(b, h) + boff + n * 2048 + k * 1024); } while (0)
; #define PG8_MMA(ai, bj, At, Bt) do { __builtin_amdgcn_s_setprio(1); _Pragma("unroll") for (int m = 0; m < 4; ++m) _Pragma("unroll") for (int n = 0; n < 2; ++n) _Pragma("unroll") for (int k = 0; k < 2; ++k) \
;         acc[ai][bj][m][n] = __builtin_amdgcn_mfma_f32_16x16x32_bf16(Bt[n][k], At[m][k], acc[ai][bj][m][n], 0, 0, 0); __builtin_amdgcn_s_setprio(0); } while (0)
; #define PG8_WAIT_V(n) asm volatile("s_waitcnt vmcnt(" #n ")" ::: "memory")
; #define PG8_WAIT_L(n) asm volatile("s_waitcnt lgkmcnt(" #n ")" ::: "memory")
; #define PG8_BAR __builtin_amdgcn_s_barrier()
; #define PG8_SCHED __builtin_amdgcn_sched_barrier(0)
; template <class Epi, class Sched, bool ALIGN_EPI = false, bool SP2 = false>
; __device__ __forceinline__ void gemm_phase(PG8_LAS unsigned char* lds, const Gemm g, const Sched& S, const Epi& E) {
;     ...
;             PG8_WAIT_V(8); PG8_WAIT_L(0); PG8_BAR; PG8_MMA(1, 0, At, B0); PG8_MMA(1, 1, At, B1); PG8_BAR; PG8_SCHED;
;             PG8_LDB(B0, 1, 0); PG8_LDB(B1, 1, 1); PG8_SCHED; PG8_LDA(At, 1, 0); PG8_STAGE(PG8_SA(0, 1), a2 + hstep, voffA);
;             PG8_WAIT_V(8); PG8_WAIT_L(0); PG8_BAR; PG8_MMA(0, 0, At, B0); PG8_MMA(0, 1, At, B1); PG8_BAR; PG8_SCHED;
	s_setprio 1
	s_waitcnt lgkmcnt(0)
	v_mfma_f32_16x16x32_bf16 v[60:63], v[144:147], v[186:189], v[60:63]
	v_mfma_f32_16x16x32_bf16 v[56:59], v[158:161], v[186:189], v[56:59]
	v_mfma_f32_16x16x32_bf16 v[52:55], v[144:147], v[194:197], v[52:55]
	v_mfma_f32_16x16x32_bf16 v[44:47], v[158:161], v[194:197], v[44:47]
	v_mfma_f32_16x16x32_bf16 v[36:39], v[144:147], v[202:205], v[36:39]
	v_mfma_f32_16x16x32_bf16 v[28:31], v[158:161], v[202:205], v[28:31]
	v_mfma_f32_16x16x32_bf16 v[20:23], v[144:147], v[210:213], v[20:23]
	v_mfma_f32_16x16x32_bf16 v[12:15], v[158:161], v[210:213], v[12:15]
	v_mfma_f32_16x16x32_bf16 v[60:63], v[154:157], v[190:193], v[60:63]
	v_mfma_f32_16x16x32_bf16 v[56:59], v[162:165], v[190:193], v[56:59]
	v_mfma_f32_16x16x32_bf16 v[52:55], v[154:157], v[198:201], v[52:55]
	v_mfma_f32_16x16x32_bf16 v[44:47], v[162:165], v[198:201], v[44:47]
	v_mfma_f32_16x16x32_bf16 v[36:39], v[154:157], v[206:209], v[36:39]
	v_mfma_f32_16x16x32_bf16 v[28:31], v[162:165], v[206:209], v[28:31]
	v_mfma_f32_16x16x32_bf16 v[20:23], v[154:157], v[214:217], v[20:23]
	v_mfma_f32_16x16x32_bf16 v[12:15], v[162:165], v[214:217], v[12:15]
	s_setprio 0
	s_setprio 1
	v_mfma_f32_16x16x32_bf16 v[48:51], v[166:169], v[186:189], v[48:51]
	v_mfma_f32_16x16x32_bf16 v[40:43], v[174:177], v[186:189], v[40:43]
	v_mfma_f32_16x16x32_bf16 v[32:35], v[166:169], v[194:197], v[32:35]
	v_mfma_f32_16x16x32_bf16 v[24:27], v[174:177], v[194:197], v[24:27]
	v_mfma_f32_16x16x32_bf16 v[16:19], v[166:169], v[202:205], v[16:19]
	v_mfma_f32_16x16x32_bf16 v[8:11], v[174:177], v[202:205], v[8:11]
	v_mfma_f32_16x16x32_bf16 v[4:7], v[166:169], v[210:213], v[4:7]
	v_mfma_f32_16x16x32_bf16 v[0:3], v[174:177], v[210:213], v[0:3]
	v_mfma_f32_16x16x32_bf16 v[48:51], v[170:173], v[190:193], v[48:51]
	v_mfma_f32_16x16x32_bf16 v[40:43], v[178:181], v[190:193], v[40:43]
	v_mfma_f32_16x16x32_bf16 v[32:35], v[170:173], v[198:201], v[32:35]
	v_mfma_f32_16x16x32_bf16 v[24:27], v[178:181], v[198:201], v[24:27]
	v_mfma_f32_16x16x32_bf16 v[16:19], v[170:173], v[206:209], v[16:19]
	v_mfma_f32_16x16x32_bf16 v[8:11], v[178:181], v[206:209], v[8:11]
	v_mfma_f32_16x16x32_bf16 v[4:7], v[170:173], v[214:217], v[4:7]
	v_mfma_f32_16x16x32_bf16 v[0:3], v[178:181], v[214:217], v[0:3]
	s_setprio 0
	s_barrier
	s_add_i32 s49, 0, 0x18000
	s_add_i32 s50, 0, 0x1c000
	v_add_u32_e32 v162, s49, v149
	v_add_u32_e32 v178, s50, v149
	ds_read_b128 v[144:147], v162
	ds_read_b128 v[154:157], v162 offset:1024
	ds_read_b128 v[158:161], v162 offset:2048
	ds_read_b128 v[162:165], v162 offset:3072
	ds_read_b128 v[166:169], v178
	ds_read_b128 v[170:173], v178 offset:1024
	ds_read_b128 v[174:177], v178 offset:2048
	ds_read_b128 v[178:181], v178 offset:3072
	s_add_u32 s14, s20, 0x18000
	s_addc_u32 s15, s21, 0
	s_mov_b32 m0, s31
	v_lshl_add_u64 v[224:225], s[14:15], 0, v[128:129]
	ds_read_b128 v[186:189], v153 offset:32768
	ds_read_b128 v[190:193], v153 offset:33792
	ds_read_b128 v[194:197], v153 offset:34816
	ds_read_b128 v[198:201], v153 offset:35840
	ds_read_b128 v[202:205], v153 offset:36864
	ds_read_b128 v[206:209], v153 offset:37888
	ds_read_b128 v[210:213], v153 offset:38912
	ds_read_b128 v[214:217], v153 offset:39936
	global_load_lds_dwordx4 v[224:225], off
	v_lshl_add_u64 v[224:225], s[14:15], 0, v[132:133]
	s_mov_b32 m0, s33
	s_nop 0
	global_load_lds_dwordx4 v[224:225], off
	s_waitcnt vmcnt(6)
	s_waitcnt lgkmcnt(0)
	s_barrier
	s_setprio 1
	s_waitcnt lgkmcnt(0)
	v_mfma_f32_16x16x32_bf16 v[124:127], v[144:147], v[186:189], v[124:127]
	v_mfma_f32_16x16x32_bf16 v[120:123], v[158:161], v[186:189], v[120:123]
	v_mfma_f32_16x16x32_bf16 v[116:119], v[144:147], v[194:197], v[116:119]
	v_mfma_f32_16x16x32_bf16 v[108:111], v[158:161], v[194:197], v[108:111]
	v_mfma_f32_16x16x32_bf16 v[100:103], v[144:147], v[202:205], v[100:103]
	v_mfma_f32_16x16x32_bf16 v[92:95], v[158:161], v[202:205], v[92:95]
	v_mfma_f32_16x16x32_bf16 v[84:87], v[144:147], v[210:213], v[84:87]
	v_mfma_f32_16x16x32_bf16 v[76:79], v[158:161], v[210:213], v[76:79]
	v_mfma_f32_16x16x32_bf16 v[124:127], v[154:157], v[190:193], v[124:127]
	v_mfma_f32_16x16x32_bf16 v[120:123], v[162:165], v[190:193], v[120:123]
	v_mfma_f32_16x16x32_bf16 v[116:119], v[154:157], v[198:201], v[116:119]
	v_mfma_f32_16x16x32_bf16 v[108:111], v[162:165], v[198:201], v[108:111]
	v_mfma_f32_16x16x32_bf16 v[100:103], v[154:157], v[206:209], v[100:103]
	v_mfma_f32_16x16x32_bf16 v[92:95], v[162:165], v[206:209], v[92:95]
	v_mfma_f32_16x16x32_bf16 v[84:87], v[154:157], v[214:217], v[84:87]
	v_mfma_f32_16x16x32_bf16 v[76:79], v[162:165], v[214:217], v[76:79]
	s_setprio 0
	s_setprio 1
	v_mfma_f32_16x16x32_bf16 v[112:115], v[166:169], v[186:189], v[112:115]
	v_mfma_f32_16x16x32_bf16 v[104:107], v[174:177], v[186:189], v[104:107]
	v_mfma_f32_16x16x32_bf16 v[96:99], v[166:169], v[194:197], v[96:99]
	v_mfma_f32_16x16x32_bf16 v[88:91], v[174:177], v[194:197], v[88:91]
	v_mfma_f32_16x16x32_bf16 v[80:83], v[166:169], v[202:205], v[80:83]
	v_mfma_f32_16x16x32_bf16 v[72:75], v[174:177], v[202:205], v[72:75]
	v_mfma_f32_16x16x32_bf16 v[68:71], v[166:169], v[210:213], v[68:71]
	v_mfma_f32_16x16x32_bf16 v[64:67], v[174:177], v[210:213], v[64:67]
	v_mfma_f32_16x16x32_bf16 v[112:115], v[170:173], v[190:193], v[112:115]
	v_mfma_f32_16x16x32_bf16 v[104:107], v[178:181], v[190:193], v[104:107]
	v_mfma_f32_16x16x32_bf16 v[96:99], v[170:173], v[198:201], v[96:99]
	v_mfma_f32_16x16x32_bf16 v[88:91], v[178:181], v[198:201], v[88:91]
	v_mfma_f32_16x16x32_bf16 v[80:83], v[170:173], v[206:209], v[80:83]
	v_mfma_f32_16x16x32_bf16 v[72:75], v[178:181], v[206:209], v[72:75]
	v_mfma_f32_16x16x32_bf16 v[68:71], v[170:173], v[214:217], v[68:71]
	v_mfma_f32_16x16x32_bf16 v[64:67], v[178:181], v[214:217], v[64:67]
	s_setprio 0
	s_barrier
; #define PG8_STAGE(bufoff, gbase, voff) do { _Pragma("unroll") for (int _i = 0; _i < 2; ++_i) \
;         __builtin_amdgcn_global_load_lds((const unsigned*)((const char*)(gbase) + (voff)[_i]), (PG8_LAS unsigned*)(lds + (bufoff) + ldsw + _i * 8192), 16, 0, 0); } while (0)
; #define PG8_LDA(dst, b, h) do { _Pragma("unroll") for (int m = 0; m < 4; ++m) _Pragma("unroll") for (int k = 0; k < 2; ++k) dst[m][k] = *(const PG8_LAS bf16x8*)(lds + PG8_SA(b, h) + aoff + m * 2048 + k * 1024); } while (0)
; #define PG8_MMA(ai, bj, At, Bt) do { __builtin_amdgcn_s_setprio(1); _Pragma("unroll") for (int m = 0; m < 4; ++m) _Pragma("unroll") for (int n = 0; n < 2; ++n) _Pragma("unroll") for (int k = 0; k < 2; ++k) \
;         acc[ai][bj][m][n] = __builtin_amdgcn_mfma_f32_16x16x32_bf16(Bt[n][k], At[m][k], acc[ai][bj][m][n], 0, 0, 0); __builtin_amdgcn_s_setprio(0); } while (0)
; #define PG8_WAIT_V(n) asm volatile("s_waitcnt vmcnt(" #n ")" ::: "memory")
; #define PG8_WAIT_L(n) asm volatile("s_waitcnt lgkmcnt(" #n ")" ::: "memory")
; #define PG8_BAR __builtin_amdgcn_s_barrier()
; #define PG8_SCHED __builtin_amdgcn_sched_barrier(0)
; template <class Epi, class Sched, bool ALIGN_EPI = false, bool SP2 = false>
; __device__ __forceinline__ void gemm_phase(PG8_LAS unsigned char* lds, const Gemm g, const Sched& S, const Epi& E) {
;     ...
;         for (int t = 0; t < nt; t += 2) {
;             const bool last = (t == nt - 2);
;             const char* a1 = cA + (size_t)(t + 1) * kstep;
;             const char* a2 = last ? nA : cA + (size_t)(t + 2) * kstep; const char* b2 = last ? nB : cB + (size_t)(t + 2) * kstep;
;     ...
;             PG8_LDA(At, 1, 1); PG8_STAGE(PG8_SB(1, 0), b3, voffB); PG8_STAGE(PG8_SB(1, 1), b3 + hstep, voffB); PG8_STAGE(PG8_SA(1, 0), a3, voffA);
;             PG8_WAIT_V(8); PG8_WAIT_L(0); PG8_BAR; PG8_MMA(1, 0, At, B0); PG8_MMA(1, 1, At, B1); PG8_BAR; PG8_SCHED;
	s_add_i32 s14, s49, s28
	v_lshl_add_u64 v[182:183], v[182:183], 0, s[8:9]
	s_mov_b32 m0, s14
	ds_read_b128 v[186:189], v153 offset:49152
	ds_read_b128 v[190:193], v153 offset:50176
	ds_read_b128 v[194:197], v153 offset:51200
	ds_read_b128 v[198:201], v153 offset:52224
	ds_read_b128 v[202:205], v153 offset:53248
	ds_read_b128 v[206:209], v153 offset:54272
	ds_read_b128 v[210:213], v153 offset:55296
	ds_read_b128 v[214:217], v153 offset:56320
	global_load_lds_dwordx4 v[182:183], off
	s_add_i32 m0, s14, 0x2000
	s_add_u32 s14, s18, 0x18080
	v_lshl_add_u64 v[182:183], v[218:219], 0, s[8:9]
	s_addc_u32 s15, s19, 0
	s_add_i32 s18, s50, s28
	global_load_lds_dwordx4 v[182:183], off
	v_lshl_add_u64 v[182:183], s[14:15], 0, v[130:131]
	s_mov_b32 m0, s18
	s_nop 0
	global_load_lds_dwordx4 v[182:183], off
	v_lshl_add_u64 v[182:183], s[14:15], 0, v[134:135]
	s_add_i32 m0, s18, 0x2000
	s_nop 0
	global_load_lds_dwordx4 v[182:183], off
	v_lshl_add_u64 v[182:183], v[220:221], 0, s[8:9]
	s_mov_b32 m0, s35
	s_nop 0
	global_load_lds_dwordx4 v[182:183], off
	v_lshl_add_u64 v[182:183], v[222:223], 0, s[8:9]
	s_mov_b32 m0, s36
	s_nop 0
	global_load_lds_dwordx4 v[182:183], off
	s_waitcnt vmcnt(6)
	s_waitcnt lgkmcnt(0)
	s_barrier
	s_setprio 1
	s_waitcnt lgkmcnt(0)
	v_mfma_f32_16x16x32_bf16 v[60:63], v[144:147], v[186:189], v[60:63]
	v_mfma_f32_16x16x32_bf16 v[56:59], v[158:161], v[186:189], v[56:59]
	v_mfma_f32_16x16x32_bf16 v[52:55], v[144:147], v[194:197], v[52:55]
	v_mfma_f32_16x16x32_bf16 v[44:47], v[158:161], v[194:197], v[44:47]
	v_mfma_f32_16x16x32_bf16 v[36:39], v[144:147], v[202:205], v[36:39]
	v_mfma_f32_16x16x32_bf16 v[28:31], v[158:161], v[202:205], v[28:31]
	v_mfma_f32_16x16x32_bf16 v[20:23], v[144:147], v[210:213], v[20:23]
	v_mfma_f32_16x16x32_bf16 v[12:15], v[158:161], v[210:213], v[12:15]
	v_mfma_f32_16x16x32_bf16 v[60:63], v[154:157], v[190:193], v[60:63]
	v_mfma_f32_16x16x32_bf16 v[56:59], v[162:165], v[190:193], v[56:59]
	v_mfma_f32_16x16x32_bf16 v[52:55], v[154:157], v[198:201], v[52:55]
	v_mfma_f32_16x16x32_bf16 v[44:47], v[162:165], v[198:201], v[44:47]
	v_mfma_f32_16x16x32_bf16 v[36:39], v[154:157], v[206:209], v[36:39]
	v_mfma_f32_16x16x32_bf16 v[28:31], v[162:165], v[206:209], v[28:31]
	v_mfma_f32_16x16x32_bf16 v[20:23], v[154:157], v[214:217], v[20:23]
	v_mfma_f32_16x16x32_bf16 v[12:15], v[162:165], v[214:217], v[12:15]
	s_setprio 0
	s_setprio 1
	v_mfma_f32_16x16x32_bf16 v[48:51], v[166:169], v[186:189], v[48:51]
	v_mfma_f32_16x16x32_bf16 v[40:43], v[174:177], v[186:189], v[40:43]
	v_mfma_f32_16x16x32_bf16 v[32:35], v[166:169], v[194:197], v[32:35]
	v_mfma_f32_16x16x32_bf16 v[24:27], v[174:177], v[194:197], v[24:27]
	v_mfma_f32_16x16x32_bf16 v[16:19], v[166:169], v[202:205], v[16:19]
	v_mfma_f32_16x16x32_bf16 v[8:11], v[174:177], v[202:205], v[8:11]
	v_mfma_f32_16x16x32_bf16 v[4:7], v[166:169], v[210:213], v[4:7]
	v_mfma_f32_16x16x32_bf16 v[0:3], v[174:177], v[210:213], v[0:3]
	v_mfma_f32_16x16x32_bf16 v[48:51], v[170:173], v[190:193], v[48:51]
	v_mfma_f32_16x16x32_bf16 v[40:43], v[178:181], v[190:193], v[40:43]
	v_mfma_f32_16x16x32_bf16 v[32:35], v[170:173], v[198:201], v[32:35]
	v_mfma_f32_16x16x32_bf16 v[24:27], v[178:181], v[198:201], v[24:27]
	v_mfma_f32_16x16x32_bf16 v[16:19], v[170:173], v[206:209], v[16:19]
	v_mfma_f32_16x16x32_bf16 v[8:11], v[178:181], v[206:209], v[8:11]
	v_mfma_f32_16x16x32_bf16 v[4:7], v[170:173], v[214:217], v[4:7]
	v_mfma_f32_16x16x32_bf16 v[0:3], v[178:181], v[214:217], v[0:3]
	s_setprio 0
	s_barrier
	s_add_i32 s48, s48, 2
	s_add_u32 s46, s46, 0x100
	s_addc_u32 s47, s47, 0
	s_cmp_gt_u32 s48, 3
	s_mov_b64 s[14:15], s[16:17]
	s_cbranch_scc0 .LBB0_515
	s_and_b64 vcc, exec, s[10:11]
	s_cbranch_vccz .LBB0_518
	s_barrier

; #define PG8_STAGE(bufoff, gbase, voff) do { _Pragma("unroll") for (int _i = 0; _i < 2; ++_i) \
;         __builtin_amdgcn_global_load_lds((const unsigned*)((const char*)(gbase) + (voff)[_i]), (PG8_LAS unsigned*)(lds + (bufoff) + ldsw + _i * 8192), 16, 0, 0); } while (0)
; #define PG8_LDA(dst, b, h) do { _Pragma("unroll") for (int m = 0; m < 4; ++m) _Pragma("unroll") for (int k = 0; k < 2; ++k) dst[m][k] = *(const PG8_LAS bf16x8*)(lds + PG8_SA(b, h) + aoff + m * 2048 + k * 1024); } while (0)
; #define PG8_LDB(dst, b, h) do { _Pragma("unroll") for (int n = 0; n < 2; ++n) _Pragma("unroll") for (int k = 0; k < 2; ++k) dst[n][k] = *(const PG8_LAS bf16x8*)(lds + PG8_SB(b, h) + boff + n * 2048 + k * 1024); } while (0)
; #define PG8_MMA(ai, bj, At, Bt) do { __builtin_amdgcn_s_setprio(1); _Pragma("unroll") for (int m = 0; m < 4; ++m) _Pragma("unroll") for (int n = 0; n < 2; ++n) _Pragma("unroll") for (int k = 0; k < 2; ++k) \
;         acc[ai][bj][m][n] = __builtin_amdgcn_mfma_f32_16x16x32_bf16(Bt[n][k], At[m][k], acc[ai][bj][m][n], 0, 0, 0); __builtin_amdgcn_s_setprio(0); } while (0)
; #define PG8_WAIT_V(n) asm volatile("s_waitcnt vmcnt(" #n ")" ::: "memory")
; #define PG8_WAIT_L(n) asm volatile("s_waitcnt lgkmcnt(" #n ")" ::: "memory")
; #define PG8_BAR __builtin_amdgcn_s_barrier()
; #define PG8_SCHED __builtin_amdgcn_sched_barrier(0)
; template <class Epi, class Sched, bool ALIGN_EPI = false, bool SP2 = false>
; __device__ __forceinline__ void gemm_phase(PG8_LAS unsigned char* lds, const Gemm g, const Sched& S, const Epi& E) {
;     ...
;         for (int t = 0; t < nt; t += 2) {
;             const bool last = (t == nt - 2);
;             const char* a1 = cA + (size_t)(t + 1) * kstep;
;             const char* a2 = last ? nA : cA + (size_t)(t + 2) * kstep; const char* b2 = last ? nB : cB + (size_t)(t + 2) * kstep;
;             const char* a3 = a2 + kstep; const char* b3 = b2 + kstep;
;             if (last && has_next) S.a_ready(nxt);
;             if constexpr (SP2) {
;             PG8_LDB(B0, 0, 0); PG8_LDB(B1, 0, 1); PG8_SCHED; PG8_LDA(At, 0, 0); PG8_STAGE(PG8_SA(1, 1), a1 + hstep, voffA);
;             PG8_WAIT_V(8); PG8_WAIT_L(0); PG8_BAR; PG8_MMA(0, 0, At, B0); PG8_MMA(0, 1, At, B1); PG8_BAR; PG8_SCHED;
;             PG8_LDA(At, 0, 1); PG8_STAGE(PG8_SB(0, 0), b2, voffB); PG8_STAGE(PG8_SB(0, 1), b2 + hstep, voffB); PG8_STAGE(PG8_SA(0, 0), a2, voffA);
.LBB0_539:
	s_add_u32 s39, s30, s38
	s_addc_u32 s44, s31, 0
	s_add_u32 s42, s39, 0x100
	s_addc_u32 s43, s44, 0
	s_and_b64 s[40:41], s[36:37], exec
	s_cselect_b32 s41, s21, s43
	s_cselect_b32 s40, s68, s42
	s_add_u32 s38, s28, s38
	s_addc_u32 s42, s29, 0
	s_add_u32 s38, s38, 0x100
	s_addc_u32 s42, s42, 0
	s_and_b64 s[36:37], s[36:37], exec
	s_cselect_b32 s43, s19, s42
	s_cselect_b32 s42, s69, s38
	s_add_u32 s46, s39, 0x10080
	ds_read_b128 v[148:151], v145
	ds_read_b128 v[152:155], v145 offset:1024
	ds_read_b128 v[156:159], v145 offset:2048
	ds_read_b128 v[160:163], v145 offset:3072
	ds_read_b128 v[164:167], v146
	ds_read_b128 v[168:171], v146 offset:1024
	ds_read_b128 v[172:175], v146 offset:2048
	ds_read_b128 v[176:179], v146 offset:3072
	s_addc_u32 s47, s44, 0
	s_add_i32 s77, s61, s52
	s_add_i32 m0, s27, 0xc000
	s_add_i32 s80, s27, 0xe000
	s_add_i32 s74, s77, 0x2000
	s_add_u32 s44, s42, 0x10000
	s_addc_u32 s45, s43, 0
	s_add_i32 s76, s62, s52
	s_add_i32 s75, s76, 0x2000
	s_add_i32 s73, 0, 0x18000
	s_add_i32 s72, 0, 0x1c000
	s_add_u32 s38, s40, 0x10000
	s_addc_u32 s39, s41, 0
	s_add_i32 s71, s73, s52
	s_add_i32 s70, s71, 0x2000
	s_add_u32 s36, s42, 0x10080
	s_addc_u32 s37, s43, 0
	s_add_i32 s79, s72, s52
	s_add_i32 s78, s79, 0x2000
	v_lshl_add_u64 v[140:141], s[46:47], 0, v[128:129]
	ds_read_b128 v[180:183], v147
	ds_read_b128 v[186:189], v147 offset:1024
	ds_read_b128 v[190:193], v147 offset:2048
	ds_read_b128 v[194:197], v147 offset:3072
	ds_read_b128 v[198:201], v147 offset:4096
	ds_read_b128 v[202:205], v147 offset:5120
	ds_read_b128 v[206:209], v147 offset:6144
	ds_read_b128 v[210:213], v147 offset:7168
	global_load_lds_dwordx4 v[140:141], off
	v_lshl_add_u64 v[140:141], s[46:47], 0, v[132:133]
	s_mov_b32 m0, s80
	s_nop 0
	global_load_lds_dwordx4 v[140:141], off
	s_waitcnt vmcnt(6)
	s_waitcnt lgkmcnt(0)
	s_barrier
	s_setprio 1
	s_waitcnt lgkmcnt(0)
	v_mfma_f32_16x16x32_bf16 v[124:127], v[148:151], v[180:183], v[124:127]
	v_mfma_f32_16x16x32_bf16 v[120:123], v[156:159], v[180:183], v[120:123]
	v_mfma_f32_16x16x32_bf16 v[116:119], v[148:151], v[190:193], v[116:119]
	v_mfma_f32_16x16x32_bf16 v[108:111], v[156:159], v[190:193], v[108:111]
	v_mfma_f32_16x16x32_bf16 v[100:103], v[148:151], v[198:201], v[100:103]
	v_mfma_f32_16x16x32_bf16 v[92:95], v[156:159], v[198:201], v[92:95]
	v_mfma_f32_16x16x32_bf16 v[84:87], v[148:151], v[206:209], v[84:87]
	v_mfma_f32_16x16x32_bf16 v[76:79], v[156:159], v[206:209], v[76:79]
	v_mfma_f32_16x16x32_bf16 v[124:127], v[152:155], v[186:189], v[124:127]
	v_mfma_f32_16x16x32_bf16 v[120:123], v[160:163], v[186:189], v[120:123]
	v_mfma_f32_16x16x32_bf16 v[116:119], v[152:155], v[194:197], v[116:119]
	v_mfma_f32_16x16x32_bf16 v[108:111], v[160:163], v[194:197], v[108:111]
	v_mfma_f32_16x16x32_bf16 v[100:103], v[152:155], v[202:205], v[100:103]
	v_mfma_f32_16x16x32_bf16 v[92:95], v[160:163], v[202:205], v[92:95]
	v_mfma_f32_16x16x32_bf16 v[84:87], v[152:155], v[210:213], v[84:87]
	v_mfma_f32_16x16x32_bf16 v[76:79], v[160:163], v[210:213], v[76:79]
	s_setprio 0
	s_setprio 1
	v_mfma_f32_16x16x32_bf16 v[112:115], v[164:167], v[180:183], v[112:115]
	v_mfma_f32_16x16x32_bf16 v[104:107], v[172:175], v[180:183], v[104:107]
	v_mfma_f32_16x16x32_bf16 v[96:99], v[164:167], v[190:193], v[96:99]
	v_mfma_f32_16x16x32_bf16 v[88:91], v[172:175], v[190:193], v[88:91]
	v_mfma_f32_16x16x32_bf16 v[80:83], v[164:167], v[198:201], v[80:83]
	v_mfma_f32_16x16x32_bf16 v[72:75], v[172:175], v[198:201], v[72:75]
	v_mfma_f32_16x16x32_bf16 v[68:71], v[164:167], v[206:209], v[68:71]
	v_mfma_f32_16x16x32_bf16 v[64:67], v[172:175], v[206:209], v[64:67]
	v_mfma_f32_16x16x32_bf16 v[112:115], v[168:171], v[186:189], v[112:115]
	v_mfma_f32_16x16x32_bf16 v[104:107], v[176:179], v[186:189], v[104:107]
	v_mfma_f32_16x16x32_bf16 v[96:99], v[168:171], v[194:197], v[96:99]
	v_mfma_f32_16x16x32_bf16 v[88:91], v[176:179], v[194:197], v[88:91]
	v_mfma_f32_16x16x32_bf16 v[80:83], v[168:171], v[202:205], v[80:83]
	v_mfma_f32_16x16x32_bf16 v[72:75], v[176:179], v[202:205], v[72:75]
	v_mfma_f32_16x16x32_bf16 v[68:71], v[168:171], v[210:213], v[68:71]
	v_mfma_f32_16x16x32_bf16 v[64:67], v[176:179], v[210:213], v[64:67]
	s_setprio 0
	s_barrier
	s_mov_b32 m0, s77
	v_lshl_add_u64 v[140:141], s[42:43], 0, v[130:131]
	ds_read_b128 v[180:183], v147 offset:16384
	ds_read_b128 v[186:189], v147 offset:17408
	ds_read_b128 v[190:193], v147 offset:18432
	ds_read_b128 v[194:197], v147 offset:19456
	ds_read_b128 v[198:201], v147 offset:20480
	ds_read_b128 v[202:205], v147 offset:21504
	ds_read_b128 v[206:209], v147 offset:22528
	ds_read_b128 v[210:213], v147 offset:23552
	global_load_lds_dwordx4 v[140:141], off
	v_lshl_add_u64 v[214:215], s[42:43], 0, v[134:135]
	s_mov_b32 m0, s74
	v_lshl_add_u64 v[216:217], s[44:45], 0, v[130:131]
	global_load_lds_dwordx4 v[214:215], off
	s_mov_b32 m0, s76
	v_lshl_add_u64 v[218:219], s[40:41], 0, v[132:133]
	global_load_lds_dwordx4 v[216:217], off
	v_lshl_add_u64 v[216:217], s[44:45], 0, v[134:135]
	s_mov_b32 m0, s75
	s_nop 0
	global_load_lds_dwordx4 v[216:217], off
	v_lshl_add_u64 v[216:217], s[40:41], 0, v[128:129]
	s_mov_b32 m0, s27
	s_nop 0
	global_load_lds_dwordx4 v[216:217], off
	s_mov_b32 m0, s53
	s_nop 0
	global_load_lds_dwordx4 v[218:219], off
	s_waitcnt vmcnt(6)
	s_waitcnt lgkmcnt(0)
	s_barrier
; #define PG8_STAGE(bufoff, gbase, voff) do { _Pragma("unroll") for (int _i = 0; _i < 2; ++_i) \
;         __builtin_amdgcn_global_load_lds((const unsigned*)((const char*)(gbase) + (voff)[_i]), (PG8_LAS unsigned*)(lds + (bufoff) + ldsw + _i * 8192), 16, 0, 0); } while (0)
; #define PG8_LDA(dst, b, h) do { _Pragma("unroll") for (int m = 0; m < 4; ++m) _Pragma("unroll") for (int k = 0; k < 2; ++k) dst[m][k] = *(const PG8_LAS bf16x8*)(lds + PG8_SA(b, h) + aoff + m * 2048 + k * 1024); } while (0)
; #define PG8_LDB(dst, b, h) do { _Pragma("unroll") for (int n = 0; n < 2; ++n) _Pragma("unroll") for (int k = 0; k < 2; ++k) dst[n][k] = *(const PG8_LAS bf16x8*)(lds + PG8_SB(b, h) + boff + n * 2048 + k * 1024); } while (0)
; #define PG8_MMA(ai, bj, At, Bt) do { __builtin_amdgcn_s_setprio(1); _Pragma("unroll") for (int m = 0; m < 4; ++m) _Pragma("unroll") for (int n = 0; n < 2; ++n) _Pragma("unroll") for (int k = 0; k < 2; ++k) \
;         acc[ai][bj][m][n] = __builtin_amdgcn_mfma_f32_16x16x32_bf16(Bt[n][k], At[m][k], acc[ai][bj][m][n], 0, 0, 0); __builtin_amdgcn_s_setprio(0); } while (0)
; #define PG8_WAIT_V(n) asm volatile("s_waitcnt vmcnt(" #n ")" ::: "memory")
; #define PG8_WAIT_L(n) asm volatile("s_waitcnt lgkmcnt(" #n ")" ::: "memory")
; #define PG8_BAR __builtin_amdgcn_s_barrier()
; #define PG8_SCHED __builtin_amdgcn_sched_barrier(0)
; template <class Epi, class Sched, bool ALIGN_EPI = false, bool SP2 = false>
; __device__ __forceinline__ void gemm_phase(PG8_LAS unsigned char* lds, const Gemm g, const Sched& S, const Epi& E) {
;     ...
;             PG8_WAIT_V(8); PG8_WAIT_L(0); PG8_BAR; PG8_MMA(1, 0, At, B0); PG8_MMA(1, 1, At, B1); PG8_BAR; PG8_SCHED;
;             PG8_LDB(B0, 1, 0); PG8_LDB(B1, 1, 1); PG8_SCHED; PG8_LDA(At, 1, 0); PG8_STAGE(PG8_SA(0, 1), a2 + hstep, voffA);
;             PG8_WAIT_V(8); PG8_WAIT_L(0); PG8_BAR; PG8_MMA(0, 0, At, B0); PG8_MMA(0, 1, At, B1); PG8_BAR; PG8_SCHED;
	s_setprio 1
	s_waitcnt lgkmcnt(0)
	v_mfma_f32_16x16x32_bf16 v[60:63], v[148:151], v[180:183], v[60:63]
	v_mfma_f32_16x16x32_bf16 v[56:59], v[156:159], v[180:183], v[56:59]
	v_mfma_f32_16x16x32_bf16 v[52:55], v[148:151], v[190:193], v[52:55]
	v_mfma_f32_16x16x32_bf16 v[44:47], v[156:159], v[190:193], v[44:47]
	v_mfma_f32_16x16x32_bf16 v[36:39], v[148:151], v[198:201], v[36:39]
	v_mfma_f32_16x16x32_bf16 v[28:31], v[156:159], v[198:201], v[28:31]
	v_mfma_f32_16x16x32_bf16 v[20:23], v[148:151], v[206:209], v[20:23]
	v_mfma_f32_16x16x32_bf16 v[12:15], v[156:159], v[206:209], v[12:15]
	v_mfma_f32_16x16x32_bf16 v[60:63], v[152:155], v[186:189], v[60:63]
	v_mfma_f32_16x16x32_bf16 v[56:59], v[160:163], v[186:189], v[56:59]
	v_mfma_f32_16x16x32_bf16 v[52:55], v[152:155], v[194:197], v[52:55]
	v_mfma_f32_16x16x32_bf16 v[44:47], v[160:163], v[194:197], v[44:47]
	v_mfma_f32_16x16x32_bf16 v[36:39], v[152:155], v[202:205], v[36:39]
	v_mfma_f32_16x16x32_bf16 v[28:31], v[160:163], v[202:205], v[28:31]
	v_mfma_f32_16x16x32_bf16 v[20:23], v[152:155], v[210:213], v[20:23]
	v_mfma_f32_16x16x32_bf16 v[12:15], v[160:163], v[210:213], v[12:15]
	s_setprio 0
	s_setprio 1
	v_mfma_f32_16x16x32_bf16 v[48:51], v[164:167], v[180:183], v[48:51]
	v_mfma_f32_16x16x32_bf16 v[40:43], v[172:175], v[180:183], v[40:43]
	v_mfma_f32_16x16x32_bf16 v[32:35], v[164:167], v[190:193], v[32:35]
	v_mfma_f32_16x16x32_bf16 v[24:27], v[172:175], v[190:193], v[24:27]
	v_mfma_f32_16x16x32_bf16 v[16:19], v[164:167], v[198:201], v[16:19]
	v_mfma_f32_16x16x32_bf16 v[8:11], v[172:175], v[198:201], v[8:11]
	v_mfma_f32_16x16x32_bf16 v[4:7], v[164:167], v[206:209], v[4:7]
	v_mfma_f32_16x16x32_bf16 v[0:3], v[172:175], v[206:209], v[0:3]
	v_mfma_f32_16x16x32_bf16 v[48:51], v[168:171], v[186:189], v[48:51]
	v_mfma_f32_16x16x32_bf16 v[40:43], v[176:179], v[186:189], v[40:43]
	v_mfma_f32_16x16x32_bf16 v[32:35], v[168:171], v[194:197], v[32:35]
	v_mfma_f32_16x16x32_bf16 v[24:27], v[176:179], v[194:197], v[24:27]
	v_mfma_f32_16x16x32_bf16 v[16:19], v[168:171], v[202:205], v[16:19]
	v_mfma_f32_16x16x32_bf16 v[8:11], v[176:179], v[202:205], v[8:11]
	v_mfma_f32_16x16x32_bf16 v[4:7], v[168:171], v[210:213], v[4:7]
	v_mfma_f32_16x16x32_bf16 v[0:3], v[176:179], v[210:213], v[0:3]
	s_setprio 0
	s_barrier
	v_add_u32_e32 v160, s73, v143
	v_add_u32_e32 v176, s72, v143
	ds_read_b128 v[148:151], v160
	ds_read_b128 v[152:155], v160 offset:1024
	ds_read_b128 v[156:159], v160 offset:2048
	ds_read_b128 v[160:163], v160 offset:3072
	ds_read_b128 v[164:167], v176
	ds_read_b128 v[168:171], v176 offset:1024
	ds_read_b128 v[172:175], v176 offset:2048
	ds_read_b128 v[176:179], v176 offset:3072
	s_mov_b32 m0, s54
	v_lshl_add_u64 v[220:221], s[38:39], 0, v[128:129]
	ds_read_b128 v[180:183], v147 offset:32768
	ds_read_b128 v[186:189], v147 offset:33792
	ds_read_b128 v[190:193], v147 offset:34816
	ds_read_b128 v[194:197], v147 offset:35840
	ds_read_b128 v[198:201], v147 offset:36864
	ds_read_b128 v[202:205], v147 offset:37888
	ds_read_b128 v[206:209], v147 offset:38912
	ds_read_b128 v[210:213], v147 offset:39936
	global_load_lds_dwordx4 v[220:221], off
	v_lshl_add_u64 v[220:221], s[38:39], 0, v[132:133]
	s_mov_b32 m0, s55
	s_nop 0
	global_load_lds_dwordx4 v[220:221], off
	s_waitcnt vmcnt(6)
	s_waitcnt lgkmcnt(0)
	s_barrier
	s_setprio 1
	s_waitcnt lgkmcnt(0)
	v_mfma_f32_16x16x32_bf16 v[124:127], v[148:151], v[180:183], v[124:127]
	v_mfma_f32_16x16x32_bf16 v[120:123], v[156:159], v[180:183], v[120:123]
	v_mfma_f32_16x16x32_bf16 v[116:119], v[148:151], v[190:193], v[116:119]
	v_mfma_f32_16x16x32_bf16 v[108:111], v[156:159], v[190:193], v[108:111]
	v_mfma_f32_16x16x32_bf16 v[100:103], v[148:151], v[198:201], v[100:103]
	v_mfma_f32_16x16x32_bf16 v[92:95], v[156:159], v[198:201], v[92:95]
	v_mfma_f32_16x16x32_bf16 v[84:87], v[148:151], v[206:209], v[84:87]
	v_mfma_f32_16x16x32_bf16 v[76:79], v[156:159], v[206:209], v[76:79]
	v_mfma_f32_16x16x32_bf16 v[124:127], v[152:155], v[186:189], v[124:127]
	v_mfma_f32_16x16x32_bf16 v[120:123], v[160:163], v[186:189], v[120:123]
	v_mfma_f32_16x16x32_bf16 v[116:119], v[152:155], v[194:197], v[116:119]
	v_mfma_f32_16x16x32_bf16 v[108:111], v[160:163], v[194:197], v[108:111]
	v_mfma_f32_16x16x32_bf16 v[100:103], v[152:155], v[202:205], v[100:103]
	v_mfma_f32_16x16x32_bf16 v[92:95], v[160:163], v[202:205], v[92:95]
	v_mfma_f32_16x16x32_bf16 v[84:87], v[152:155], v[210:213], v[84:87]
	v_mfma_f32_16x16x32_bf16 v[76:79], v[160:163], v[210:213], v[76:79]
	s_setprio 0
	s_setprio 1
	v_mfma_f32_16x16x32_bf16 v[112:115], v[164:167], v[180:183], v[112:115]
	v_mfma_f32_16x16x32_bf16 v[104:107], v[172:175], v[180:183], v[104:107]
	v_mfma_f32_16x16x32_bf16 v[96:99], v[164:167], v[190:193], v[96:99]
	v_mfma_f32_16x16x32_bf16 v[88:91], v[172:175], v[190:193], v[88:91]
	v_mfma_f32_16x16x32_bf16 v[80:83], v[164:167], v[198:201], v[80:83]
	v_mfma_f32_16x16x32_bf16 v[72:75], v[172:175], v[198:201], v[72:75]
	v_mfma_f32_16x16x32_bf16 v[68:71], v[164:167], v[206:209], v[68:71]
	v_mfma_f32_16x16x32_bf16 v[64:67], v[172:175], v[206:209], v[64:67]
	v_mfma_f32_16x16x32_bf16 v[112:115], v[168:171], v[186:189], v[112:115]
	v_mfma_f32_16x16x32_bf16 v[104:107], v[176:179], v[186:189], v[104:107]
	v_mfma_f32_16x16x32_bf16 v[96:99], v[168:171], v[194:197], v[96:99]
	v_mfma_f32_16x16x32_bf16 v[88:91], v[176:179], v[194:197], v[88:91]
	v_mfma_f32_16x16x32_bf16 v[80:83], v[168:171], v[202:205], v[80:83]
	v_mfma_f32_16x16x32_bf16 v[72:75], v[176:179], v[202:205], v[72:75]
	v_mfma_f32_16x16x32_bf16 v[68:71], v[168:171], v[210:213], v[68:71]
	v_mfma_f32_16x16x32_bf16 v[64:67], v[176:179], v[210:213], v[64:67]
	s_setprio 0
	s_barrier
; #define PG8_STAGE(bufoff, gbase, voff) do { _Pragma("unroll") for (int _i = 0; _i < 2; ++_i) \
;         __builtin_amdgcn_global_load_lds((const unsigned*)((const char*)(gbase) + (voff)[_i]), (PG8_LAS unsigned*)(lds + (bufoff) + ldsw + _i * 8192), 16, 0, 0); } while (0)
; #define PG8_LDA(dst, b, h) do { _Pragma("unroll") for (int m = 0; m < 4; ++m) _Pragma("unroll") for (int k = 0; k < 2; ++k) dst[m][k] = *(const PG8_LAS bf16x8*)(lds + PG8_SA(b, h) + aoff + m * 2048 + k * 1024); } while (0)
; #define PG8_MMA(ai, bj, At, Bt) do { __builtin_amdgcn_s_setprio(1); _Pragma("unroll") for (int m = 0; m < 4; ++m) _Pragma("unroll") for (int n = 0; n < 2; ++n) _Pragma("unroll") for (int k = 0; k < 2; ++k) \
;         acc[ai][bj][m][n] = __builtin_amdgcn_mfma_f32_16x16x32_bf16(Bt[n][k], At[m][k], acc[ai][bj][m][n], 0, 0, 0); __builtin_amdgcn_s_setprio(0); } while (0)
; #define PG8_WAIT_V(n) asm volatile("s_waitcnt vmcnt(" #n ")" ::: "memory")
; #define PG8_WAIT_L(n) asm volatile("s_waitcnt lgkmcnt(" #n ")" ::: "memory")
; #define PG8_BAR __builtin_amdgcn_s_barrier()
; #define PG8_SCHED __builtin_amdgcn_sched_barrier(0)
; template <class Epi, class Sched, bool ALIGN_EPI = false, bool SP2 = false>
; __device__ __forceinline__ void gemm_phase(PG8_LAS unsigned char* lds, const Gemm g, const Sched& S, const Epi& E) {
;     ...
;         for (int t = 0; t < nt; t += 2) {
;             const bool last = (t == nt - 2);
;             const char* a1 = cA + (size_t)(t + 1) * kstep;
;             const char* a2 = last ? nA : cA + (size_t)(t + 2) * kstep; const char* b2 = last ? nB : cB + (size_t)(t + 2) * kstep;
;     ...
;             PG8_LDA(At, 1, 1); PG8_STAGE(PG8_SB(1, 0), b3, voffB); PG8_STAGE(PG8_SB(1, 1), b3 + hstep, voffB); PG8_STAGE(PG8_SA(1, 0), a3, voffA);
;             PG8_WAIT_V(8); PG8_WAIT_L(0); PG8_BAR; PG8_MMA(1, 0, At, B0); PG8_MMA(1, 1, At, B1); PG8_BAR; PG8_SCHED;
	s_mov_b32 m0, s71
	v_lshl_add_u64 v[140:141], v[140:141], 0, s[6:7]
	ds_read_b128 v[180:183], v147 offset:49152
	ds_read_b128 v[186:189], v147 offset:50176
	ds_read_b128 v[190:193], v147 offset:51200
	ds_read_b128 v[194:197], v147 offset:52224
	ds_read_b128 v[198:201], v147 offset:53248
	ds_read_b128 v[202:205], v147 offset:54272
	ds_read_b128 v[206:209], v147 offset:55296
	ds_read_b128 v[210:213], v147 offset:56320
	global_load_lds_dwordx4 v[140:141], off
	v_lshl_add_u64 v[140:141], v[214:215], 0, s[6:7]
	s_mov_b32 m0, s70
	s_nop 0
	global_load_lds_dwordx4 v[140:141], off
	v_lshl_add_u64 v[140:141], s[36:37], 0, v[130:131]
	s_mov_b32 m0, s79
	s_nop 0
	global_load_lds_dwordx4 v[140:141], off
	v_lshl_add_u64 v[140:141], s[36:37], 0, v[134:135]
	s_mov_b32 m0, s78
	s_nop 0
	global_load_lds_dwordx4 v[140:141], off
	v_lshl_add_u64 v[140:141], v[216:217], 0, s[6:7]
	s_mov_b32 m0, s57
	s_nop 0
	global_load_lds_dwordx4 v[140:141], off
	v_lshl_add_u64 v[140:141], v[218:219], 0, s[6:7]
	s_mov_b32 m0, s58
	s_nop 0
	global_load_lds_dwordx4 v[140:141], off
	s_waitcnt vmcnt(6)
	s_waitcnt lgkmcnt(0)
	s_barrier
	s_setprio 1
	s_waitcnt lgkmcnt(0)
	v_mfma_f32_16x16x32_bf16 v[60:63], v[148:151], v[180:183], v[60:63]
	v_mfma_f32_16x16x32_bf16 v[56:59], v[156:159], v[180:183], v[56:59]
	v_mfma_f32_16x16x32_bf16 v[52:55], v[148:151], v[190:193], v[52:55]
	v_mfma_f32_16x16x32_bf16 v[44:47], v[156:159], v[190:193], v[44:47]
	v_mfma_f32_16x16x32_bf16 v[36:39], v[148:151], v[198:201], v[36:39]
	v_mfma_f32_16x16x32_bf16 v[28:31], v[156:159], v[198:201], v[28:31]
	v_mfma_f32_16x16x32_bf16 v[20:23], v[148:151], v[206:209], v[20:23]
	v_mfma_f32_16x16x32_bf16 v[12:15], v[156:159], v[206:209], v[12:15]
	v_mfma_f32_16x16x32_bf16 v[60:63], v[152:155], v[186:189], v[60:63]
	v_mfma_f32_16x16x32_bf16 v[56:59], v[160:163], v[186:189], v[56:59]
	v_mfma_f32_16x16x32_bf16 v[52:55], v[152:155], v[194:197], v[52:55]
	v_mfma_f32_16x16x32_bf16 v[44:47], v[160:163], v[194:197], v[44:47]
	v_mfma_f32_16x16x32_bf16 v[36:39], v[152:155], v[202:205], v[36:39]
	v_mfma_f32_16x16x32_bf16 v[28:31], v[160:163], v[202:205], v[28:31]
	v_mfma_f32_16x16x32_bf16 v[20:23], v[152:155], v[210:213], v[20:23]
	v_mfma_f32_16x16x32_bf16 v[12:15], v[160:163], v[210:213], v[12:15]
	s_setprio 0
	s_setprio 1
	v_mfma_f32_16x16x32_bf16 v[48:51], v[164:167], v[180:183], v[48:51]
	v_mfma_f32_16x16x32_bf16 v[40:43], v[172:175], v[180:183], v[40:43]
	v_mfma_f32_16x16x32_bf16 v[32:35], v[164:167], v[190:193], v[32:35]
	v_mfma_f32_16x16x32_bf16 v[24:27], v[172:175], v[190:193], v[24:27]
	v_mfma_f32_16x16x32_bf16 v[16:19], v[164:167], v[198:201], v[16:19]
	v_mfma_f32_16x16x32_bf16 v[8:11], v[172:175], v[198:201], v[8:11]
	v_mfma_f32_16x16x32_bf16 v[4:7], v[164:167], v[206:209], v[4:7]
	v_mfma_f32_16x16x32_bf16 v[0:3], v[172:175], v[206:209], v[0:3]
	v_mfma_f32_16x16x32_bf16 v[48:51], v[168:171], v[186:189], v[48:51]
	v_mfma_f32_16x16x32_bf16 v[40:43], v[176:179], v[186:189], v[40:43]
	v_mfma_f32_16x16x32_bf16 v[32:35], v[168:171], v[194:197], v[32:35]
	v_mfma_f32_16x16x32_bf16 v[24:27], v[176:179], v[194:197], v[24:27]
	v_mfma_f32_16x16x32_bf16 v[16:19], v[168:171], v[202:205], v[16:19]
	v_mfma_f32_16x16x32_bf16 v[8:11], v[176:179], v[202:205], v[8:11]
	v_mfma_f32_16x16x32_bf16 v[4:7], v[168:171], v[210:213], v[4:7]
	v_mfma_f32_16x16x32_bf16 v[0:3], v[176:179], v[210:213], v[0:3]
	s_setprio 0
	s_barrier
	s_movk_i32 s38, 0x100
	s_andn2_b64 vcc, exec, s[34:35]
	s_mov_b64 s[36:37], -1
	s_mov_b64 s[34:35], 0
	s_cbranch_vccz .LBB0_539
	s_and_b64 vcc, exec, s[8:9]
	s_cbranch_vccz .LBB0_542
	s_barrier

; #define PG8_STAGE(bufoff, gbase, voff) do { _Pragma("unroll") for (int _i = 0; _i < 2; ++_i) \
;         __builtin_amdgcn_global_load_lds((const unsigned*)((const char*)(gbase) + (voff)[_i]), (PG8_LAS unsigned*)(lds + (bufoff) + ldsw + _i * 8192), 16, 0, 0); } while (0)
; #define PG8_LDA(dst, b, h) do { _Pragma("unroll") for (int m = 0; m < 4; ++m) _Pragma("unroll") for (int k = 0; k < 2; ++k) dst[m][k] = *(const PG8_LAS bf16x8*)(lds + PG8_SA(b, h) + aoff + m * 2048 + k * 1024); } while (0)
; #define PG8_LDB(dst, b, h) do { _Pragma("unroll") for (int n = 0; n < 2; ++n) _Pragma("unroll") for (int k = 0; k < 2; ++k) dst[n][k] = *(const PG8_LAS bf16x8*)(lds + PG8_SB(b, h) + boff + n * 2048 + k * 1024); } while (0)
; #define PG8_MMA(ai, bj, At, Bt) do { __builtin_amdgcn_s_setprio(1); _Pragma("unroll") for (int m = 0; m < 4; ++m) _Pragma("unroll") for (int n = 0; n < 2; ++n) _Pragma("unroll") for (int k = 0; k < 2; ++k) \
;         acc[ai][bj][m][n] = __builtin_amdgcn_mfma_f32_16x16x32_bf16(Bt[n][k], At[m][k], acc[ai][bj][m][n], 0, 0, 0); __builtin_amdgcn_s_setprio(0); } while (0)
; #define PG8_WAIT_V(n) asm volatile("s_waitcnt vmcnt(" #n ")" ::: "memory")
; #define PG8_WAIT_L(n) asm volatile("s_waitcnt lgkmcnt(" #n ")" ::: "memory")
; #define PG8_BAR __builtin_amdgcn_s_barrier()
; #define PG8_SCHED __builtin_amdgcn_sched_barrier(0)
; template <class Epi, class Sched, bool ALIGN_EPI = false, bool SP2 = false>
; __device__ __forceinline__ void gemm_phase(PG8_LAS unsigned char* lds, const Gemm g, const Sched& S, const Epi& E) {
;     ...
;         for (int t = 0; t < nt; t += 2) {
;             const bool last = (t == nt - 2);
;             const char* a1 = cA + (size_t)(t + 1) * kstep;
;             const char* a2 = last ? nA : cA + (size_t)(t + 2) * kstep; const char* b2 = last ? nB : cB + (size_t)(t + 2) * kstep;
;             const char* a3 = a2 + kstep; const char* b3 = b2 + kstep;
;             if (last && has_next) S.a_ready(nxt);
;             if constexpr (SP2) {
;             PG8_LDB(B0, 0, 0); PG8_LDB(B1, 0, 1); PG8_SCHED; PG8_LDA(At, 0, 0); PG8_STAGE(PG8_SA(1, 1), a1 + hstep, voffA);
;             PG8_WAIT_V(8); PG8_WAIT_L(0); PG8_BAR; PG8_MMA(0, 0, At, B0); PG8_MMA(0, 1, At, B1); PG8_BAR; PG8_SCHED;
;             PG8_LDA(At, 0, 1); PG8_STAGE(PG8_SB(0, 0), b2, voffB); PG8_STAGE(PG8_SB(0, 1), b2 + hstep, voffB); PG8_STAGE(PG8_SA(0, 0), a2, voffA);
.LBB0_868:
	ds_read_b128 v[152:155], v149
	ds_read_b128 v[156:159], v149 offset:1024
	ds_read_b128 v[160:163], v149 offset:2048
	ds_read_b128 v[164:167], v149 offset:3072
	ds_read_b128 v[168:171], v150
	ds_read_b128 v[172:175], v150 offset:1024
	ds_read_b128 v[176:179], v150 offset:2048
	ds_read_b128 v[180:183], v150 offset:3072
	s_add_u32 s34, s30, 0xfffc0080
	s_addc_u32 s35, s31, -1
	s_cmp_eq_u32 s61, 12
	s_cselect_b32 s37, s23, s35
	s_cselect_b32 s36, s57, s34
	s_cselect_b32 s35, s21, s60
	s_cselect_b32 s34, s58, s59
	v_lshl_add_u64 v[144:145], s[30:31], 0, v[138:139]
	s_add_i32 m0, s29, 0xc000
	ds_read_b128 v[186:189], v151
	ds_read_b128 v[190:193], v151 offset:1024
	ds_read_b128 v[194:197], v151 offset:2048
	ds_read_b128 v[198:201], v151 offset:3072
	ds_read_b128 v[202:205], v151 offset:4096
	ds_read_b128 v[206:209], v151 offset:5120
	ds_read_b128 v[210:213], v151 offset:6144
	ds_read_b128 v[214:217], v151 offset:7168
	global_load_lds_dwordx4 v[144:145], off
	v_lshl_add_u64 v[144:145], s[30:31], 0, v[136:137]
	s_add_i32 m0, s29, 0xe000
	s_nop 0
	global_load_lds_dwordx4 v[144:145], off
	s_waitcnt vmcnt(6)
	s_waitcnt lgkmcnt(0)
	s_barrier
	s_setprio 1
	s_waitcnt lgkmcnt(0)
	v_mfma_f32_16x16x32_bf16 v[124:127], v[152:155], v[186:189], v[124:127]
	v_mfma_f32_16x16x32_bf16 v[120:123], v[160:163], v[186:189], v[120:123]
	v_mfma_f32_16x16x32_bf16 v[116:119], v[152:155], v[194:197], v[116:119]
	v_mfma_f32_16x16x32_bf16 v[108:111], v[160:163], v[194:197], v[108:111]
	v_mfma_f32_16x16x32_bf16 v[100:103], v[152:155], v[202:205], v[100:103]
	v_mfma_f32_16x16x32_bf16 v[92:95], v[160:163], v[202:205], v[92:95]
	v_mfma_f32_16x16x32_bf16 v[84:87], v[152:155], v[210:213], v[84:87]
	v_mfma_f32_16x16x32_bf16 v[76:79], v[160:163], v[210:213], v[76:79]
	v_mfma_f32_16x16x32_bf16 v[124:127], v[156:159], v[190:193], v[124:127]
	v_mfma_f32_16x16x32_bf16 v[120:123], v[164:167], v[190:193], v[120:123]
	v_mfma_f32_16x16x32_bf16 v[116:119], v[156:159], v[198:201], v[116:119]
	v_mfma_f32_16x16x32_bf16 v[108:111], v[164:167], v[198:201], v[108:111]
	v_mfma_f32_16x16x32_bf16 v[100:103], v[156:159], v[206:209], v[100:103]
	v_mfma_f32_16x16x32_bf16 v[92:95], v[164:167], v[206:209], v[92:95]
	v_mfma_f32_16x16x32_bf16 v[84:87], v[156:159], v[214:217], v[84:87]
	v_mfma_f32_16x16x32_bf16 v[76:79], v[164:167], v[214:217], v[76:79]
	s_setprio 0
	s_setprio 1
	v_mfma_f32_16x16x32_bf16 v[112:115], v[168:171], v[186:189], v[112:115]
	v_mfma_f32_16x16x32_bf16 v[104:107], v[176:179], v[186:189], v[104:107]
	v_mfma_f32_16x16x32_bf16 v[96:99], v[168:171], v[194:197], v[96:99]
	v_mfma_f32_16x16x32_bf16 v[88:91], v[176:179], v[194:197], v[88:91]
	v_mfma_f32_16x16x32_bf16 v[80:83], v[168:171], v[202:205], v[80:83]
	v_mfma_f32_16x16x32_bf16 v[72:75], v[176:179], v[202:205], v[72:75]
	v_mfma_f32_16x16x32_bf16 v[68:71], v[168:171], v[210:213], v[68:71]
	v_mfma_f32_16x16x32_bf16 v[64:67], v[176:179], v[210:213], v[64:67]
	v_mfma_f32_16x16x32_bf16 v[112:115], v[172:175], v[190:193], v[112:115]
	v_mfma_f32_16x16x32_bf16 v[104:107], v[180:183], v[190:193], v[104:107]
	v_mfma_f32_16x16x32_bf16 v[96:99], v[172:175], v[198:201], v[96:99]
	v_mfma_f32_16x16x32_bf16 v[88:91], v[180:183], v[198:201], v[88:91]
	v_mfma_f32_16x16x32_bf16 v[80:83], v[172:175], v[206:209], v[80:83]
	v_mfma_f32_16x16x32_bf16 v[72:75], v[180:183], v[206:209], v[72:75]
	v_mfma_f32_16x16x32_bf16 v[68:71], v[172:175], v[214:217], v[68:71]
	v_mfma_f32_16x16x32_bf16 v[64:67], v[180:183], v[214:217], v[64:67]
	s_setprio 0
	s_barrier
	s_add_i32 s62, s51, s42
	v_lshl_add_u64 v[144:145], s[34:35], 0, v[130:131]
	s_mov_b32 m0, s62
	ds_read_b128 v[186:189], v151 offset:16384
	ds_read_b128 v[190:193], v151 offset:17408
	ds_read_b128 v[194:197], v151 offset:18432
	ds_read_b128 v[198:201], v151 offset:19456
	ds_read_b128 v[202:205], v151 offset:20480
	ds_read_b128 v[206:209], v151 offset:21504
	ds_read_b128 v[210:213], v151 offset:22528
	ds_read_b128 v[214:217], v151 offset:23552
	global_load_lds_dwordx4 v[144:145], off
	s_add_i32 m0, s62, 0x2000
	s_add_u32 s62, s34, 0x40000
	v_lshl_add_u64 v[218:219], s[34:35], 0, v[134:135]
	s_addc_u32 s63, s35, 0
	s_add_i32 s64, s93, s42
	global_load_lds_dwordx4 v[218:219], off
	v_lshl_add_u64 v[220:221], s[62:63], 0, v[130:131]
	s_mov_b32 m0, s64
	v_lshl_add_u64 v[222:223], s[36:37], 0, v[132:133]
	global_load_lds_dwordx4 v[220:221], off
	v_lshl_add_u64 v[220:221], s[62:63], 0, v[134:135]
	s_add_i32 m0, s64, 0x2000
	s_nop 0
	global_load_lds_dwordx4 v[220:221], off
	v_lshl_add_u64 v[220:221], s[36:37], 0, v[128:129]
	s_mov_b32 m0, s29
	s_nop 0
	global_load_lds_dwordx4 v[220:221], off
	s_mov_b32 m0, s43
	s_nop 0
	global_load_lds_dwordx4 v[222:223], off
	s_waitcnt vmcnt(6)
	s_waitcnt lgkmcnt(0)
	s_barrier
; #define PG8_STAGE(bufoff, gbase, voff) do { _Pragma("unroll") for (int _i = 0; _i < 2; ++_i) \
;         __builtin_amdgcn_global_load_lds((const unsigned*)((const char*)(gbase) + (voff)[_i]), (PG8_LAS unsigned*)(lds + (bufoff) + ldsw + _i * 8192), 16, 0, 0); } while (0)
; #define PG8_LDA(dst, b, h) do { _Pragma("unroll") for (int m = 0; m < 4; ++m) _Pragma("unroll") for (int k = 0; k < 2; ++k) dst[m][k] = *(const PG8_LAS bf16x8*)(lds + PG8_SA(b, h) + aoff + m * 2048 + k * 1024); } while (0)
; #define PG8_LDB(dst, b, h) do { _Pragma("unroll") for (int n = 0; n < 2; ++n) _Pragma("unroll") for (int k = 0; k < 2; ++k) dst[n][k] = *(const PG8_LAS bf16x8*)(lds + PG8_SB(b, h) + boff + n * 2048 + k * 1024); } while (0)
; #define PG8_MMA(ai, bj, At, Bt) do { __builtin_amdgcn_s_setprio(1); _Pragma("unroll") for (int m = 0; m < 4; ++m) _Pragma("unroll") for (int n = 0; n < 2; ++n) _Pragma("unroll") for (int k = 0; k < 2; ++k) \
;         acc[ai][bj][m][n] = __builtin_amdgcn_mfma_f32_16x16x32_bf16(Bt[n][k], At[m][k], acc[ai][bj][m][n], 0, 0, 0); __builtin_amdgcn_s_setprio(0); } while (0)
; #define PG8_WAIT_V(n) asm volatile("s_waitcnt vmcnt(" #n ")" ::: "memory")
; #define PG8_WAIT_L(n) asm volatile("s_waitcnt lgkmcnt(" #n ")" ::: "memory")
; #define PG8_BAR __builtin_amdgcn_s_barrier()
; #define PG8_SCHED __builtin_amdgcn_sched_barrier(0)
; template <class Epi, class Sched, bool ALIGN_EPI = false, bool SP2 = false>
; __device__ __forceinline__ void gemm_phase(PG8_LAS unsigned char* lds, const Gemm g, const Sched& S, const Epi& E) {
;     ...
;             PG8_WAIT_V(8); PG8_WAIT_L(0); PG8_BAR; PG8_MMA(1, 0, At, B0); PG8_MMA(1, 1, At, B1); PG8_BAR; PG8_SCHED;
;             PG8_LDB(B0, 1, 0); PG8_LDB(B1, 1, 1); PG8_SCHED; PG8_LDA(At, 1, 0); PG8_STAGE(PG8_SA(0, 1), a2 + hstep, voffA);
;             PG8_WAIT_V(8); PG8_WAIT_L(0); PG8_BAR; PG8_MMA(0, 0, At, B0); PG8_MMA(0, 1, At, B1); PG8_BAR; PG8_SCHED;
	s_setprio 1
	s_waitcnt lgkmcnt(0)
	v_mfma_f32_16x16x32_bf16 v[60:63], v[152:155], v[186:189], v[60:63]
	v_mfma_f32_16x16x32_bf16 v[56:59], v[160:163], v[186:189], v[56:59]
	v_mfma_f32_16x16x32_bf16 v[52:55], v[152:155], v[194:197], v[52:55]
	v_mfma_f32_16x16x32_bf16 v[44:47], v[160:163], v[194:197], v[44:47]
	v_mfma_f32_16x16x32_bf16 v[36:39], v[152:155], v[202:205], v[36:39]
	v_mfma_f32_16x16x32_bf16 v[28:31], v[160:163], v[202:205], v[28:31]
	v_mfma_f32_16x16x32_bf16 v[20:23], v[152:155], v[210:213], v[20:23]
	v_mfma_f32_16x16x32_bf16 v[12:15], v[160:163], v[210:213], v[12:15]
	v_mfma_f32_16x16x32_bf16 v[60:63], v[156:159], v[190:193], v[60:63]
	v_mfma_f32_16x16x32_bf16 v[56:59], v[164:167], v[190:193], v[56:59]
	v_mfma_f32_16x16x32_bf16 v[52:55], v[156:159], v[198:201], v[52:55]
	v_mfma_f32_16x16x32_bf16 v[44:47], v[164:167], v[198:201], v[44:47]
	v_mfma_f32_16x16x32_bf16 v[36:39], v[156:159], v[206:209], v[36:39]
	v_mfma_f32_16x16x32_bf16 v[28:31], v[164:167], v[206:209], v[28:31]
	v_mfma_f32_16x16x32_bf16 v[20:23], v[156:159], v[214:217], v[20:23]
	v_mfma_f32_16x16x32_bf16 v[12:15], v[164:167], v[214:217], v[12:15]
	s_setprio 0
	s_setprio 1
	v_mfma_f32_16x16x32_bf16 v[48:51], v[168:171], v[186:189], v[48:51]
	v_mfma_f32_16x16x32_bf16 v[40:43], v[176:179], v[186:189], v[40:43]
	v_mfma_f32_16x16x32_bf16 v[32:35], v[168:171], v[194:197], v[32:35]
	v_mfma_f32_16x16x32_bf16 v[24:27], v[176:179], v[194:197], v[24:27]
	v_mfma_f32_16x16x32_bf16 v[16:19], v[168:171], v[202:205], v[16:19]
	v_mfma_f32_16x16x32_bf16 v[8:11], v[176:179], v[202:205], v[8:11]
	v_mfma_f32_16x16x32_bf16 v[4:7], v[168:171], v[210:213], v[4:7]
	v_mfma_f32_16x16x32_bf16 v[0:3], v[176:179], v[210:213], v[0:3]
	v_mfma_f32_16x16x32_bf16 v[48:51], v[172:175], v[190:193], v[48:51]
	v_mfma_f32_16x16x32_bf16 v[40:43], v[180:183], v[190:193], v[40:43]
	v_mfma_f32_16x16x32_bf16 v[32:35], v[172:175], v[198:201], v[32:35]
	v_mfma_f32_16x16x32_bf16 v[24:27], v[180:183], v[198:201], v[24:27]
	v_mfma_f32_16x16x32_bf16 v[16:19], v[172:175], v[206:209], v[16:19]
	v_mfma_f32_16x16x32_bf16 v[8:11], v[180:183], v[206:209], v[8:11]
	v_mfma_f32_16x16x32_bf16 v[4:7], v[172:175], v[214:217], v[4:7]
	v_mfma_f32_16x16x32_bf16 v[0:3], v[180:183], v[214:217], v[0:3]
	s_setprio 0
	s_barrier
	s_add_i32 s62, 0, 0x18000
	s_add_i32 s63, 0, 0x1c000
	v_add_u32_e32 v164, s62, v147
	v_add_u32_e32 v180, s63, v147
	ds_read_b128 v[152:155], v164
	ds_read_b128 v[156:159], v164 offset:1024
	ds_read_b128 v[160:163], v164 offset:2048
	ds_read_b128 v[164:167], v164 offset:3072
	ds_read_b128 v[168:171], v180
	ds_read_b128 v[172:175], v180 offset:1024
	ds_read_b128 v[176:179], v180 offset:2048
	ds_read_b128 v[180:183], v180 offset:3072
	s_add_u32 s36, s36, 0x40000
	s_addc_u32 s37, s37, 0
	s_mov_b32 m0, s44
	v_lshl_add_u64 v[224:225], s[36:37], 0, v[128:129]
	ds_read_b128 v[186:189], v151 offset:32768
	ds_read_b128 v[190:193], v151 offset:33792
	ds_read_b128 v[194:197], v151 offset:34816
	ds_read_b128 v[198:201], v151 offset:35840
	ds_read_b128 v[202:205], v151 offset:36864
	ds_read_b128 v[206:209], v151 offset:37888
	ds_read_b128 v[210:213], v151 offset:38912
	ds_read_b128 v[214:217], v151 offset:39936
	global_load_lds_dwordx4 v[224:225], off
	v_lshl_add_u64 v[224:225], s[36:37], 0, v[132:133]
	s_mov_b32 m0, s45
	s_nop 0
	global_load_lds_dwordx4 v[224:225], off
	s_waitcnt vmcnt(6)
	s_waitcnt lgkmcnt(0)
	s_barrier
	s_setprio 1
	s_waitcnt lgkmcnt(0)
	v_mfma_f32_16x16x32_bf16 v[124:127], v[152:155], v[186:189], v[124:127]
	v_mfma_f32_16x16x32_bf16 v[120:123], v[160:163], v[186:189], v[120:123]
	v_mfma_f32_16x16x32_bf16 v[116:119], v[152:155], v[194:197], v[116:119]
	v_mfma_f32_16x16x32_bf16 v[108:111], v[160:163], v[194:197], v[108:111]
	v_mfma_f32_16x16x32_bf16 v[100:103], v[152:155], v[202:205], v[100:103]
	v_mfma_f32_16x16x32_bf16 v[92:95], v[160:163], v[202:205], v[92:95]
	v_mfma_f32_16x16x32_bf16 v[84:87], v[152:155], v[210:213], v[84:87]
	v_mfma_f32_16x16x32_bf16 v[76:79], v[160:163], v[210:213], v[76:79]
	v_mfma_f32_16x16x32_bf16 v[124:127], v[156:159], v[190:193], v[124:127]
	v_mfma_f32_16x16x32_bf16 v[120:123], v[164:167], v[190:193], v[120:123]
	v_mfma_f32_16x16x32_bf16 v[116:119], v[156:159], v[198:201], v[116:119]
	v_mfma_f32_16x16x32_bf16 v[108:111], v[164:167], v[198:201], v[108:111]
	v_mfma_f32_16x16x32_bf16 v[100:103], v[156:159], v[206:209], v[100:103]
	v_mfma_f32_16x16x32_bf16 v[92:95], v[164:167], v[206:209], v[92:95]
	v_mfma_f32_16x16x32_bf16 v[84:87], v[156:159], v[214:217], v[84:87]
	v_mfma_f32_16x16x32_bf16 v[76:79], v[164:167], v[214:217], v[76:79]
	s_setprio 0
	s_setprio 1
	v_mfma_f32_16x16x32_bf16 v[112:115], v[168:171], v[186:189], v[112:115]
	v_mfma_f32_16x16x32_bf16 v[104:107], v[176:179], v[186:189], v[104:107]
	v_mfma_f32_16x16x32_bf16 v[96:99], v[168:171], v[194:197], v[96:99]
	v_mfma_f32_16x16x32_bf16 v[88:91], v[176:179], v[194:197], v[88:91]
	v_mfma_f32_16x16x32_bf16 v[80:83], v[168:171], v[202:205], v[80:83]
	v_mfma_f32_16x16x32_bf16 v[72:75], v[176:179], v[202:205], v[72:75]
	v_mfma_f32_16x16x32_bf16 v[68:71], v[168:171], v[210:213], v[68:71]
	v_mfma_f32_16x16x32_bf16 v[64:67], v[176:179], v[210:213], v[64:67]
	v_mfma_f32_16x16x32_bf16 v[112:115], v[172:175], v[190:193], v[112:115]
	v_mfma_f32_16x16x32_bf16 v[104:107], v[180:183], v[190:193], v[104:107]
	v_mfma_f32_16x16x32_bf16 v[96:99], v[172:175], v[198:201], v[96:99]
	v_mfma_f32_16x16x32_bf16 v[88:91], v[180:183], v[198:201], v[88:91]
	v_mfma_f32_16x16x32_bf16 v[80:83], v[172:175], v[206:209], v[80:83]
	v_mfma_f32_16x16x32_bf16 v[72:75], v[180:183], v[206:209], v[72:75]
	v_mfma_f32_16x16x32_bf16 v[68:71], v[172:175], v[214:217], v[68:71]
	v_mfma_f32_16x16x32_bf16 v[64:67], v[180:183], v[214:217], v[64:67]
	s_setprio 0
	s_barrier
; #define PG8_STAGE(bufoff, gbase, voff) do { _Pragma("unroll") for (int _i = 0; _i < 2; ++_i) \
;         __builtin_amdgcn_global_load_lds((const unsigned*)((const char*)(gbase) + (voff)[_i]), (PG8_LAS unsigned*)(lds + (bufoff) + ldsw + _i * 8192), 16, 0, 0); } while (0)
; #define PG8_LDA(dst, b, h) do { _Pragma("unroll") for (int m = 0; m < 4; ++m) _Pragma("unroll") for (int k = 0; k < 2; ++k) dst[m][k] = *(const PG8_LAS bf16x8*)(lds + PG8_SA(b, h) + aoff + m * 2048 + k * 1024); } while (0)
; #define PG8_MMA(ai, bj, At, Bt) do { __builtin_amdgcn_s_setprio(1); _Pragma("unroll") for (int m = 0; m < 4; ++m) _Pragma("unroll") for (int n = 0; n < 2; ++n) _Pragma("unroll") for (int k = 0; k < 2; ++k) \
;         acc[ai][bj][m][n] = __builtin_amdgcn_mfma_f32_16x16x32_bf16(Bt[n][k], At[m][k], acc[ai][bj][m][n], 0, 0, 0); __builtin_amdgcn_s_setprio(0); } while (0)
; #define PG8_WAIT_V(n) asm volatile("s_waitcnt vmcnt(" #n ")" ::: "memory")
; #define PG8_WAIT_L(n) asm volatile("s_waitcnt lgkmcnt(" #n ")" ::: "memory")
; #define PG8_BAR __builtin_amdgcn_s_barrier()
; #define PG8_SCHED __builtin_amdgcn_sched_barrier(0)
; template <class Epi, class Sched, bool ALIGN_EPI = false, bool SP2 = false>
; __device__ __forceinline__ void gemm_phase(PG8_LAS unsigned char* lds, const Gemm g, const Sched& S, const Epi& E) {
;     ...
;         for (int t = 0; t < nt; t += 2) {
;             const bool last = (t == nt - 2);
;             const char* a1 = cA + (size_t)(t + 1) * kstep;
;             const char* a2 = last ? nA : cA + (size_t)(t + 2) * kstep; const char* b2 = last ? nB : cB + (size_t)(t + 2) * kstep;
;     ...
;             PG8_LDA(At, 1, 1); PG8_STAGE(PG8_SB(1, 0), b3, voffB); PG8_STAGE(PG8_SB(1, 1), b3 + hstep, voffB); PG8_STAGE(PG8_SA(1, 0), a3, voffA);
;             PG8_WAIT_V(8); PG8_WAIT_L(0); PG8_BAR; PG8_MMA(1, 0, At, B0); PG8_MMA(1, 1, At, B1); PG8_BAR; PG8_SCHED;
	s_add_i32 s36, s62, s42
	v_lshl_add_u64 v[144:145], v[144:145], 0, s[10:11]
	s_mov_b32 m0, s36
	ds_read_b128 v[186:189], v151 offset:49152
	ds_read_b128 v[190:193], v151 offset:50176
	ds_read_b128 v[194:197], v151 offset:51200
	ds_read_b128 v[198:201], v151 offset:52224
	ds_read_b128 v[202:205], v151 offset:53248
	ds_read_b128 v[206:209], v151 offset:54272
	ds_read_b128 v[210:213], v151 offset:55296
	ds_read_b128 v[214:217], v151 offset:56320
	global_load_lds_dwordx4 v[144:145], off
	s_add_i32 m0, s36, 0x2000
	s_add_u32 s34, s34, 0x40080
	v_lshl_add_u64 v[144:145], v[218:219], 0, s[10:11]
	s_addc_u32 s35, s35, 0
	s_add_i32 s36, s63, s42
	global_load_lds_dwordx4 v[144:145], off
	v_lshl_add_u64 v[144:145], s[34:35], 0, v[130:131]
	s_mov_b32 m0, s36
	s_nop 0
	global_load_lds_dwordx4 v[144:145], off
	v_lshl_add_u64 v[144:145], s[34:35], 0, v[134:135]
	s_add_i32 m0, s36, 0x2000
	s_nop 0
	global_load_lds_dwordx4 v[144:145], off
	v_lshl_add_u64 v[144:145], v[220:221], 0, s[10:11]
	s_mov_b32 m0, s47
	s_nop 0
	global_load_lds_dwordx4 v[144:145], off
	v_lshl_add_u64 v[144:145], v[222:223], 0, s[10:11]
	s_mov_b32 m0, s48
	s_nop 0
	global_load_lds_dwordx4 v[144:145], off
	s_waitcnt vmcnt(6)
	s_waitcnt lgkmcnt(0)
	s_barrier
	s_setprio 1
	s_waitcnt lgkmcnt(0)
	v_mfma_f32_16x16x32_bf16 v[60:63], v[152:155], v[186:189], v[60:63]
	v_mfma_f32_16x16x32_bf16 v[56:59], v[160:163], v[186:189], v[56:59]
	v_mfma_f32_16x16x32_bf16 v[52:55], v[152:155], v[194:197], v[52:55]
	v_mfma_f32_16x16x32_bf16 v[44:47], v[160:163], v[194:197], v[44:47]
	v_mfma_f32_16x16x32_bf16 v[36:39], v[152:155], v[202:205], v[36:39]
	v_mfma_f32_16x16x32_bf16 v[28:31], v[160:163], v[202:205], v[28:31]
	v_mfma_f32_16x16x32_bf16 v[20:23], v[152:155], v[210:213], v[20:23]
	v_mfma_f32_16x16x32_bf16 v[12:15], v[160:163], v[210:213], v[12:15]
	v_mfma_f32_16x16x32_bf16 v[60:63], v[156:159], v[190:193], v[60:63]
	v_mfma_f32_16x16x32_bf16 v[56:59], v[164:167], v[190:193], v[56:59]
	v_mfma_f32_16x16x32_bf16 v[52:55], v[156:159], v[198:201], v[52:55]
	v_mfma_f32_16x16x32_bf16 v[44:47], v[164:167], v[198:201], v[44:47]
	v_mfma_f32_16x16x32_bf16 v[36:39], v[156:159], v[206:209], v[36:39]
	v_mfma_f32_16x16x32_bf16 v[28:31], v[164:167], v[206:209], v[28:31]
	v_mfma_f32_16x16x32_bf16 v[20:23], v[156:159], v[214:217], v[20:23]
	v_mfma_f32_16x16x32_bf16 v[12:15], v[164:167], v[214:217], v[12:15]
	s_setprio 0
	s_setprio 1
	v_mfma_f32_16x16x32_bf16 v[48:51], v[168:171], v[186:189], v[48:51]
	v_mfma_f32_16x16x32_bf16 v[40:43], v[176:179], v[186:189], v[40:43]
	v_mfma_f32_16x16x32_bf16 v[32:35], v[168:171], v[194:197], v[32:35]
	v_mfma_f32_16x16x32_bf16 v[24:27], v[176:179], v[194:197], v[24:27]
	v_mfma_f32_16x16x32_bf16 v[16:19], v[168:171], v[202:205], v[16:19]
	v_mfma_f32_16x16x32_bf16 v[8:11], v[176:179], v[202:205], v[8:11]
	v_mfma_f32_16x16x32_bf16 v[4:7], v[168:171], v[210:213], v[4:7]
	v_mfma_f32_16x16x32_bf16 v[0:3], v[176:179], v[210:213], v[0:3]
	v_mfma_f32_16x16x32_bf16 v[48:51], v[172:175], v[190:193], v[48:51]
	v_mfma_f32_16x16x32_bf16 v[40:43], v[180:183], v[190:193], v[40:43]
	v_mfma_f32_16x16x32_bf16 v[32:35], v[172:175], v[198:201], v[32:35]
	v_mfma_f32_16x16x32_bf16 v[24:27], v[180:183], v[198:201], v[24:27]
	v_mfma_f32_16x16x32_bf16 v[16:19], v[172:175], v[206:209], v[16:19]
	v_mfma_f32_16x16x32_bf16 v[8:11], v[180:183], v[206:209], v[8:11]
	v_mfma_f32_16x16x32_bf16 v[4:7], v[172:175], v[214:217], v[4:7]
	v_mfma_f32_16x16x32_bf16 v[0:3], v[180:183], v[214:217], v[0:3]
	s_setprio 0
	s_barrier
	s_add_i32 s61, s61, 2
	s_add_u32 s59, s59, 0x100
	s_addc_u32 s60, s60, 0
	s_add_u32 s30, s30, 0x100
	s_addc_u32 s31, s31, 0
	s_cmp_gt_u32 s61, 13
	s_cbranch_scc0 .LBB0_868
	s_and_b64 vcc, exec, s[12:13]
	s_cbranch_vccz .LBB0_871
	s_barrier

; #define PG8_STAGE(bufoff, gbase, voff) do { _Pragma("unroll") for (int _i = 0; _i < 2; ++_i) \
;         __builtin_amdgcn_global_load_lds((const unsigned*)((const char*)(gbase) + (voff)[_i]), (PG8_LAS unsigned*)(lds + (bufoff) + ldsw + _i * 8192), 16, 0, 0); } while (0)
; #define PG8_LDA(dst, b, h) do { _Pragma("unroll") for (int m = 0; m < 4; ++m) _Pragma("unroll") for (int k = 0; k < 2; ++k) dst[m][k] = *(const PG8_LAS bf16x8*)(lds + PG8_SA(b, h) + aoff + m * 2048 + k * 1024); } while (0)
; #define PG8_LDB(dst, b, h) do { _Pragma("unroll") for (int n = 0; n < 2; ++n) _Pragma("unroll") for (int k = 0; k < 2; ++k) dst[n][k] = *(const PG8_LAS bf16x8*)(lds + PG8_SB(b, h) + boff + n * 2048 + k * 1024); } while (0)
; #define PG8_MMA(ai, bj, At, Bt) do { __builtin_amdgcn_s_setprio(1); _Pragma("unroll") for (int m = 0; m < 4; ++m) _Pragma("unroll") for (int n = 0; n < 2; ++n) _Pragma("unroll") for (int k = 0; k < 2; ++k) \
;         acc[ai][bj][m][n] = __builtin_amdgcn_mfma_f32_16x16x32_bf16(Bt[n][k], At[m][k], acc[ai][bj][m][n], 0, 0, 0); __builtin_amdgcn_s_setprio(0); } while (0)
; #define PG8_WAIT_V(n) asm volatile("s_waitcnt vmcnt(" #n ")" ::: "memory")
; #define PG8_WAIT_L(n) asm volatile("s_waitcnt lgkmcnt(" #n ")" ::: "memory")
; #define PG8_BAR __builtin_amdgcn_s_barrier()
; #define PG8_SCHED __builtin_amdgcn_sched_barrier(0)
; template <class Epi, class Sched, bool ALIGN_EPI = false, bool SP2 = false>
; __device__ __forceinline__ void gemm_phase(PG8_LAS unsigned char* lds, const Gemm g, const Sched& S, const Epi& E) {
;     ...
;         for (int t = 0; t < nt; t += 2) {
;             const bool last = (t == nt - 2);
;             const char* a1 = cA + (size_t)(t + 1) * kstep;
;             const char* a2 = last ? nA : cA + (size_t)(t + 2) * kstep; const char* b2 = last ? nB : cB + (size_t)(t + 2) * kstep;
;             const char* a3 = a2 + kstep; const char* b3 = b2 + kstep;
;             if (last && has_next) S.a_ready(nxt);
;             if constexpr (SP2) {
;             PG8_LDB(B0, 0, 0); PG8_LDB(B1, 0, 1); PG8_SCHED; PG8_LDA(At, 0, 0); PG8_STAGE(PG8_SA(1, 1), a1 + hstep, voffA);
;             PG8_WAIT_V(8); PG8_WAIT_L(0); PG8_BAR; PG8_MMA(0, 0, At, B0); PG8_MMA(0, 1, At, B1); PG8_BAR; PG8_SCHED;
;             PG8_LDA(At, 0, 1); PG8_STAGE(PG8_SB(0, 0), b2, voffB); PG8_STAGE(PG8_SB(0, 1), b2 + hstep, voffB); PG8_STAGE(PG8_SA(0, 0), a2, voffA);
.LBB0_937:
	ds_read_b128 v[148:151], v145
	ds_read_b128 v[152:155], v145 offset:1024
	ds_read_b128 v[156:159], v145 offset:2048
	ds_read_b128 v[160:163], v145 offset:3072
	ds_read_b128 v[164:167], v146
	ds_read_b128 v[168:171], v146 offset:1024
	ds_read_b128 v[172:175], v146 offset:2048
	ds_read_b128 v[176:179], v146 offset:3072
	s_add_u32 s34, s30, 0xfffc0080
	s_addc_u32 s35, s31, -1
	s_cmp_eq_u32 s60, 12
	s_cselect_b32 s37, s23, s35
	s_cselect_b32 s36, s56, s34
	s_cselect_b32 s35, s21, s59
	s_cselect_b32 s34, s57, s58
	v_lshl_add_u64 v[140:141], s[30:31], 0, v[138:139]
	s_add_i32 m0, s40, 0xc000
	ds_read_b128 v[180:183], v147
	ds_read_b128 v[186:189], v147 offset:1024
	ds_read_b128 v[190:193], v147 offset:2048
	ds_read_b128 v[194:197], v147 offset:3072
	ds_read_b128 v[198:201], v147 offset:4096
	ds_read_b128 v[202:205], v147 offset:5120
	ds_read_b128 v[206:209], v147 offset:6144
	ds_read_b128 v[210:213], v147 offset:7168
	global_load_lds_dwordx4 v[140:141], off
	v_lshl_add_u64 v[140:141], s[30:31], 0, v[136:137]
	s_add_i32 m0, s40, 0xe000
	s_nop 0
	global_load_lds_dwordx4 v[140:141], off
	s_waitcnt vmcnt(6)
	s_waitcnt lgkmcnt(0)
	s_barrier
	s_setprio 1
	s_waitcnt lgkmcnt(0)
	v_mfma_f32_16x16x32_bf16 v[124:127], v[148:151], v[180:183], v[124:127]
	v_mfma_f32_16x16x32_bf16 v[120:123], v[156:159], v[180:183], v[120:123]
	v_mfma_f32_16x16x32_bf16 v[116:119], v[148:151], v[190:193], v[116:119]
	v_mfma_f32_16x16x32_bf16 v[108:111], v[156:159], v[190:193], v[108:111]
	v_mfma_f32_16x16x32_bf16 v[100:103], v[148:151], v[198:201], v[100:103]
	v_mfma_f32_16x16x32_bf16 v[92:95], v[156:159], v[198:201], v[92:95]
	v_mfma_f32_16x16x32_bf16 v[84:87], v[148:151], v[206:209], v[84:87]
	v_mfma_f32_16x16x32_bf16 v[76:79], v[156:159], v[206:209], v[76:79]
	v_mfma_f32_16x16x32_bf16 v[124:127], v[152:155], v[186:189], v[124:127]
	v_mfma_f32_16x16x32_bf16 v[120:123], v[160:163], v[186:189], v[120:123]
	v_mfma_f32_16x16x32_bf16 v[116:119], v[152:155], v[194:197], v[116:119]
	v_mfma_f32_16x16x32_bf16 v[108:111], v[160:163], v[194:197], v[108:111]
	v_mfma_f32_16x16x32_bf16 v[100:103], v[152:155], v[202:205], v[100:103]
	v_mfma_f32_16x16x32_bf16 v[92:95], v[160:163], v[202:205], v[92:95]
	v_mfma_f32_16x16x32_bf16 v[84:87], v[152:155], v[210:213], v[84:87]
	v_mfma_f32_16x16x32_bf16 v[76:79], v[160:163], v[210:213], v[76:79]
	s_setprio 0
	s_setprio 1
	v_mfma_f32_16x16x32_bf16 v[112:115], v[164:167], v[180:183], v[112:115]
	v_mfma_f32_16x16x32_bf16 v[104:107], v[172:175], v[180:183], v[104:107]
	v_mfma_f32_16x16x32_bf16 v[96:99], v[164:167], v[190:193], v[96:99]
	v_mfma_f32_16x16x32_bf16 v[88:91], v[172:175], v[190:193], v[88:91]
	v_mfma_f32_16x16x32_bf16 v[80:83], v[164:167], v[198:201], v[80:83]
	v_mfma_f32_16x16x32_bf16 v[72:75], v[172:175], v[198:201], v[72:75]
	v_mfma_f32_16x16x32_bf16 v[68:71], v[164:167], v[206:209], v[68:71]
	v_mfma_f32_16x16x32_bf16 v[64:67], v[172:175], v[206:209], v[64:67]
	v_mfma_f32_16x16x32_bf16 v[112:115], v[168:171], v[186:189], v[112:115]
	v_mfma_f32_16x16x32_bf16 v[104:107], v[176:179], v[186:189], v[104:107]
	v_mfma_f32_16x16x32_bf16 v[96:99], v[168:171], v[194:197], v[96:99]
	v_mfma_f32_16x16x32_bf16 v[88:91], v[176:179], v[194:197], v[88:91]
	v_mfma_f32_16x16x32_bf16 v[80:83], v[168:171], v[202:205], v[80:83]
	v_mfma_f32_16x16x32_bf16 v[72:75], v[176:179], v[202:205], v[72:75]
	v_mfma_f32_16x16x32_bf16 v[68:71], v[168:171], v[210:213], v[68:71]
	v_mfma_f32_16x16x32_bf16 v[64:67], v[176:179], v[210:213], v[64:67]
	s_setprio 0
	s_barrier
	s_add_i32 s61, s48, s39
	v_lshl_add_u64 v[140:141], s[34:35], 0, v[130:131]
	s_mov_b32 m0, s61
	ds_read_b128 v[180:183], v147 offset:16384
	ds_read_b128 v[186:189], v147 offset:17408
	ds_read_b128 v[190:193], v147 offset:18432
	ds_read_b128 v[194:197], v147 offset:19456
	ds_read_b128 v[198:201], v147 offset:20480
	ds_read_b128 v[202:205], v147 offset:21504
	ds_read_b128 v[206:209], v147 offset:22528
	ds_read_b128 v[210:213], v147 offset:23552
	global_load_lds_dwordx4 v[140:141], off
	s_add_i32 m0, s61, 0x2000
	s_add_u32 s62, s34, 0x40000
	v_lshl_add_u64 v[214:215], s[34:35], 0, v[134:135]
	s_addc_u32 s63, s35, 0
	s_add_i32 s61, s93, s39
	global_load_lds_dwordx4 v[214:215], off
	v_lshl_add_u64 v[216:217], s[62:63], 0, v[130:131]
	s_mov_b32 m0, s61
	v_lshl_add_u64 v[218:219], s[36:37], 0, v[132:133]
	global_load_lds_dwordx4 v[216:217], off
	v_lshl_add_u64 v[216:217], s[62:63], 0, v[134:135]
	s_add_i32 m0, s61, 0x2000
	s_nop 0
	global_load_lds_dwordx4 v[216:217], off
	v_lshl_add_u64 v[216:217], s[36:37], 0, v[128:129]
	s_mov_b32 m0, s40
	s_nop 0
	global_load_lds_dwordx4 v[216:217], off
	s_mov_b32 m0, s41
	s_nop 0
	global_load_lds_dwordx4 v[218:219], off
	s_waitcnt vmcnt(6)
	s_waitcnt lgkmcnt(0)
	s_barrier
; #define PG8_STAGE(bufoff, gbase, voff) do { _Pragma("unroll") for (int _i = 0; _i < 2; ++_i) \
;         __builtin_amdgcn_global_load_lds((const unsigned*)((const char*)(gbase) + (voff)[_i]), (PG8_LAS unsigned*)(lds + (bufoff) + ldsw + _i * 8192), 16, 0, 0); } while (0)
; #define PG8_LDA(dst, b, h) do { _Pragma("unroll") for (int m = 0; m < 4; ++m) _Pragma("unroll") for (int k = 0; k < 2; ++k) dst[m][k] = *(const PG8_LAS bf16x8*)(lds + PG8_SA(b, h) + aoff + m * 2048 + k * 1024); } while (0)
; #define PG8_LDB(dst, b, h) do { _Pragma("unroll") for (int n = 0; n < 2; ++n) _Pragma("unroll") for (int k = 0; k < 2; ++k) dst[n][k] = *(const PG8_LAS bf16x8*)(lds + PG8_SB(b, h) + boff + n * 2048 + k * 1024); } while (0)
; #define PG8_MMA(ai, bj, At, Bt) do { __builtin_amdgcn_s_setprio(1); _Pragma("unroll") for (int m = 0; m < 4; ++m) _Pragma("unroll") for (int n = 0; n < 2; ++n) _Pragma("unroll") for (int k = 0; k < 2; ++k) \
;         acc[ai][bj][m][n] = __builtin_amdgcn_mfma_f32_16x16x32_bf16(Bt[n][k], At[m][k], acc[ai][bj][m][n], 0, 0, 0); __builtin_amdgcn_s_setprio(0); } while (0)
; #define PG8_WAIT_V(n) asm volatile("s_waitcnt vmcnt(" #n ")" ::: "memory")
; #define PG8_WAIT_L(n) asm volatile("s_waitcnt lgkmcnt(" #n ")" ::: "memory")
; #define PG8_BAR __builtin_amdgcn_s_barrier()
; #define PG8_SCHED __builtin_amdgcn_sched_barrier(0)
; template <class Epi, class Sched, bool ALIGN_EPI = false, bool SP2 = false>
; __device__ __forceinline__ void gemm_phase(PG8_LAS unsigned char* lds, const Gemm g, const Sched& S, const Epi& E) {
;     ...
;             PG8_WAIT_V(8); PG8_WAIT_L(0); PG8_BAR; PG8_MMA(1, 0, At, B0); PG8_MMA(1, 1, At, B1); PG8_BAR; PG8_SCHED;
;             PG8_LDB(B0, 1, 0); PG8_LDB(B1, 1, 1); PG8_SCHED; PG8_LDA(At, 1, 0); PG8_STAGE(PG8_SA(0, 1), a2 + hstep, voffA);
;             PG8_WAIT_V(8); PG8_WAIT_L(0); PG8_BAR; PG8_MMA(0, 0, At, B0); PG8_MMA(0, 1, At, B1); PG8_BAR; PG8_SCHED;
	s_setprio 1
	s_waitcnt lgkmcnt(0)
	v_mfma_f32_16x16x32_bf16 v[60:63], v[148:151], v[180:183], v[60:63]
	v_mfma_f32_16x16x32_bf16 v[56:59], v[156:159], v[180:183], v[56:59]
	v_mfma_f32_16x16x32_bf16 v[52:55], v[148:151], v[190:193], v[52:55]
	v_mfma_f32_16x16x32_bf16 v[44:47], v[156:159], v[190:193], v[44:47]
	v_mfma_f32_16x16x32_bf16 v[36:39], v[148:151], v[198:201], v[36:39]
	v_mfma_f32_16x16x32_bf16 v[28:31], v[156:159], v[198:201], v[28:31]
	v_mfma_f32_16x16x32_bf16 v[20:23], v[148:151], v[206:209], v[20:23]
	v_mfma_f32_16x16x32_bf16 v[12:15], v[156:159], v[206:209], v[12:15]
	v_mfma_f32_16x16x32_bf16 v[60:63], v[152:155], v[186:189], v[60:63]
	v_mfma_f32_16x16x32_bf16 v[56:59], v[160:163], v[186:189], v[56:59]
	v_mfma_f32_16x16x32_bf16 v[52:55], v[152:155], v[194:197], v[52:55]
	v_mfma_f32_16x16x32_bf16 v[44:47], v[160:163], v[194:197], v[44:47]
	v_mfma_f32_16x16x32_bf16 v[36:39], v[152:155], v[202:205], v[36:39]
	v_mfma_f32_16x16x32_bf16 v[28:31], v[160:163], v[202:205], v[28:31]
	v_mfma_f32_16x16x32_bf16 v[20:23], v[152:155], v[210:213], v[20:23]
	v_mfma_f32_16x16x32_bf16 v[12:15], v[160:163], v[210:213], v[12:15]
	s_setprio 0
	s_setprio 1
	v_mfma_f32_16x16x32_bf16 v[48:51], v[164:167], v[180:183], v[48:51]
	v_mfma_f32_16x16x32_bf16 v[40:43], v[172:175], v[180:183], v[40:43]
	v_mfma_f32_16x16x32_bf16 v[32:35], v[164:167], v[190:193], v[32:35]
	v_mfma_f32_16x16x32_bf16 v[24:27], v[172:175], v[190:193], v[24:27]
	v_mfma_f32_16x16x32_bf16 v[16:19], v[164:167], v[198:201], v[16:19]
	v_mfma_f32_16x16x32_bf16 v[8:11], v[172:175], v[198:201], v[8:11]
	v_mfma_f32_16x16x32_bf16 v[4:7], v[164:167], v[206:209], v[4:7]
	v_mfma_f32_16x16x32_bf16 v[0:3], v[172:175], v[206:209], v[0:3]
	v_mfma_f32_16x16x32_bf16 v[48:51], v[168:171], v[186:189], v[48:51]
	v_mfma_f32_16x16x32_bf16 v[40:43], v[176:179], v[186:189], v[40:43]
	v_mfma_f32_16x16x32_bf16 v[32:35], v[168:171], v[194:197], v[32:35]
	v_mfma_f32_16x16x32_bf16 v[24:27], v[176:179], v[194:197], v[24:27]
	v_mfma_f32_16x16x32_bf16 v[16:19], v[168:171], v[202:205], v[16:19]
	v_mfma_f32_16x16x32_bf16 v[8:11], v[176:179], v[202:205], v[8:11]
	v_mfma_f32_16x16x32_bf16 v[4:7], v[168:171], v[210:213], v[4:7]
	v_mfma_f32_16x16x32_bf16 v[0:3], v[176:179], v[210:213], v[0:3]
	s_setprio 0
	s_barrier
	s_add_i32 s61, 0, 0x18000
	s_add_i32 s62, 0, 0x1c000
	v_add_u32_e32 v160, s61, v143
	v_add_u32_e32 v176, s62, v143
	ds_read_b128 v[148:151], v160
	ds_read_b128 v[152:155], v160 offset:1024
	ds_read_b128 v[156:159], v160 offset:2048
	ds_read_b128 v[160:163], v160 offset:3072
	ds_read_b128 v[164:167], v176
	ds_read_b128 v[168:171], v176 offset:1024
	ds_read_b128 v[172:175], v176 offset:2048
	ds_read_b128 v[176:179], v176 offset:3072
	s_add_u32 s36, s36, 0x40000
	s_addc_u32 s37, s37, 0
	s_mov_b32 m0, s42
	v_lshl_add_u64 v[220:221], s[36:37], 0, v[128:129]
	ds_read_b128 v[180:183], v147 offset:32768
	ds_read_b128 v[186:189], v147 offset:33792
	ds_read_b128 v[190:193], v147 offset:34816
	ds_read_b128 v[194:197], v147 offset:35840
	ds_read_b128 v[198:201], v147 offset:36864
	ds_read_b128 v[202:205], v147 offset:37888
	ds_read_b128 v[206:209], v147 offset:38912
	ds_read_b128 v[210:213], v147 offset:39936
	global_load_lds_dwordx4 v[220:221], off
	v_lshl_add_u64 v[220:221], s[36:37], 0, v[132:133]
	s_mov_b32 m0, s43
	s_nop 0
	global_load_lds_dwordx4 v[220:221], off
	s_waitcnt vmcnt(6)
	s_waitcnt lgkmcnt(0)
	s_barrier
	s_setprio 1
	s_waitcnt lgkmcnt(0)
	v_mfma_f32_16x16x32_bf16 v[124:127], v[148:151], v[180:183], v[124:127]
	v_mfma_f32_16x16x32_bf16 v[120:123], v[156:159], v[180:183], v[120:123]
	v_mfma_f32_16x16x32_bf16 v[116:119], v[148:151], v[190:193], v[116:119]
	v_mfma_f32_16x16x32_bf16 v[108:111], v[156:159], v[190:193], v[108:111]
	v_mfma_f32_16x16x32_bf16 v[100:103], v[148:151], v[198:201], v[100:103]
	v_mfma_f32_16x16x32_bf16 v[92:95], v[156:159], v[198:201], v[92:95]
	v_mfma_f32_16x16x32_bf16 v[84:87], v[148:151], v[206:209], v[84:87]
	v_mfma_f32_16x16x32_bf16 v[76:79], v[156:159], v[206:209], v[76:79]
	v_mfma_f32_16x16x32_bf16 v[124:127], v[152:155], v[186:189], v[124:127]
	v_mfma_f32_16x16x32_bf16 v[120:123], v[160:163], v[186:189], v[120:123]
	v_mfma_f32_16x16x32_bf16 v[116:119], v[152:155], v[194:197], v[116:119]
	v_mfma_f32_16x16x32_bf16 v[108:111], v[160:163], v[194:197], v[108:111]
	v_mfma_f32_16x16x32_bf16 v[100:103], v[152:155], v[202:205], v[100:103]
	v_mfma_f32_16x16x32_bf16 v[92:95], v[160:163], v[202:205], v[92:95]
	v_mfma_f32_16x16x32_bf16 v[84:87], v[152:155], v[210:213], v[84:87]
	v_mfma_f32_16x16x32_bf16 v[76:79], v[160:163], v[210:213], v[76:79]
	s_setprio 0
	s_setprio 1
	v_mfma_f32_16x16x32_bf16 v[112:115], v[164:167], v[180:183], v[112:115]
	v_mfma_f32_16x16x32_bf16 v[104:107], v[172:175], v[180:183], v[104:107]
	v_mfma_f32_16x16x32_bf16 v[96:99], v[164:167], v[190:193], v[96:99]
	v_mfma_f32_16x16x32_bf16 v[88:91], v[172:175], v[190:193], v[88:91]
	v_mfma_f32_16x16x32_bf16 v[80:83], v[164:167], v[198:201], v[80:83]
	v_mfma_f32_16x16x32_bf16 v[72:75], v[172:175], v[198:201], v[72:75]
	v_mfma_f32_16x16x32_bf16 v[68:71], v[164:167], v[206:209], v[68:71]
	v_mfma_f32_16x16x32_bf16 v[64:67], v[172:175], v[206:209], v[64:67]
	v_mfma_f32_16x16x32_bf16 v[112:115], v[168:171], v[186:189], v[112:115]
	v_mfma_f32_16x16x32_bf16 v[104:107], v[176:179], v[186:189], v[104:107]
	v_mfma_f32_16x16x32_bf16 v[96:99], v[168:171], v[194:197], v[96:99]
	v_mfma_f32_16x16x32_bf16 v[88:91], v[176:179], v[194:197], v[88:91]
	v_mfma_f32_16x16x32_bf16 v[80:83], v[168:171], v[202:205], v[80:83]
	v_mfma_f32_16x16x32_bf16 v[72:75], v[176:179], v[202:205], v[72:75]
	v_mfma_f32_16x16x32_bf16 v[68:71], v[168:171], v[210:213], v[68:71]
	v_mfma_f32_16x16x32_bf16 v[64:67], v[176:179], v[210:213], v[64:67]
	s_setprio 0
	s_barrier
; #define PG8_STAGE(bufoff, gbase, voff) do { _Pragma("unroll") for (int _i = 0; _i < 2; ++_i) \
;         __builtin_amdgcn_global_load_lds((const unsigned*)((const char*)(gbase) + (voff)[_i]), (PG8_LAS unsigned*)(lds + (bufoff) + ldsw + _i * 8192), 16, 0, 0); } while (0)
; #define PG8_LDA(dst, b, h) do { _Pragma("unroll") for (int m = 0; m < 4; ++m) _Pragma("unroll") for (int k = 0; k < 2; ++k) dst[m][k] = *(const PG8_LAS bf16x8*)(lds + PG8_SA(b, h) + aoff + m * 2048 + k * 1024); } while (0)
; #define PG8_MMA(ai, bj, At, Bt) do { __builtin_amdgcn_s_setprio(1); _Pragma("unroll") for (int m = 0; m < 4; ++m) _Pragma("unroll") for (int n = 0; n < 2; ++n) _Pragma("unroll") for (int k = 0; k < 2; ++k) \
;         acc[ai][bj][m][n] = __builtin_amdgcn_mfma_f32_16x16x32_bf16(Bt[n][k], At[m][k], acc[ai][bj][m][n], 0, 0, 0); __builtin_amdgcn_s_setprio(0); } while (0)
; #define PG8_WAIT_V(n) asm volatile("s_waitcnt vmcnt(" #n ")" ::: "memory")
; #define PG8_WAIT_L(n) asm volatile("s_waitcnt lgkmcnt(" #n ")" ::: "memory")
; #define PG8_BAR __builtin_amdgcn_s_barrier()
; #define PG8_SCHED __builtin_amdgcn_sched_barrier(0)
; template <class Epi, class Sched, bool ALIGN_EPI = false, bool SP2 = false>
; __device__ __forceinline__ void gemm_phase(PG8_LAS unsigned char* lds, const Gemm g, const Sched& S, const Epi& E) {
;     ...
;             PG8_LDA(At, 1, 1); PG8_STAGE(PG8_SB(1, 0), b3, voffB); PG8_STAGE(PG8_SB(1, 1), b3 + hstep, voffB); PG8_STAGE(PG8_SA(1, 0), a3, voffA);
;             PG8_WAIT_V(8); PG8_WAIT_L(0); PG8_BAR; PG8_MMA(1, 0, At, B0); PG8_MMA(1, 1, At, B1); PG8_BAR; PG8_SCHED;
;     ...
;         if constexpr (ALIGN_EPI) { if (wr == 0) PG8_BAR; }
	s_add_i32 s36, s61, s39
	v_lshl_add_u64 v[140:141], v[140:141], 0, s[10:11]
	s_mov_b32 m0, s36
	ds_read_b128 v[180:183], v147 offset:49152
	ds_read_b128 v[186:189], v147 offset:50176
	ds_read_b128 v[190:193], v147 offset:51200
	ds_read_b128 v[194:197], v147 offset:52224
	ds_read_b128 v[198:201], v147 offset:53248
	ds_read_b128 v[202:205], v147 offset:54272
	ds_read_b128 v[206:209], v147 offset:55296
	ds_read_b128 v[210:213], v147 offset:56320
	global_load_lds_dwordx4 v[140:141], off
	s_add_i32 m0, s36, 0x2000
	s_add_u32 s34, s34, 0x40080
	v_lshl_add_u64 v[140:141], v[214:215], 0, s[10:11]
	s_addc_u32 s35, s35, 0
	s_add_i32 s36, s62, s39
	global_load_lds_dwordx4 v[140:141], off
	v_lshl_add_u64 v[140:141], s[34:35], 0, v[130:131]
	s_mov_b32 m0, s36
	s_nop 0
	global_load_lds_dwordx4 v[140:141], off
	v_lshl_add_u64 v[140:141], s[34:35], 0, v[134:135]
	s_add_i32 m0, s36, 0x2000
	s_nop 0
	global_load_lds_dwordx4 v[140:141], off
	v_lshl_add_u64 v[140:141], v[216:217], 0, s[10:11]
	s_mov_b32 m0, s44
	s_nop 0
	global_load_lds_dwordx4 v[140:141], off
	v_lshl_add_u64 v[140:141], v[218:219], 0, s[10:11]
	s_mov_b32 m0, s45
	s_nop 0
	global_load_lds_dwordx4 v[140:141], off
	s_waitcnt vmcnt(6)
	s_waitcnt lgkmcnt(0)
	s_barrier
	s_setprio 1
	s_waitcnt lgkmcnt(0)
	v_mfma_f32_16x16x32_bf16 v[60:63], v[148:151], v[180:183], v[60:63]
	v_mfma_f32_16x16x32_bf16 v[56:59], v[156:159], v[180:183], v[56:59]
	v_mfma_f32_16x16x32_bf16 v[52:55], v[148:151], v[190:193], v[52:55]
	v_mfma_f32_16x16x32_bf16 v[44:47], v[156:159], v[190:193], v[44:47]
	v_mfma_f32_16x16x32_bf16 v[36:39], v[148:151], v[198:201], v[36:39]
	v_mfma_f32_16x16x32_bf16 v[28:31], v[156:159], v[198:201], v[28:31]
	v_mfma_f32_16x16x32_bf16 v[20:23], v[148:151], v[206:209], v[20:23]
	v_mfma_f32_16x16x32_bf16 v[12:15], v[156:159], v[206:209], v[12:15]
	v_mfma_f32_16x16x32_bf16 v[60:63], v[152:155], v[186:189], v[60:63]
	v_mfma_f32_16x16x32_bf16 v[56:59], v[160:163], v[186:189], v[56:59]
	v_mfma_f32_16x16x32_bf16 v[52:55], v[152:155], v[194:197], v[52:55]
	v_mfma_f32_16x16x32_bf16 v[44:47], v[160:163], v[194:197], v[44:47]
	v_mfma_f32_16x16x32_bf16 v[36:39], v[152:155], v[202:205], v[36:39]
	v_mfma_f32_16x16x32_bf16 v[28:31], v[160:163], v[202:205], v[28:31]
	v_mfma_f32_16x16x32_bf16 v[20:23], v[152:155], v[210:213], v[20:23]
	v_mfma_f32_16x16x32_bf16 v[12:15], v[160:163], v[210:213], v[12:15]
	s_setprio 0
	s_setprio 1
	v_mfma_f32_16x16x32_bf16 v[48:51], v[164:167], v[180:183], v[48:51]
	v_mfma_f32_16x16x32_bf16 v[40:43], v[172:175], v[180:183], v[40:43]
	v_mfma_f32_16x16x32_bf16 v[32:35], v[164:167], v[190:193], v[32:35]
	v_mfma_f32_16x16x32_bf16 v[24:27], v[172:175], v[190:193], v[24:27]
	v_mfma_f32_16x16x32_bf16 v[16:19], v[164:167], v[198:201], v[16:19]
	v_mfma_f32_16x16x32_bf16 v[8:11], v[172:175], v[198:201], v[8:11]
	v_mfma_f32_16x16x32_bf16 v[4:7], v[164:167], v[206:209], v[4:7]
	v_mfma_f32_16x16x32_bf16 v[0:3], v[172:175], v[206:209], v[0:3]
	v_mfma_f32_16x16x32_bf16 v[48:51], v[168:171], v[186:189], v[48:51]
	v_mfma_f32_16x16x32_bf16 v[40:43], v[176:179], v[186:189], v[40:43]
	v_mfma_f32_16x16x32_bf16 v[32:35], v[168:171], v[194:197], v[32:35]
	v_mfma_f32_16x16x32_bf16 v[24:27], v[176:179], v[194:197], v[24:27]
	v_mfma_f32_16x16x32_bf16 v[16:19], v[168:171], v[202:205], v[16:19]
	v_mfma_f32_16x16x32_bf16 v[8:11], v[176:179], v[202:205], v[8:11]
	v_mfma_f32_16x16x32_bf16 v[4:7], v[168:171], v[210:213], v[4:7]
	v_mfma_f32_16x16x32_bf16 v[0:3], v[176:179], v[210:213], v[0:3]
	s_setprio 0
	s_barrier
	s_add_i32 s60, s60, 2
	s_add_u32 s58, s58, 0x100
	s_addc_u32 s59, s59, 0
	s_add_u32 s30, s30, 0x100
	s_addc_u32 s31, s31, 0
	s_cmp_gt_u32 s60, 13
	s_cbranch_scc0 .LBB0_937
	s_and_b64 vcc, exec, s[12:13]
	s_cbranch_vccz .LBB0_940
	s_barrier

; #define PG8_STAGE(bufoff, gbase, voff) do { _Pragma("unroll") for (int _i = 0; _i < 2; ++_i) \
;         __builtin_amdgcn_global_load_lds((const unsigned*)((const char*)(gbase) + (voff)[_i]), (PG8_LAS unsigned*)(lds + (bufoff) + ldsw + _i * 8192), 16, 0, 0); } while (0)
; #define PG8_LDA(dst, b, h) do { _Pragma("unroll") for (int m = 0; m < 4; ++m) _Pragma("unroll") for (int k = 0; k < 2; ++k) dst[m][k] = *(const PG8_LAS bf16x8*)(lds + PG8_SA(b, h) + aoff + m * 2048 + k * 1024); } while (0)
; #define PG8_LDB(dst, b, h) do { _Pragma("unroll") for (int n = 0; n < 2; ++n) _Pragma("unroll") for (int k = 0; k < 2; ++k) dst[n][k] = *(const PG8_LAS bf16x8*)(lds + PG8_SB(b, h) + boff + n * 2048 + k * 1024); } while (0)
; #define PG8_MMA(ai, bj, At, Bt) do { __builtin_amdgcn_s_setprio(1); _Pragma("unroll") for (int m = 0; m < 4; ++m) _Pragma("unroll") for (int n = 0; n < 2; ++n) _Pragma("unroll") for (int k = 0; k < 2; ++k) \
;         acc[ai][bj][m][n] = __builtin_amdgcn_mfma_f32_16x16x32_bf16(Bt[n][k], At[m][k], acc[ai][bj][m][n], 0, 0, 0); __builtin_amdgcn_s_setprio(0); } while (0)
; #define PG8_WAIT_V(n) asm volatile("s_waitcnt vmcnt(" #n ")" ::: "memory")
; #define PG8_WAIT_L(n) asm volatile("s_waitcnt lgkmcnt(" #n ")" ::: "memory")
; template <class Epi, class Sched, bool ALIGN_EPI = false, bool SP2 = false>
; __device__ __forceinline__ void gemm_phase(PG8_LAS unsigned char* lds, const Gemm g, const Sched& S, const Epi& E) {
;     ...
;             const bool last = (t == nt - 2);
;             const char* a1 = cA + (size_t)(t + 1) * kstep;
;             const char* a2 = last ? nA : cA + (size_t)(t + 2) * kstep; const char* b2 = last ? nB : cB + (size_t)(t + 2) * kstep;
;             const char* a3 = a2 + kstep; const char* b3 = b2 + kstep;
;             if (last && has_next) S.a_ready(nxt);
;             if constexpr (SP2) {
;             PG8_LDB(B0, 0, 0); PG8_LDB(B1, 0, 1); PG8_SCHED; PG8_LDA(At, 0, 0); PG8_STAGE(PG8_SA(1, 1), a1 + hstep, voffA);
;             PG8_WAIT_V(8); PG8_WAIT_L(0); PG8_BAR; PG8_MMA(0, 0, At, B0); PG8_MMA(0, 1, At, B1); PG8_BAR; PG8_SCHED;
;             PG8_LDA(At, 0, 1); PG8_STAGE(PG8_SB(0, 0), b2, voffB); PG8_STAGE(PG8_SB(0, 1), b2 + hstep, voffB); PG8_STAGE(PG8_SA(0, 0), a2, voffA);
;             PG8_WAIT_V(8); PG8_WAIT_L(0); PG8_BAR; PG8_MMA(1, 0, At, B0); PG8_MMA(1, 1, At, B1); PG8_BAR; PG8_SCHED;
.LBB0_1017:
	ds_read_b128 v[144:147], v151
	ds_read_b128 v[154:157], v151 offset:1024
	ds_read_b128 v[158:161], v151 offset:2048
	ds_read_b128 v[162:165], v151 offset:3072
	ds_read_b128 v[166:169], v152
	ds_read_b128 v[170:173], v152 offset:1024
	ds_read_b128 v[174:177], v152 offset:2048
	ds_read_b128 v[178:181], v152 offset:3072
	s_add_u32 s24, s22, 0xfffc0080
	s_addc_u32 s25, s23, -1
	s_cmp_eq_u32 s50, 12
	s_cselect_b32 s27, s15, s25
	s_cselect_b32 s26, s46, s24
	s_cselect_b32 s25, s13, s49
	s_cselect_b32 s24, s47, s48
	v_lshl_add_u64 v[182:183], s[22:23], 0, v[138:139]
	s_add_i32 m0, s21, 0xc000
	ds_read_b128 v[186:189], v153
	ds_read_b128 v[190:193], v153 offset:1024
	ds_read_b128 v[194:197], v153 offset:2048
	ds_read_b128 v[198:201], v153 offset:3072
	ds_read_b128 v[202:205], v153 offset:4096
	ds_read_b128 v[206:209], v153 offset:5120
	ds_read_b128 v[210:213], v153 offset:6144
	ds_read_b128 v[214:217], v153 offset:7168
	global_load_lds_dwordx4 v[182:183], off
	v_lshl_add_u64 v[182:183], s[22:23], 0, v[136:137]
	s_add_i32 m0, s21, 0xe000
	s_nop 0
	global_load_lds_dwordx4 v[182:183], off
	s_waitcnt vmcnt(6)
	s_waitcnt lgkmcnt(0)
	s_barrier
	s_setprio 1
	s_waitcnt lgkmcnt(0)
	v_mfma_f32_16x16x32_bf16 v[124:127], v[144:147], v[186:189], v[124:127]
	v_mfma_f32_16x16x32_bf16 v[116:119], v[158:161], v[186:189], v[116:119]
	v_mfma_f32_16x16x32_bf16 v[108:111], v[144:147], v[194:197], v[108:111]
	v_mfma_f32_16x16x32_bf16 v[100:103], v[158:161], v[194:197], v[100:103]
	v_mfma_f32_16x16x32_bf16 v[92:95], v[144:147], v[202:205], v[92:95]
	v_mfma_f32_16x16x32_bf16 v[84:87], v[158:161], v[202:205], v[84:87]
	v_mfma_f32_16x16x32_bf16 v[76:79], v[144:147], v[210:213], v[76:79]
	v_mfma_f32_16x16x32_bf16 v[68:71], v[158:161], v[210:213], v[68:71]
	v_mfma_f32_16x16x32_bf16 v[124:127], v[154:157], v[190:193], v[124:127]
	v_mfma_f32_16x16x32_bf16 v[116:119], v[162:165], v[190:193], v[116:119]
	v_mfma_f32_16x16x32_bf16 v[108:111], v[154:157], v[198:201], v[108:111]
	v_mfma_f32_16x16x32_bf16 v[100:103], v[162:165], v[198:201], v[100:103]
	v_mfma_f32_16x16x32_bf16 v[92:95], v[154:157], v[206:209], v[92:95]
	v_mfma_f32_16x16x32_bf16 v[84:87], v[162:165], v[206:209], v[84:87]
	v_mfma_f32_16x16x32_bf16 v[76:79], v[154:157], v[214:217], v[76:79]
	v_mfma_f32_16x16x32_bf16 v[68:71], v[162:165], v[214:217], v[68:71]
	s_setprio 0
	s_setprio 1
	v_mfma_f32_16x16x32_bf16 v[120:123], v[166:169], v[186:189], v[120:123]
	v_mfma_f32_16x16x32_bf16 v[112:115], v[174:177], v[186:189], v[112:115]
	v_mfma_f32_16x16x32_bf16 v[104:107], v[166:169], v[194:197], v[104:107]
	v_mfma_f32_16x16x32_bf16 v[96:99], v[174:177], v[194:197], v[96:99]
	v_mfma_f32_16x16x32_bf16 v[88:91], v[166:169], v[202:205], v[88:91]
	v_mfma_f32_16x16x32_bf16 v[80:83], v[174:177], v[202:205], v[80:83]
	v_mfma_f32_16x16x32_bf16 v[72:75], v[166:169], v[210:213], v[72:75]
	v_mfma_f32_16x16x32_bf16 v[64:67], v[174:177], v[210:213], v[64:67]
	v_mfma_f32_16x16x32_bf16 v[120:123], v[170:173], v[190:193], v[120:123]
	v_mfma_f32_16x16x32_bf16 v[112:115], v[178:181], v[190:193], v[112:115]
	v_mfma_f32_16x16x32_bf16 v[104:107], v[170:173], v[198:201], v[104:107]
	v_mfma_f32_16x16x32_bf16 v[96:99], v[178:181], v[198:201], v[96:99]
	v_mfma_f32_16x16x32_bf16 v[88:91], v[170:173], v[206:209], v[88:91]
	v_mfma_f32_16x16x32_bf16 v[80:83], v[178:181], v[206:209], v[80:83]
	v_mfma_f32_16x16x32_bf16 v[72:75], v[170:173], v[214:217], v[72:75]
	v_mfma_f32_16x16x32_bf16 v[64:67], v[178:181], v[214:217], v[64:67]
	s_setprio 0
	s_barrier
	s_add_i32 s51, s43, s34
	v_lshl_add_u64 v[182:183], s[24:25], 0, v[130:131]
	s_mov_b32 m0, s51
	ds_read_b128 v[186:189], v153 offset:16384
	ds_read_b128 v[190:193], v153 offset:17408
	ds_read_b128 v[194:197], v153 offset:18432
	ds_read_b128 v[198:201], v153 offset:19456
	ds_read_b128 v[202:205], v153 offset:20480
	ds_read_b128 v[206:209], v153 offset:21504
	ds_read_b128 v[210:213], v153 offset:22528
	ds_read_b128 v[214:217], v153 offset:23552
	global_load_lds_dwordx4 v[182:183], off
	s_add_i32 m0, s51, 0x2000
	s_add_u32 s52, s24, 0x40000
	v_lshl_add_u64 v[218:219], s[24:25], 0, v[134:135]
	s_addc_u32 s53, s25, 0
	s_add_i32 s51, s93, s34
	global_load_lds_dwordx4 v[218:219], off
	v_lshl_add_u64 v[220:221], s[52:53], 0, v[130:131]
	s_mov_b32 m0, s51
	v_lshl_add_u64 v[222:223], s[26:27], 0, v[132:133]
	global_load_lds_dwordx4 v[220:221], off
	v_lshl_add_u64 v[220:221], s[52:53], 0, v[134:135]
	s_add_i32 m0, s51, 0x2000
	s_nop 0
	global_load_lds_dwordx4 v[220:221], off
	v_lshl_add_u64 v[220:221], s[26:27], 0, v[128:129]
	s_mov_b32 m0, s21
	s_nop 0
	global_load_lds_dwordx4 v[220:221], off
	s_mov_b32 m0, s35
	s_nop 0
	global_load_lds_dwordx4 v[222:223], off
	s_waitcnt vmcnt(6)
	s_waitcnt lgkmcnt(0)
	s_barrier
; #define PG8_STAGE(bufoff, gbase, voff) do { _Pragma("unroll") for (int _i = 0; _i < 2; ++_i) \
;         __builtin_amdgcn_global_load_lds((const unsigned*)((const char*)(gbase) + (voff)[_i]), (PG8_LAS unsigned*)(lds + (bufoff) + ldsw + _i * 8192), 16, 0, 0); } while (0)
; #define PG8_LDA(dst, b, h) do { _Pragma("unroll") for (int m = 0; m < 4; ++m) _Pragma("unroll") for (int k = 0; k < 2; ++k) dst[m][k] = *(const PG8_LAS bf16x8*)(lds + PG8_SA(b, h) + aoff + m * 2048 + k * 1024); } while (0)
; #define PG8_LDB(dst, b, h) do { _Pragma("unroll") for (int n = 0; n < 2; ++n) _Pragma("unroll") for (int k = 0; k < 2; ++k) dst[n][k] = *(const PG8_LAS bf16x8*)(lds + PG8_SB(b, h) + boff + n * 2048 + k * 1024); } while (0)
; #define PG8_MMA(ai, bj, At, Bt) do { __builtin_amdgcn_s_setprio(1); _Pragma("unroll") for (int m = 0; m < 4; ++m) _Pragma("unroll") for (int n = 0; n < 2; ++n) _Pragma("unroll") for (int k = 0; k < 2; ++k) \
;         acc[ai][bj][m][n] = __builtin_amdgcn_mfma_f32_16x16x32_bf16(Bt[n][k], At[m][k], acc[ai][bj][m][n], 0, 0, 0); __builtin_amdgcn_s_setprio(0); } while (0)
; #define PG8_WAIT_V(n) asm volatile("s_waitcnt vmcnt(" #n ")" ::: "memory")
; #define PG8_WAIT_L(n) asm volatile("s_waitcnt lgkmcnt(" #n ")" ::: "memory")
; #define PG8_BAR __builtin_amdgcn_s_barrier()
; #define PG8_SCHED __builtin_amdgcn_sched_barrier(0)
; template <class Epi, class Sched, bool ALIGN_EPI = false, bool SP2 = false>
; __device__ __forceinline__ void gemm_phase(PG8_LAS unsigned char* lds, const Gemm g, const Sched& S, const Epi& E) {
;     ...
;             PG8_WAIT_V(8); PG8_WAIT_L(0); PG8_BAR; PG8_MMA(1, 0, At, B0); PG8_MMA(1, 1, At, B1); PG8_BAR; PG8_SCHED;
;             PG8_LDB(B0, 1, 0); PG8_LDB(B1, 1, 1); PG8_SCHED; PG8_LDA(At, 1, 0); PG8_STAGE(PG8_SA(0, 1), a2 + hstep, voffA);
;             PG8_WAIT_V(8); PG8_WAIT_L(0); PG8_BAR; PG8_MMA(0, 0, At, B0); PG8_MMA(0, 1, At, B1); PG8_BAR; PG8_SCHED;
	s_setprio 1
	s_waitcnt lgkmcnt(0)
	v_mfma_f32_16x16x32_bf16 v[60:63], v[144:147], v[186:189], v[60:63]
	v_mfma_f32_16x16x32_bf16 v[52:55], v[158:161], v[186:189], v[52:55]
	v_mfma_f32_16x16x32_bf16 v[44:47], v[144:147], v[194:197], v[44:47]
	v_mfma_f32_16x16x32_bf16 v[36:39], v[158:161], v[194:197], v[36:39]
	v_mfma_f32_16x16x32_bf16 v[28:31], v[144:147], v[202:205], v[28:31]
	v_mfma_f32_16x16x32_bf16 v[20:23], v[158:161], v[202:205], v[20:23]
	v_mfma_f32_16x16x32_bf16 v[12:15], v[144:147], v[210:213], v[12:15]
	v_mfma_f32_16x16x32_bf16 v[4:7], v[158:161], v[210:213], v[4:7]
	v_mfma_f32_16x16x32_bf16 v[60:63], v[154:157], v[190:193], v[60:63]
	v_mfma_f32_16x16x32_bf16 v[52:55], v[162:165], v[190:193], v[52:55]
	v_mfma_f32_16x16x32_bf16 v[44:47], v[154:157], v[198:201], v[44:47]
	v_mfma_f32_16x16x32_bf16 v[36:39], v[162:165], v[198:201], v[36:39]
	v_mfma_f32_16x16x32_bf16 v[28:31], v[154:157], v[206:209], v[28:31]
	v_mfma_f32_16x16x32_bf16 v[20:23], v[162:165], v[206:209], v[20:23]
	v_mfma_f32_16x16x32_bf16 v[12:15], v[154:157], v[214:217], v[12:15]
	v_mfma_f32_16x16x32_bf16 v[4:7], v[162:165], v[214:217], v[4:7]
	s_setprio 0
	s_setprio 1
	v_mfma_f32_16x16x32_bf16 v[56:59], v[166:169], v[186:189], v[56:59]
	v_mfma_f32_16x16x32_bf16 v[48:51], v[174:177], v[186:189], v[48:51]
	v_mfma_f32_16x16x32_bf16 v[40:43], v[166:169], v[194:197], v[40:43]
	v_mfma_f32_16x16x32_bf16 v[32:35], v[174:177], v[194:197], v[32:35]
	v_mfma_f32_16x16x32_bf16 v[24:27], v[166:169], v[202:205], v[24:27]
	v_mfma_f32_16x16x32_bf16 v[16:19], v[174:177], v[202:205], v[16:19]
	v_mfma_f32_16x16x32_bf16 v[8:11], v[166:169], v[210:213], v[8:11]
	v_mfma_f32_16x16x32_bf16 v[0:3], v[174:177], v[210:213], v[0:3]
	v_mfma_f32_16x16x32_bf16 v[56:59], v[170:173], v[190:193], v[56:59]
	v_mfma_f32_16x16x32_bf16 v[48:51], v[178:181], v[190:193], v[48:51]
	v_mfma_f32_16x16x32_bf16 v[40:43], v[170:173], v[198:201], v[40:43]
	v_mfma_f32_16x16x32_bf16 v[32:35], v[178:181], v[198:201], v[32:35]
	v_mfma_f32_16x16x32_bf16 v[24:27], v[170:173], v[206:209], v[24:27]
	v_mfma_f32_16x16x32_bf16 v[16:19], v[178:181], v[206:209], v[16:19]
	v_mfma_f32_16x16x32_bf16 v[8:11], v[170:173], v[214:217], v[8:11]
	v_mfma_f32_16x16x32_bf16 v[0:3], v[178:181], v[214:217], v[0:3]
	s_setprio 0
	s_barrier
	s_add_i32 s51, 0, 0x18000
	s_add_i32 s52, 0, 0x1c000
	v_add_u32_e32 v162, s51, v149
	v_add_u32_e32 v178, s52, v149
	ds_read_b128 v[144:147], v162
	ds_read_b128 v[154:157], v162 offset:1024
	ds_read_b128 v[158:161], v162 offset:2048
	ds_read_b128 v[162:165], v162 offset:3072
	ds_read_b128 v[166:169], v178
	ds_read_b128 v[170:173], v178 offset:1024
	ds_read_b128 v[174:177], v178 offset:2048
	ds_read_b128 v[178:181], v178 offset:3072
	s_add_u32 s26, s26, 0x40000
	s_addc_u32 s27, s27, 0
	s_mov_b32 m0, s36
	v_lshl_add_u64 v[224:225], s[26:27], 0, v[128:129]
	ds_read_b128 v[186:189], v153 offset:32768
	ds_read_b128 v[190:193], v153 offset:33792
	ds_read_b128 v[194:197], v153 offset:34816
	ds_read_b128 v[198:201], v153 offset:35840
	ds_read_b128 v[202:205], v153 offset:36864
	ds_read_b128 v[206:209], v153 offset:37888
	ds_read_b128 v[210:213], v153 offset:38912
	ds_read_b128 v[214:217], v153 offset:39936
	global_load_lds_dwordx4 v[224:225], off
	v_lshl_add_u64 v[224:225], s[26:27], 0, v[132:133]
	s_mov_b32 m0, s37
	s_nop 0
	global_load_lds_dwordx4 v[224:225], off
	s_waitcnt vmcnt(6)
	s_waitcnt lgkmcnt(0)
	s_barrier
	s_setprio 1
	s_waitcnt lgkmcnt(0)
	v_mfma_f32_16x16x32_bf16 v[124:127], v[144:147], v[186:189], v[124:127]
	v_mfma_f32_16x16x32_bf16 v[116:119], v[158:161], v[186:189], v[116:119]
	v_mfma_f32_16x16x32_bf16 v[108:111], v[144:147], v[194:197], v[108:111]
	v_mfma_f32_16x16x32_bf16 v[100:103], v[158:161], v[194:197], v[100:103]
	v_mfma_f32_16x16x32_bf16 v[92:95], v[144:147], v[202:205], v[92:95]
	v_mfma_f32_16x16x32_bf16 v[84:87], v[158:161], v[202:205], v[84:87]
	v_mfma_f32_16x16x32_bf16 v[76:79], v[144:147], v[210:213], v[76:79]
	v_mfma_f32_16x16x32_bf16 v[68:71], v[158:161], v[210:213], v[68:71]
	v_mfma_f32_16x16x32_bf16 v[124:127], v[154:157], v[190:193], v[124:127]
	v_mfma_f32_16x16x32_bf16 v[116:119], v[162:165], v[190:193], v[116:119]
	v_mfma_f32_16x16x32_bf16 v[108:111], v[154:157], v[198:201], v[108:111]
	v_mfma_f32_16x16x32_bf16 v[100:103], v[162:165], v[198:201], v[100:103]
	v_mfma_f32_16x16x32_bf16 v[92:95], v[154:157], v[206:209], v[92:95]
	v_mfma_f32_16x16x32_bf16 v[84:87], v[162:165], v[206:209], v[84:87]
	v_mfma_f32_16x16x32_bf16 v[76:79], v[154:157], v[214:217], v[76:79]
	v_mfma_f32_16x16x32_bf16 v[68:71], v[162:165], v[214:217], v[68:71]
	s_setprio 0
	s_setprio 1
	v_mfma_f32_16x16x32_bf16 v[120:123], v[166:169], v[186:189], v[120:123]
	v_mfma_f32_16x16x32_bf16 v[112:115], v[174:177], v[186:189], v[112:115]
	v_mfma_f32_16x16x32_bf16 v[104:107], v[166:169], v[194:197], v[104:107]
	v_mfma_f32_16x16x32_bf16 v[96:99], v[174:177], v[194:197], v[96:99]
	v_mfma_f32_16x16x32_bf16 v[88:91], v[166:169], v[202:205], v[88:91]
	v_mfma_f32_16x16x32_bf16 v[80:83], v[174:177], v[202:205], v[80:83]
	v_mfma_f32_16x16x32_bf16 v[72:75], v[166:169], v[210:213], v[72:75]
	v_mfma_f32_16x16x32_bf16 v[64:67], v[174:177], v[210:213], v[64:67]
	v_mfma_f32_16x16x32_bf16 v[120:123], v[170:173], v[190:193], v[120:123]
	v_mfma_f32_16x16x32_bf16 v[112:115], v[178:181], v[190:193], v[112:115]
	v_mfma_f32_16x16x32_bf16 v[104:107], v[170:173], v[198:201], v[104:107]
	v_mfma_f32_16x16x32_bf16 v[96:99], v[178:181], v[198:201], v[96:99]
	v_mfma_f32_16x16x32_bf16 v[88:91], v[170:173], v[206:209], v[88:91]
	v_mfma_f32_16x16x32_bf16 v[80:83], v[178:181], v[206:209], v[80:83]
	v_mfma_f32_16x16x32_bf16 v[72:75], v[170:173], v[214:217], v[72:75]
	v_mfma_f32_16x16x32_bf16 v[64:67], v[178:181], v[214:217], v[64:67]
	s_setprio 0
	s_barrier
; #define PG8_STAGE(bufoff, gbase, voff) do { _Pragma("unroll") for (int _i = 0; _i < 2; ++_i) \
;         __builtin_amdgcn_global_load_lds((const unsigned*)((const char*)(gbase) + (voff)[_i]), (PG8_LAS unsigned*)(lds + (bufoff) + ldsw + _i * 8192), 16, 0, 0); } while (0)
; #define PG8_LDA(dst, b, h) do { _Pragma("unroll") for (int m = 0; m < 4; ++m) _Pragma("unroll") for (int k = 0; k < 2; ++k) dst[m][k] = *(const PG8_LAS bf16x8*)(lds + PG8_SA(b, h) + aoff + m * 2048 + k * 1024); } while (0)
; #define PG8_MMA(ai, bj, At, Bt) do { __builtin_amdgcn_s_setprio(1); _Pragma("unroll") for (int m = 0; m < 4; ++m) _Pragma("unroll") for (int n = 0; n < 2; ++n) _Pragma("unroll") for (int k = 0; k < 2; ++k) \
;         acc[ai][bj][m][n] = __builtin_amdgcn_mfma_f32_16x16x32_bf16(Bt[n][k], At[m][k], acc[ai][bj][m][n], 0, 0, 0); __builtin_amdgcn_s_setprio(0); } while (0)
; #define PG8_WAIT_V(n) asm volatile("s_waitcnt vmcnt(" #n ")" ::: "memory")
; #define PG8_WAIT_L(n) asm volatile("s_waitcnt lgkmcnt(" #n ")" ::: "memory")
; #define PG8_BAR __builtin_amdgcn_s_barrier()
; #define PG8_SCHED __builtin_amdgcn_sched_barrier(0)
; template <class Epi, class Sched, bool ALIGN_EPI = false, bool SP2 = false>
; __device__ __forceinline__ void gemm_phase(PG8_LAS unsigned char* lds, const Gemm g, const Sched& S, const Epi& E) {
;     ...
;             PG8_LDA(At, 1, 1); PG8_STAGE(PG8_SB(1, 0), b3, voffB); PG8_STAGE(PG8_SB(1, 1), b3 + hstep, voffB); PG8_STAGE(PG8_SA(1, 0), a3, voffA);
;             PG8_WAIT_V(8); PG8_WAIT_L(0); PG8_BAR; PG8_MMA(1, 0, At, B0); PG8_MMA(1, 1, At, B1); PG8_BAR; PG8_SCHED;
;     ...
;         if constexpr (ALIGN_EPI) { if (wr == 0) PG8_BAR; }
	s_add_i32 s26, s51, s34
	v_lshl_add_u64 v[182:183], v[182:183], 0, s[8:9]
	s_mov_b32 m0, s26
	ds_read_b128 v[186:189], v153 offset:49152
	ds_read_b128 v[190:193], v153 offset:50176
	ds_read_b128 v[194:197], v153 offset:51200
	ds_read_b128 v[198:201], v153 offset:52224
	ds_read_b128 v[202:205], v153 offset:53248
	ds_read_b128 v[206:209], v153 offset:54272
	ds_read_b128 v[210:213], v153 offset:55296
	ds_read_b128 v[214:217], v153 offset:56320
	global_load_lds_dwordx4 v[182:183], off
	s_add_i32 m0, s26, 0x2000
	s_add_u32 s24, s24, 0x40080
	v_lshl_add_u64 v[182:183], v[218:219], 0, s[8:9]
	s_addc_u32 s25, s25, 0
	s_add_i32 s26, s52, s34
	global_load_lds_dwordx4 v[182:183], off
	v_lshl_add_u64 v[182:183], s[24:25], 0, v[130:131]
	s_mov_b32 m0, s26
	s_nop 0
	global_load_lds_dwordx4 v[182:183], off
	v_lshl_add_u64 v[182:183], s[24:25], 0, v[134:135]
	s_add_i32 m0, s26, 0x2000
	s_nop 0
	global_load_lds_dwordx4 v[182:183], off
	v_lshl_add_u64 v[182:183], v[220:221], 0, s[8:9]
	s_mov_b32 m0, s39
	s_nop 0
	global_load_lds_dwordx4 v[182:183], off
	v_lshl_add_u64 v[182:183], v[222:223], 0, s[8:9]
	s_mov_b32 m0, s40
	s_nop 0
	global_load_lds_dwordx4 v[182:183], off
	s_waitcnt vmcnt(6)
	s_waitcnt lgkmcnt(0)
	s_barrier
	s_setprio 1
	s_waitcnt lgkmcnt(0)
	v_mfma_f32_16x16x32_bf16 v[60:63], v[144:147], v[186:189], v[60:63]
	v_mfma_f32_16x16x32_bf16 v[52:55], v[158:161], v[186:189], v[52:55]
	v_mfma_f32_16x16x32_bf16 v[44:47], v[144:147], v[194:197], v[44:47]
	v_mfma_f32_16x16x32_bf16 v[36:39], v[158:161], v[194:197], v[36:39]
	v_mfma_f32_16x16x32_bf16 v[28:31], v[144:147], v[202:205], v[28:31]
	v_mfma_f32_16x16x32_bf16 v[20:23], v[158:161], v[202:205], v[20:23]
	v_mfma_f32_16x16x32_bf16 v[12:15], v[144:147], v[210:213], v[12:15]
	v_mfma_f32_16x16x32_bf16 v[4:7], v[158:161], v[210:213], v[4:7]
	v_mfma_f32_16x16x32_bf16 v[60:63], v[154:157], v[190:193], v[60:63]
	v_mfma_f32_16x16x32_bf16 v[52:55], v[162:165], v[190:193], v[52:55]
	v_mfma_f32_16x16x32_bf16 v[44:47], v[154:157], v[198:201], v[44:47]
	v_mfma_f32_16x16x32_bf16 v[36:39], v[162:165], v[198:201], v[36:39]
	v_mfma_f32_16x16x32_bf16 v[28:31], v[154:157], v[206:209], v[28:31]
	v_mfma_f32_16x16x32_bf16 v[20:23], v[162:165], v[206:209], v[20:23]
	v_mfma_f32_16x16x32_bf16 v[12:15], v[154:157], v[214:217], v[12:15]
	v_mfma_f32_16x16x32_bf16 v[4:7], v[162:165], v[214:217], v[4:7]
	s_setprio 0
	s_setprio 1
	v_mfma_f32_16x16x32_bf16 v[56:59], v[166:169], v[186:189], v[56:59]
	v_mfma_f32_16x16x32_bf16 v[48:51], v[174:177], v[186:189], v[48:51]
	v_mfma_f32_16x16x32_bf16 v[40:43], v[166:169], v[194:197], v[40:43]
	v_mfma_f32_16x16x32_bf16 v[32:35], v[174:177], v[194:197], v[32:35]
	v_mfma_f32_16x16x32_bf16 v[24:27], v[166:169], v[202:205], v[24:27]
	v_mfma_f32_16x16x32_bf16 v[16:19], v[174:177], v[202:205], v[16:19]
	v_mfma_f32_16x16x32_bf16 v[8:11], v[166:169], v[210:213], v[8:11]
	v_mfma_f32_16x16x32_bf16 v[0:3], v[174:177], v[210:213], v[0:3]
	v_mfma_f32_16x16x32_bf16 v[56:59], v[170:173], v[190:193], v[56:59]
	v_mfma_f32_16x16x32_bf16 v[48:51], v[178:181], v[190:193], v[48:51]
	v_mfma_f32_16x16x32_bf16 v[40:43], v[170:173], v[198:201], v[40:43]
	v_mfma_f32_16x16x32_bf16 v[32:35], v[178:181], v[198:201], v[32:35]
	v_mfma_f32_16x16x32_bf16 v[24:27], v[170:173], v[206:209], v[24:27]
	v_mfma_f32_16x16x32_bf16 v[16:19], v[178:181], v[206:209], v[16:19]
	v_mfma_f32_16x16x32_bf16 v[8:11], v[170:173], v[214:217], v[8:11]
	v_mfma_f32_16x16x32_bf16 v[0:3], v[178:181], v[214:217], v[0:3]
	s_setprio 0
	s_barrier
	s_add_i32 s50, s50, 2
	s_add_u32 s48, s48, 0x100
	s_addc_u32 s49, s49, 0
	s_add_u32 s22, s22, 0x100
	s_addc_u32 s23, s23, 0
	s_cmp_gt_u32 s50, 13
	s_cbranch_scc0 .LBB0_1017
	s_and_b64 vcc, exec, s[10:11]
	s_cbranch_vccz .LBB0_1020
	s_barrier

; #define PG8_STAGE(bufoff, gbase, voff) do { _Pragma("unroll") for (int _i = 0; _i < 2; ++_i) \
;         __builtin_amdgcn_global_load_lds((const unsigned*)((const char*)(gbase) + (voff)[_i]), (PG8_LAS unsigned*)(lds + (bufoff) + ldsw + _i * 8192), 16, 0, 0); } while (0)
; #define PG8_LDA(dst, b, h) do { _Pragma("unroll") for (int m = 0; m < 4; ++m) _Pragma("unroll") for (int k = 0; k < 2; ++k) dst[m][k] = *(const PG8_LAS bf16x8*)(lds + PG8_SA(b, h) + aoff + m * 2048 + k * 1024); } while (0)
; #define PG8_LDB(dst, b, h) do { _Pragma("unroll") for (int n = 0; n < 2; ++n) _Pragma("unroll") for (int k = 0; k < 2; ++k) dst[n][k] = *(const PG8_LAS bf16x8*)(lds + PG8_SB(b, h) + boff + n * 2048 + k * 1024); } while (0)
; #define PG8_MMA(ai, bj, At, Bt) do { __builtin_amdgcn_s_setprio(1); _Pragma("unroll") for (int m = 0; m < 4; ++m) _Pragma("unroll") for (int n = 0; n < 2; ++n) _Pragma("unroll") for (int k = 0; k < 2; ++k) \
;         acc[ai][bj][m][n] = __builtin_amdgcn_mfma_f32_16x16x32_bf16(Bt[n][k], At[m][k], acc[ai][bj][m][n], 0, 0, 0); __builtin_amdgcn_s_setprio(0); } while (0)
; #define PG8_WAIT_V(n) asm volatile("s_waitcnt vmcnt(" #n ")" ::: "memory")
; #define PG8_WAIT_L(n) asm volatile("s_waitcnt lgkmcnt(" #n ")" ::: "memory")
; template <class Epi, class Sched, bool ALIGN_EPI = false, bool SP2 = false>
; __device__ __forceinline__ void gemm_phase(PG8_LAS unsigned char* lds, const Gemm g, const Sched& S, const Epi& E) {
;     ...
;             const bool last = (t == nt - 2);
;             const char* a1 = cA + (size_t)(t + 1) * kstep;
;             const char* a2 = last ? nA : cA + (size_t)(t + 2) * kstep; const char* b2 = last ? nB : cB + (size_t)(t + 2) * kstep;
;             const char* a3 = a2 + kstep; const char* b3 = b2 + kstep;
;             if (last && has_next) S.a_ready(nxt);
;             if constexpr (SP2) {
;             PG8_LDB(B0, 0, 0); PG8_LDB(B1, 0, 1); PG8_SCHED; PG8_LDA(At, 0, 0); PG8_STAGE(PG8_SA(1, 1), a1 + hstep, voffA);
;             PG8_WAIT_V(8); PG8_WAIT_L(0); PG8_BAR; PG8_MMA(0, 0, At, B0); PG8_MMA(0, 1, At, B1); PG8_BAR; PG8_SCHED;
;             PG8_LDA(At, 0, 1); PG8_STAGE(PG8_SB(0, 0), b2, voffB); PG8_STAGE(PG8_SB(0, 1), b2 + hstep, voffB); PG8_STAGE(PG8_SA(0, 0), a2, voffA);
;             PG8_WAIT_V(8); PG8_WAIT_L(0); PG8_BAR; PG8_MMA(1, 0, At, B0); PG8_MMA(1, 1, At, B1); PG8_BAR; PG8_SCHED;
.LBB0_1089:
	ds_read_b128 v[152:155], v149
	ds_read_b128 v[156:159], v149 offset:1024
	ds_read_b128 v[160:163], v149 offset:2048
	ds_read_b128 v[164:167], v149 offset:3072
	ds_read_b128 v[168:171], v150
	ds_read_b128 v[172:175], v150 offset:1024
	ds_read_b128 v[176:179], v150 offset:2048
	ds_read_b128 v[180:183], v150 offset:3072
	s_add_u32 s24, s22, 0x100
	s_addc_u32 s25, s23, 0
	s_cmp_eq_u32 s57, 40
	s_cselect_b32 s29, s5, s25
	s_cselect_b32 s28, s4, s24
	s_cselect_b32 s27, s21, s56
	s_cselect_b32 s26, s20, s55
	v_lshl_add_u64 v[144:145], s[22:23], 0, v[138:139]
	s_add_i32 m0, s37, 0xc000
	ds_read_b128 v[186:189], v151
	ds_read_b128 v[190:193], v151 offset:1024
	ds_read_b128 v[194:197], v151 offset:2048
	ds_read_b128 v[198:201], v151 offset:3072
	ds_read_b128 v[202:205], v151 offset:4096
	ds_read_b128 v[206:209], v151 offset:5120
	ds_read_b128 v[210:213], v151 offset:6144
	ds_read_b128 v[214:217], v151 offset:7168
	global_load_lds_dwordx4 v[144:145], off
	v_lshl_add_u64 v[144:145], s[22:23], 0, v[136:137]
	s_add_i32 m0, s37, 0xe000
	s_nop 0
	global_load_lds_dwordx4 v[144:145], off
	s_waitcnt vmcnt(6)
	s_waitcnt lgkmcnt(0)
	s_barrier
	s_setprio 1
	s_waitcnt lgkmcnt(0)
	v_mfma_f32_16x16x32_bf16 v[124:127], v[152:155], v[186:189], v[124:127]
	v_mfma_f32_16x16x32_bf16 v[120:123], v[160:163], v[186:189], v[120:123]
	v_mfma_f32_16x16x32_bf16 v[116:119], v[152:155], v[194:197], v[116:119]
	v_mfma_f32_16x16x32_bf16 v[108:111], v[160:163], v[194:197], v[108:111]
	v_mfma_f32_16x16x32_bf16 v[100:103], v[152:155], v[202:205], v[100:103]
	v_mfma_f32_16x16x32_bf16 v[92:95], v[160:163], v[202:205], v[92:95]
	v_mfma_f32_16x16x32_bf16 v[84:87], v[152:155], v[210:213], v[84:87]
	v_mfma_f32_16x16x32_bf16 v[76:79], v[160:163], v[210:213], v[76:79]
	v_mfma_f32_16x16x32_bf16 v[124:127], v[156:159], v[190:193], v[124:127]
	v_mfma_f32_16x16x32_bf16 v[120:123], v[164:167], v[190:193], v[120:123]
	v_mfma_f32_16x16x32_bf16 v[116:119], v[156:159], v[198:201], v[116:119]
	v_mfma_f32_16x16x32_bf16 v[108:111], v[164:167], v[198:201], v[108:111]
	v_mfma_f32_16x16x32_bf16 v[100:103], v[156:159], v[206:209], v[100:103]
	v_mfma_f32_16x16x32_bf16 v[92:95], v[164:167], v[206:209], v[92:95]
	v_mfma_f32_16x16x32_bf16 v[84:87], v[156:159], v[214:217], v[84:87]
	v_mfma_f32_16x16x32_bf16 v[76:79], v[164:167], v[214:217], v[76:79]
	s_setprio 0
	s_setprio 1
	v_mfma_f32_16x16x32_bf16 v[112:115], v[168:171], v[186:189], v[112:115]
	v_mfma_f32_16x16x32_bf16 v[104:107], v[176:179], v[186:189], v[104:107]
	v_mfma_f32_16x16x32_bf16 v[96:99], v[168:171], v[194:197], v[96:99]
	v_mfma_f32_16x16x32_bf16 v[88:91], v[176:179], v[194:197], v[88:91]
	v_mfma_f32_16x16x32_bf16 v[80:83], v[168:171], v[202:205], v[80:83]
	v_mfma_f32_16x16x32_bf16 v[72:75], v[176:179], v[202:205], v[72:75]
	v_mfma_f32_16x16x32_bf16 v[68:71], v[168:171], v[210:213], v[68:71]
	v_mfma_f32_16x16x32_bf16 v[64:67], v[176:179], v[210:213], v[64:67]
	v_mfma_f32_16x16x32_bf16 v[112:115], v[172:175], v[190:193], v[112:115]
	v_mfma_f32_16x16x32_bf16 v[104:107], v[180:183], v[190:193], v[104:107]
	v_mfma_f32_16x16x32_bf16 v[96:99], v[172:175], v[198:201], v[96:99]
	v_mfma_f32_16x16x32_bf16 v[88:91], v[180:183], v[198:201], v[88:91]
	v_mfma_f32_16x16x32_bf16 v[80:83], v[172:175], v[206:209], v[80:83]
	v_mfma_f32_16x16x32_bf16 v[72:75], v[180:183], v[206:209], v[72:75]
	v_mfma_f32_16x16x32_bf16 v[68:71], v[172:175], v[214:217], v[68:71]
	v_mfma_f32_16x16x32_bf16 v[64:67], v[180:183], v[214:217], v[64:67]
	s_setprio 0
	s_barrier
	s_add_i32 s22, s46, s36
	v_lshl_add_u64 v[144:145], s[26:27], 0, v[130:131]
	s_mov_b32 m0, s22
	ds_read_b128 v[186:189], v151 offset:16384
	ds_read_b128 v[190:193], v151 offset:17408
	ds_read_b128 v[194:197], v151 offset:18432
	ds_read_b128 v[198:201], v151 offset:19456
	ds_read_b128 v[202:205], v151 offset:20480
	ds_read_b128 v[206:209], v151 offset:21504
	ds_read_b128 v[210:213], v151 offset:22528
	ds_read_b128 v[214:217], v151 offset:23552
	global_load_lds_dwordx4 v[144:145], off
	s_add_i32 m0, s22, 0x2000
	s_add_u32 s22, s26, 0xb0000
	v_lshl_add_u64 v[218:219], s[26:27], 0, v[134:135]
	s_addc_u32 s23, s27, 0
	s_add_i32 s58, s93, s36
	global_load_lds_dwordx4 v[218:219], off
	v_lshl_add_u64 v[220:221], s[22:23], 0, v[130:131]
	s_mov_b32 m0, s58
	v_lshl_add_u64 v[222:223], s[28:29], 0, v[132:133]
	global_load_lds_dwordx4 v[220:221], off
	v_lshl_add_u64 v[220:221], s[22:23], 0, v[134:135]
	s_add_i32 m0, s58, 0x2000
	s_nop 0
	global_load_lds_dwordx4 v[220:221], off
	v_lshl_add_u64 v[220:221], s[28:29], 0, v[128:129]
	s_mov_b32 m0, s37
	s_nop 0
	global_load_lds_dwordx4 v[220:221], off
	s_mov_b32 m0, s38
	s_nop 0
	global_load_lds_dwordx4 v[222:223], off
	s_waitcnt vmcnt(6)
	s_waitcnt lgkmcnt(0)
	s_barrier
; #define PG8_STAGE(bufoff, gbase, voff) do { _Pragma("unroll") for (int _i = 0; _i < 2; ++_i) \
;         __builtin_amdgcn_global_load_lds((const unsigned*)((const char*)(gbase) + (voff)[_i]), (PG8_LAS unsigned*)(lds + (bufoff) + ldsw + _i * 8192), 16, 0, 0); } while (0)
; #define PG8_LDA(dst, b, h) do { _Pragma("unroll") for (int m = 0; m < 4; ++m) _Pragma("unroll") for (int k = 0; k < 2; ++k) dst[m][k] = *(const PG8_LAS bf16x8*)(lds + PG8_SA(b, h) + aoff + m * 2048 + k * 1024); } while (0)
; #define PG8_LDB(dst, b, h) do { _Pragma("unroll") for (int n = 0; n < 2; ++n) _Pragma("unroll") for (int k = 0; k < 2; ++k) dst[n][k] = *(const PG8_LAS bf16x8*)(lds + PG8_SB(b, h) + boff + n * 2048 + k * 1024); } while (0)
; #define PG8_MMA(ai, bj, At, Bt) do { __builtin_amdgcn_s_setprio(1); _Pragma("unroll") for (int m = 0; m < 4; ++m) _Pragma("unroll") for (int n = 0; n < 2; ++n) _Pragma("unroll") for (int k = 0; k < 2; ++k) \
;         acc[ai][bj][m][n] = __builtin_amdgcn_mfma_f32_16x16x32_bf16(Bt[n][k], At[m][k], acc[ai][bj][m][n], 0, 0, 0); __builtin_amdgcn_s_setprio(0); } while (0)
; #define PG8_WAIT_V(n) asm volatile("s_waitcnt vmcnt(" #n ")" ::: "memory")
; #define PG8_WAIT_L(n) asm volatile("s_waitcnt lgkmcnt(" #n ")" ::: "memory")
; #define PG8_BAR __builtin_amdgcn_s_barrier()
; #define PG8_SCHED __builtin_amdgcn_sched_barrier(0)
; template <class Epi, class Sched, bool ALIGN_EPI = false, bool SP2 = false>
; __device__ __forceinline__ void gemm_phase(PG8_LAS unsigned char* lds, const Gemm g, const Sched& S, const Epi& E) {
;     ...
;             PG8_WAIT_V(8); PG8_WAIT_L(0); PG8_BAR; PG8_MMA(1, 0, At, B0); PG8_MMA(1, 1, At, B1); PG8_BAR; PG8_SCHED;
;             PG8_LDB(B0, 1, 0); PG8_LDB(B1, 1, 1); PG8_SCHED; PG8_LDA(At, 1, 0); PG8_STAGE(PG8_SA(0, 1), a2 + hstep, voffA);
;             PG8_WAIT_V(8); PG8_WAIT_L(0); PG8_BAR; PG8_MMA(0, 0, At, B0); PG8_MMA(0, 1, At, B1); PG8_BAR; PG8_SCHED;
	s_setprio 1
	s_waitcnt lgkmcnt(0)
	v_mfma_f32_16x16x32_bf16 v[60:63], v[152:155], v[186:189], v[60:63]
	v_mfma_f32_16x16x32_bf16 v[56:59], v[160:163], v[186:189], v[56:59]
	v_mfma_f32_16x16x32_bf16 v[52:55], v[152:155], v[194:197], v[52:55]
	v_mfma_f32_16x16x32_bf16 v[44:47], v[160:163], v[194:197], v[44:47]
	v_mfma_f32_16x16x32_bf16 v[36:39], v[152:155], v[202:205], v[36:39]
	v_mfma_f32_16x16x32_bf16 v[28:31], v[160:163], v[202:205], v[28:31]
	v_mfma_f32_16x16x32_bf16 v[20:23], v[152:155], v[210:213], v[20:23]
	v_mfma_f32_16x16x32_bf16 v[12:15], v[160:163], v[210:213], v[12:15]
	v_mfma_f32_16x16x32_bf16 v[60:63], v[156:159], v[190:193], v[60:63]
	v_mfma_f32_16x16x32_bf16 v[56:59], v[164:167], v[190:193], v[56:59]
	v_mfma_f32_16x16x32_bf16 v[52:55], v[156:159], v[198:201], v[52:55]
	v_mfma_f32_16x16x32_bf16 v[44:47], v[164:167], v[198:201], v[44:47]
	v_mfma_f32_16x16x32_bf16 v[36:39], v[156:159], v[206:209], v[36:39]
	v_mfma_f32_16x16x32_bf16 v[28:31], v[164:167], v[206:209], v[28:31]
	v_mfma_f32_16x16x32_bf16 v[20:23], v[156:159], v[214:217], v[20:23]
	v_mfma_f32_16x16x32_bf16 v[12:15], v[164:167], v[214:217], v[12:15]
	s_setprio 0
	s_setprio 1
	v_mfma_f32_16x16x32_bf16 v[48:51], v[168:171], v[186:189], v[48:51]
	v_mfma_f32_16x16x32_bf16 v[40:43], v[176:179], v[186:189], v[40:43]
	v_mfma_f32_16x16x32_bf16 v[32:35], v[168:171], v[194:197], v[32:35]
	v_mfma_f32_16x16x32_bf16 v[24:27], v[176:179], v[194:197], v[24:27]
	v_mfma_f32_16x16x32_bf16 v[16:19], v[168:171], v[202:205], v[16:19]
	v_mfma_f32_16x16x32_bf16 v[8:11], v[176:179], v[202:205], v[8:11]
	v_mfma_f32_16x16x32_bf16 v[4:7], v[168:171], v[210:213], v[4:7]
	v_mfma_f32_16x16x32_bf16 v[0:3], v[176:179], v[210:213], v[0:3]
	v_mfma_f32_16x16x32_bf16 v[48:51], v[172:175], v[190:193], v[48:51]
	v_mfma_f32_16x16x32_bf16 v[40:43], v[180:183], v[190:193], v[40:43]
	v_mfma_f32_16x16x32_bf16 v[32:35], v[172:175], v[198:201], v[32:35]
	v_mfma_f32_16x16x32_bf16 v[24:27], v[180:183], v[198:201], v[24:27]
	v_mfma_f32_16x16x32_bf16 v[16:19], v[172:175], v[206:209], v[16:19]
	v_mfma_f32_16x16x32_bf16 v[8:11], v[180:183], v[206:209], v[8:11]
	v_mfma_f32_16x16x32_bf16 v[4:7], v[172:175], v[214:217], v[4:7]
	v_mfma_f32_16x16x32_bf16 v[0:3], v[180:183], v[214:217], v[0:3]
	s_setprio 0
	s_barrier
	s_add_i32 s58, 0, 0x18000
	s_add_i32 s59, 0, 0x1c000
	v_add_u32_e32 v164, s58, v147
	v_add_u32_e32 v180, s59, v147
	ds_read_b128 v[152:155], v164
	ds_read_b128 v[156:159], v164 offset:1024
	ds_read_b128 v[160:163], v164 offset:2048
	ds_read_b128 v[164:167], v164 offset:3072
	ds_read_b128 v[168:171], v180
	ds_read_b128 v[172:175], v180 offset:1024
	ds_read_b128 v[176:179], v180 offset:2048
	ds_read_b128 v[180:183], v180 offset:3072
	s_add_u32 s22, s28, 0xb0000
	s_addc_u32 s23, s29, 0
	s_mov_b32 m0, s39
	v_lshl_add_u64 v[224:225], s[22:23], 0, v[128:129]
	ds_read_b128 v[186:189], v151 offset:32768
	ds_read_b128 v[190:193], v151 offset:33792
	ds_read_b128 v[194:197], v151 offset:34816
	ds_read_b128 v[198:201], v151 offset:35840
	ds_read_b128 v[202:205], v151 offset:36864
	ds_read_b128 v[206:209], v151 offset:37888
	ds_read_b128 v[210:213], v151 offset:38912
	ds_read_b128 v[214:217], v151 offset:39936
	global_load_lds_dwordx4 v[224:225], off
	v_lshl_add_u64 v[224:225], s[22:23], 0, v[132:133]
	s_mov_b32 m0, s40
	s_nop 0
	global_load_lds_dwordx4 v[224:225], off
	s_waitcnt vmcnt(6)
	s_waitcnt lgkmcnt(0)
	s_barrier
	s_setprio 1
	s_waitcnt lgkmcnt(0)
	v_mfma_f32_16x16x32_bf16 v[124:127], v[152:155], v[186:189], v[124:127]
	v_mfma_f32_16x16x32_bf16 v[120:123], v[160:163], v[186:189], v[120:123]
	v_mfma_f32_16x16x32_bf16 v[116:119], v[152:155], v[194:197], v[116:119]
	v_mfma_f32_16x16x32_bf16 v[108:111], v[160:163], v[194:197], v[108:111]
	v_mfma_f32_16x16x32_bf16 v[100:103], v[152:155], v[202:205], v[100:103]
	v_mfma_f32_16x16x32_bf16 v[92:95], v[160:163], v[202:205], v[92:95]
	v_mfma_f32_16x16x32_bf16 v[84:87], v[152:155], v[210:213], v[84:87]
	v_mfma_f32_16x16x32_bf16 v[76:79], v[160:163], v[210:213], v[76:79]
	v_mfma_f32_16x16x32_bf16 v[124:127], v[156:159], v[190:193], v[124:127]
	v_mfma_f32_16x16x32_bf16 v[120:123], v[164:167], v[190:193], v[120:123]
	v_mfma_f32_16x16x32_bf16 v[116:119], v[156:159], v[198:201], v[116:119]
	v_mfma_f32_16x16x32_bf16 v[108:111], v[164:167], v[198:201], v[108:111]
	v_mfma_f32_16x16x32_bf16 v[100:103], v[156:159], v[206:209], v[100:103]
	v_mfma_f32_16x16x32_bf16 v[92:95], v[164:167], v[206:209], v[92:95]
	v_mfma_f32_16x16x32_bf16 v[84:87], v[156:159], v[214:217], v[84:87]
	v_mfma_f32_16x16x32_bf16 v[76:79], v[164:167], v[214:217], v[76:79]
	s_setprio 0
	s_setprio 1
	v_mfma_f32_16x16x32_bf16 v[112:115], v[168:171], v[186:189], v[112:115]
	v_mfma_f32_16x16x32_bf16 v[104:107], v[176:179], v[186:189], v[104:107]
	v_mfma_f32_16x16x32_bf16 v[96:99], v[168:171], v[194:197], v[96:99]
	v_mfma_f32_16x16x32_bf16 v[88:91], v[176:179], v[194:197], v[88:91]
	v_mfma_f32_16x16x32_bf16 v[80:83], v[168:171], v[202:205], v[80:83]
	v_mfma_f32_16x16x32_bf16 v[72:75], v[176:179], v[202:205], v[72:75]
	v_mfma_f32_16x16x32_bf16 v[68:71], v[168:171], v[210:213], v[68:71]
	v_mfma_f32_16x16x32_bf16 v[64:67], v[176:179], v[210:213], v[64:67]
	v_mfma_f32_16x16x32_bf16 v[112:115], v[172:175], v[190:193], v[112:115]
	v_mfma_f32_16x16x32_bf16 v[104:107], v[180:183], v[190:193], v[104:107]
	v_mfma_f32_16x16x32_bf16 v[96:99], v[172:175], v[198:201], v[96:99]
	v_mfma_f32_16x16x32_bf16 v[88:91], v[180:183], v[198:201], v[88:91]
	v_mfma_f32_16x16x32_bf16 v[80:83], v[172:175], v[206:209], v[80:83]
	v_mfma_f32_16x16x32_bf16 v[72:75], v[180:183], v[206:209], v[72:75]
	v_mfma_f32_16x16x32_bf16 v[68:71], v[172:175], v[214:217], v[68:71]
	v_mfma_f32_16x16x32_bf16 v[64:67], v[180:183], v[214:217], v[64:67]
	s_setprio 0
	s_barrier
; #define PG8_STAGE(bufoff, gbase, voff) do { _Pragma("unroll") for (int _i = 0; _i < 2; ++_i) \
;         __builtin_amdgcn_global_load_lds((const unsigned*)((const char*)(gbase) + (voff)[_i]), (PG8_LAS unsigned*)(lds + (bufoff) + ldsw + _i * 8192), 16, 0, 0); } while (0)
; #define PG8_LDA(dst, b, h) do { _Pragma("unroll") for (int m = 0; m < 4; ++m) _Pragma("unroll") for (int k = 0; k < 2; ++k) dst[m][k] = *(const PG8_LAS bf16x8*)(lds + PG8_SA(b, h) + aoff + m * 2048 + k * 1024); } while (0)
; #define PG8_MMA(ai, bj, At, Bt) do { __builtin_amdgcn_s_setprio(1); _Pragma("unroll") for (int m = 0; m < 4; ++m) _Pragma("unroll") for (int n = 0; n < 2; ++n) _Pragma("unroll") for (int k = 0; k < 2; ++k) \
;         acc[ai][bj][m][n] = __builtin_amdgcn_mfma_f32_16x16x32_bf16(Bt[n][k], At[m][k], acc[ai][bj][m][n], 0, 0, 0); __builtin_amdgcn_s_setprio(0); } while (0)
; #define PG8_WAIT_V(n) asm volatile("s_waitcnt vmcnt(" #n ")" ::: "memory")
; #define PG8_WAIT_L(n) asm volatile("s_waitcnt lgkmcnt(" #n ")" ::: "memory")
; #define PG8_BAR __builtin_amdgcn_s_barrier()
; #define PG8_SCHED __builtin_amdgcn_sched_barrier(0)
; template <class Epi, class Sched, bool ALIGN_EPI = false, bool SP2 = false>
; __device__ __forceinline__ void gemm_phase(PG8_LAS unsigned char* lds, const Gemm g, const Sched& S, const Epi& E) {
;     ...
;             PG8_LDA(At, 1, 1); PG8_STAGE(PG8_SB(1, 0), b3, voffB); PG8_STAGE(PG8_SB(1, 1), b3 + hstep, voffB); PG8_STAGE(PG8_SA(1, 0), a3, voffA);
;             PG8_WAIT_V(8); PG8_WAIT_L(0); PG8_BAR; PG8_MMA(1, 0, At, B0); PG8_MMA(1, 1, At, B1); PG8_BAR; PG8_SCHED;
;     ...
;         if constexpr (ALIGN_EPI) { if (wr == 0) PG8_BAR; }
	s_add_i32 s22, s58, s36
	v_lshl_add_u64 v[144:145], v[144:145], 0, s[8:9]
	s_mov_b32 m0, s22
	ds_read_b128 v[186:189], v151 offset:49152
	ds_read_b128 v[190:193], v151 offset:50176
	ds_read_b128 v[194:197], v151 offset:51200
	ds_read_b128 v[198:201], v151 offset:52224
	ds_read_b128 v[202:205], v151 offset:53248
	ds_read_b128 v[206:209], v151 offset:54272
	ds_read_b128 v[210:213], v151 offset:55296
	ds_read_b128 v[214:217], v151 offset:56320
	global_load_lds_dwordx4 v[144:145], off
	s_add_i32 m0, s22, 0x2000
	s_add_u32 s22, s26, 0xb0080
	v_lshl_add_u64 v[144:145], v[218:219], 0, s[8:9]
	s_addc_u32 s23, s27, 0
	s_add_i32 s26, s59, s36
	global_load_lds_dwordx4 v[144:145], off
	v_lshl_add_u64 v[144:145], s[22:23], 0, v[130:131]
	s_mov_b32 m0, s26
	s_nop 0
	global_load_lds_dwordx4 v[144:145], off
	v_lshl_add_u64 v[144:145], s[22:23], 0, v[134:135]
	s_add_i32 m0, s26, 0x2000
	s_nop 0
	global_load_lds_dwordx4 v[144:145], off
	v_lshl_add_u64 v[144:145], v[220:221], 0, s[8:9]
	s_mov_b32 m0, s42
	s_nop 0
	global_load_lds_dwordx4 v[144:145], off
	v_lshl_add_u64 v[144:145], v[222:223], 0, s[8:9]
	s_mov_b32 m0, s43
	s_nop 0
	global_load_lds_dwordx4 v[144:145], off
	s_waitcnt vmcnt(6)
	s_waitcnt lgkmcnt(0)
	s_barrier
	s_setprio 1
	s_waitcnt lgkmcnt(0)
	v_mfma_f32_16x16x32_bf16 v[60:63], v[152:155], v[186:189], v[60:63]
	v_mfma_f32_16x16x32_bf16 v[56:59], v[160:163], v[186:189], v[56:59]
	v_mfma_f32_16x16x32_bf16 v[52:55], v[152:155], v[194:197], v[52:55]
	v_mfma_f32_16x16x32_bf16 v[44:47], v[160:163], v[194:197], v[44:47]
	v_mfma_f32_16x16x32_bf16 v[36:39], v[152:155], v[202:205], v[36:39]
	v_mfma_f32_16x16x32_bf16 v[28:31], v[160:163], v[202:205], v[28:31]
	v_mfma_f32_16x16x32_bf16 v[20:23], v[152:155], v[210:213], v[20:23]
	v_mfma_f32_16x16x32_bf16 v[12:15], v[160:163], v[210:213], v[12:15]
	v_mfma_f32_16x16x32_bf16 v[60:63], v[156:159], v[190:193], v[60:63]
	v_mfma_f32_16x16x32_bf16 v[56:59], v[164:167], v[190:193], v[56:59]
	v_mfma_f32_16x16x32_bf16 v[52:55], v[156:159], v[198:201], v[52:55]
	v_mfma_f32_16x16x32_bf16 v[44:47], v[164:167], v[198:201], v[44:47]
	v_mfma_f32_16x16x32_bf16 v[36:39], v[156:159], v[206:209], v[36:39]
	v_mfma_f32_16x16x32_bf16 v[28:31], v[164:167], v[206:209], v[28:31]
	v_mfma_f32_16x16x32_bf16 v[20:23], v[156:159], v[214:217], v[20:23]
	v_mfma_f32_16x16x32_bf16 v[12:15], v[164:167], v[214:217], v[12:15]
	s_setprio 0
	s_setprio 1
	v_mfma_f32_16x16x32_bf16 v[48:51], v[168:171], v[186:189], v[48:51]
	v_mfma_f32_16x16x32_bf16 v[40:43], v[176:179], v[186:189], v[40:43]
	v_mfma_f32_16x16x32_bf16 v[32:35], v[168:171], v[194:197], v[32:35]
	v_mfma_f32_16x16x32_bf16 v[24:27], v[176:179], v[194:197], v[24:27]
	v_mfma_f32_16x16x32_bf16 v[16:19], v[168:171], v[202:205], v[16:19]
	v_mfma_f32_16x16x32_bf16 v[8:11], v[176:179], v[202:205], v[8:11]
	v_mfma_f32_16x16x32_bf16 v[4:7], v[168:171], v[210:213], v[4:7]
	v_mfma_f32_16x16x32_bf16 v[0:3], v[176:179], v[210:213], v[0:3]
	v_mfma_f32_16x16x32_bf16 v[48:51], v[172:175], v[190:193], v[48:51]
	v_mfma_f32_16x16x32_bf16 v[40:43], v[180:183], v[190:193], v[40:43]
	v_mfma_f32_16x16x32_bf16 v[32:35], v[172:175], v[198:201], v[32:35]
	v_mfma_f32_16x16x32_bf16 v[24:27], v[180:183], v[198:201], v[24:27]
	v_mfma_f32_16x16x32_bf16 v[16:19], v[172:175], v[206:209], v[16:19]
	v_mfma_f32_16x16x32_bf16 v[8:11], v[180:183], v[206:209], v[8:11]
	v_mfma_f32_16x16x32_bf16 v[4:7], v[172:175], v[214:217], v[4:7]
	v_mfma_f32_16x16x32_bf16 v[0:3], v[180:183], v[214:217], v[0:3]
	s_setprio 0
	s_barrier
	s_add_i32 s57, s57, 2
	s_add_u32 s55, s55, 0x100
	s_addc_u32 s56, s56, 0
	s_cmp_gt_u32 s57, 41
	s_mov_b64 s[22:23], s[24:25]
	s_cbranch_scc0 .LBB0_1089
	s_and_b64 vcc, exec, s[10:11]
	s_cbranch_vccz .LBB0_1092
	s_barrier

; #define PG8_STAGE(bufoff, gbase, voff) do { _Pragma("unroll") for (int _i = 0; _i < 2; ++_i) \
;         __builtin_amdgcn_global_load_lds((const unsigned*)((const char*)(gbase) + (voff)[_i]), (PG8_LAS unsigned*)(lds + (bufoff) + ldsw + _i * 8192), 16, 0, 0); } while (0)
; #define PG8_LDA(dst, b, h) do { _Pragma("unroll") for (int m = 0; m < 4; ++m) _Pragma("unroll") for (int k = 0; k < 2; ++k) dst[m][k] = *(const PG8_LAS bf16x8*)(lds + PG8_SA(b, h) + aoff + m * 2048 + k * 1024); } while (0)
; #define PG8_LDB(dst, b, h) do { _Pragma("unroll") for (int n = 0; n < 2; ++n) _Pragma("unroll") for (int k = 0; k < 2; ++k) dst[n][k] = *(const PG8_LAS bf16x8*)(lds + PG8_SB(b, h) + boff + n * 2048 + k * 1024); } while (0)
; #define PG8_MMA(ai, bj, At, Bt) do { __builtin_amdgcn_s_setprio(1); _Pragma("unroll") for (int m = 0; m < 4; ++m) _Pragma("unroll") for (int n = 0; n < 2; ++n) _Pragma("unroll") for (int k = 0; k < 2; ++k) \
;         acc[ai][bj][m][n] = __builtin_amdgcn_mfma_f32_16x16x32_bf16(Bt[n][k], At[m][k], acc[ai][bj][m][n], 0, 0, 0); __builtin_amdgcn_s_setprio(0); } while (0)
; #define PG8_WAIT_V(n) asm volatile("s_waitcnt vmcnt(" #n ")" ::: "memory")
; #define PG8_WAIT_L(n) asm volatile("s_waitcnt lgkmcnt(" #n ")" ::: "memory")
; template <class Epi, class Sched, bool ALIGN_EPI = false, bool SP2 = false>
; __device__ __forceinline__ void gemm_phase(PG8_LAS unsigned char* lds, const Gemm g, const Sched& S, const Epi& E) {
;     ...
;             const bool last = (t == nt - 2);
;             const char* a1 = cA + (size_t)(t + 1) * kstep;
;             const char* a2 = last ? nA : cA + (size_t)(t + 2) * kstep; const char* b2 = last ? nB : cB + (size_t)(t + 2) * kstep;
;             const char* a3 = a2 + kstep; const char* b3 = b2 + kstep;
;             if (last && has_next) S.a_ready(nxt);
;             if constexpr (SP2) {
;             PG8_LDB(B0, 0, 0); PG8_LDB(B1, 0, 1); PG8_SCHED; PG8_LDA(At, 0, 0); PG8_STAGE(PG8_SA(1, 1), a1 + hstep, voffA);
;             PG8_WAIT_V(8); PG8_WAIT_L(0); PG8_BAR; PG8_MMA(0, 0, At, B0); PG8_MMA(0, 1, At, B1); PG8_BAR; PG8_SCHED;
;             PG8_LDA(At, 0, 1); PG8_STAGE(PG8_SB(0, 0), b2, voffB); PG8_STAGE(PG8_SB(0, 1), b2 + hstep, voffB); PG8_STAGE(PG8_SA(0, 0), a2, voffA);
;             PG8_WAIT_V(8); PG8_WAIT_L(0); PG8_BAR; PG8_MMA(1, 0, At, B0); PG8_MMA(1, 1, At, B1); PG8_BAR; PG8_SCHED;
.LBB0_1158:
	ds_read_b128 v[148:151], v145
	ds_read_b128 v[152:155], v145 offset:1024
	ds_read_b128 v[156:159], v145 offset:2048
	ds_read_b128 v[160:163], v145 offset:3072
	ds_read_b128 v[164:167], v146
	ds_read_b128 v[168:171], v146 offset:1024
	ds_read_b128 v[172:175], v146 offset:2048
	ds_read_b128 v[176:179], v146 offset:3072
	s_add_u32 s26, s24, 0x100
	s_addc_u32 s27, s25, 0
	s_cmp_eq_u32 s55, 40
	s_cselect_b32 s31, s21, s27
	s_cselect_b32 s30, s20, s26
	s_cselect_b32 s29, s23, s54
	s_cselect_b32 s28, s22, s53
	v_lshl_add_u64 v[140:141], s[24:25], 0, v[138:139]
	s_add_i32 m0, s36, 0xc000
	ds_read_b128 v[180:183], v147
	ds_read_b128 v[186:189], v147 offset:1024
	ds_read_b128 v[190:193], v147 offset:2048
	ds_read_b128 v[194:197], v147 offset:3072
	ds_read_b128 v[198:201], v147 offset:4096
	ds_read_b128 v[202:205], v147 offset:5120
	ds_read_b128 v[206:209], v147 offset:6144
	ds_read_b128 v[210:213], v147 offset:7168
	global_load_lds_dwordx4 v[140:141], off
	v_lshl_add_u64 v[140:141], s[24:25], 0, v[136:137]
	s_add_i32 m0, s36, 0xe000
	s_nop 0
	global_load_lds_dwordx4 v[140:141], off
	s_waitcnt vmcnt(6)
	s_waitcnt lgkmcnt(0)
	s_barrier
	s_setprio 1
	s_waitcnt lgkmcnt(0)
	v_mfma_f32_16x16x32_bf16 v[124:127], v[148:151], v[180:183], v[124:127]
	v_mfma_f32_16x16x32_bf16 v[120:123], v[156:159], v[180:183], v[120:123]
	v_mfma_f32_16x16x32_bf16 v[116:119], v[148:151], v[190:193], v[116:119]
	v_mfma_f32_16x16x32_bf16 v[108:111], v[156:159], v[190:193], v[108:111]
	v_mfma_f32_16x16x32_bf16 v[100:103], v[148:151], v[198:201], v[100:103]
	v_mfma_f32_16x16x32_bf16 v[92:95], v[156:159], v[198:201], v[92:95]
	v_mfma_f32_16x16x32_bf16 v[84:87], v[148:151], v[206:209], v[84:87]
	v_mfma_f32_16x16x32_bf16 v[76:79], v[156:159], v[206:209], v[76:79]
	v_mfma_f32_16x16x32_bf16 v[124:127], v[152:155], v[186:189], v[124:127]
	v_mfma_f32_16x16x32_bf16 v[120:123], v[160:163], v[186:189], v[120:123]
	v_mfma_f32_16x16x32_bf16 v[116:119], v[152:155], v[194:197], v[116:119]
	v_mfma_f32_16x16x32_bf16 v[108:111], v[160:163], v[194:197], v[108:111]
	v_mfma_f32_16x16x32_bf16 v[100:103], v[152:155], v[202:205], v[100:103]
	v_mfma_f32_16x16x32_bf16 v[92:95], v[160:163], v[202:205], v[92:95]
	v_mfma_f32_16x16x32_bf16 v[84:87], v[152:155], v[210:213], v[84:87]
	v_mfma_f32_16x16x32_bf16 v[76:79], v[160:163], v[210:213], v[76:79]
	s_setprio 0
	s_setprio 1
	v_mfma_f32_16x16x32_bf16 v[112:115], v[164:167], v[180:183], v[112:115]
	v_mfma_f32_16x16x32_bf16 v[104:107], v[172:175], v[180:183], v[104:107]
	v_mfma_f32_16x16x32_bf16 v[96:99], v[164:167], v[190:193], v[96:99]
	v_mfma_f32_16x16x32_bf16 v[88:91], v[172:175], v[190:193], v[88:91]
	v_mfma_f32_16x16x32_bf16 v[80:83], v[164:167], v[198:201], v[80:83]
	v_mfma_f32_16x16x32_bf16 v[72:75], v[172:175], v[198:201], v[72:75]
	v_mfma_f32_16x16x32_bf16 v[68:71], v[164:167], v[206:209], v[68:71]
	v_mfma_f32_16x16x32_bf16 v[64:67], v[172:175], v[206:209], v[64:67]
	v_mfma_f32_16x16x32_bf16 v[112:115], v[168:171], v[186:189], v[112:115]
	v_mfma_f32_16x16x32_bf16 v[104:107], v[176:179], v[186:189], v[104:107]
	v_mfma_f32_16x16x32_bf16 v[96:99], v[168:171], v[194:197], v[96:99]
	v_mfma_f32_16x16x32_bf16 v[88:91], v[176:179], v[194:197], v[88:91]
	v_mfma_f32_16x16x32_bf16 v[80:83], v[168:171], v[202:205], v[80:83]
	v_mfma_f32_16x16x32_bf16 v[72:75], v[176:179], v[202:205], v[72:75]
	v_mfma_f32_16x16x32_bf16 v[68:71], v[168:171], v[210:213], v[68:71]
	v_mfma_f32_16x16x32_bf16 v[64:67], v[176:179], v[210:213], v[64:67]
	s_setprio 0
	s_barrier
	s_add_i32 s24, s43, s35
	v_lshl_add_u64 v[140:141], s[28:29], 0, v[130:131]
	s_mov_b32 m0, s24
	ds_read_b128 v[180:183], v147 offset:16384
	ds_read_b128 v[186:189], v147 offset:17408
	ds_read_b128 v[190:193], v147 offset:18432
	ds_read_b128 v[194:197], v147 offset:19456
	ds_read_b128 v[198:201], v147 offset:20480
	ds_read_b128 v[202:205], v147 offset:21504
	ds_read_b128 v[206:209], v147 offset:22528
	ds_read_b128 v[210:213], v147 offset:23552
	global_load_lds_dwordx4 v[140:141], off
	s_add_i32 m0, s24, 0x2000
	s_add_u32 s24, s28, 0xb0000
	v_lshl_add_u64 v[214:215], s[28:29], 0, v[134:135]
	s_addc_u32 s25, s29, 0
	s_add_i32 s56, s93, s35
	global_load_lds_dwordx4 v[214:215], off
	v_lshl_add_u64 v[216:217], s[24:25], 0, v[130:131]
	s_mov_b32 m0, s56
	v_lshl_add_u64 v[218:219], s[30:31], 0, v[132:133]
	global_load_lds_dwordx4 v[216:217], off
	v_lshl_add_u64 v[216:217], s[24:25], 0, v[134:135]
	s_add_i32 m0, s56, 0x2000
	s_nop 0
	global_load_lds_dwordx4 v[216:217], off
	v_lshl_add_u64 v[216:217], s[30:31], 0, v[128:129]
	s_mov_b32 m0, s36
	s_nop 0
	global_load_lds_dwordx4 v[216:217], off
	s_mov_b32 m0, s37
	s_nop 0
	global_load_lds_dwordx4 v[218:219], off
	s_waitcnt vmcnt(6)
	s_waitcnt lgkmcnt(0)
	s_barrier
; #define PG8_STAGE(bufoff, gbase, voff) do { _Pragma("unroll") for (int _i = 0; _i < 2; ++_i) \
;         __builtin_amdgcn_global_load_lds((const unsigned*)((const char*)(gbase) + (voff)[_i]), (PG8_LAS unsigned*)(lds + (bufoff) + ldsw + _i * 8192), 16, 0, 0); } while (0)
; #define PG8_LDA(dst, b, h) do { _Pragma("unroll") for (int m = 0; m < 4; ++m) _Pragma("unroll") for (int k = 0; k < 2; ++k) dst[m][k] = *(const PG8_LAS bf16x8*)(lds + PG8_SA(b, h) + aoff + m * 2048 + k * 1024); } while (0)
; #define PG8_LDB(dst, b, h) do { _Pragma("unroll") for (int n = 0; n < 2; ++n) _Pragma("unroll") for (int k = 0; k < 2; ++k) dst[n][k] = *(const PG8_LAS bf16x8*)(lds + PG8_SB(b, h) + boff + n * 2048 + k * 1024); } while (0)
; #define PG8_MMA(ai, bj, At, Bt) do { __builtin_amdgcn_s_setprio(1); _Pragma("unroll") for (int m = 0; m < 4; ++m) _Pragma("unroll") for (int n = 0; n < 2; ++n) _Pragma("unroll") for (int k = 0; k < 2; ++k) \
;         acc[ai][bj][m][n] = __builtin_amdgcn_mfma_f32_16x16x32_bf16(Bt[n][k], At[m][k], acc[ai][bj][m][n], 0, 0, 0); __builtin_amdgcn_s_setprio(0); } while (0)
; #define PG8_WAIT_V(n) asm volatile("s_waitcnt vmcnt(" #n ")" ::: "memory")
; #define PG8_WAIT_L(n) asm volatile("s_waitcnt lgkmcnt(" #n ")" ::: "memory")
; #define PG8_BAR __builtin_amdgcn_s_barrier()
; #define PG8_SCHED __builtin_amdgcn_sched_barrier(0)
; template <class Epi, class Sched, bool ALIGN_EPI = false, bool SP2 = false>
; __device__ __forceinline__ void gemm_phase(PG8_LAS unsigned char* lds, const Gemm g, const Sched& S, const Epi& E) {
;     ...
;             PG8_WAIT_V(8); PG8_WAIT_L(0); PG8_BAR; PG8_MMA(1, 0, At, B0); PG8_MMA(1, 1, At, B1); PG8_BAR; PG8_SCHED;
;             PG8_LDB(B0, 1, 0); PG8_LDB(B1, 1, 1); PG8_SCHED; PG8_LDA(At, 1, 0); PG8_STAGE(PG8_SA(0, 1), a2 + hstep, voffA);
;             PG8_WAIT_V(8); PG8_WAIT_L(0); PG8_BAR; PG8_MMA(0, 0, At, B0); PG8_MMA(0, 1, At, B1); PG8_BAR; PG8_SCHED;
	s_setprio 1
	s_waitcnt lgkmcnt(0)
	v_mfma_f32_16x16x32_bf16 v[60:63], v[148:151], v[180:183], v[60:63]
	v_mfma_f32_16x16x32_bf16 v[56:59], v[156:159], v[180:183], v[56:59]
	v_mfma_f32_16x16x32_bf16 v[52:55], v[148:151], v[190:193], v[52:55]
	v_mfma_f32_16x16x32_bf16 v[44:47], v[156:159], v[190:193], v[44:47]
	v_mfma_f32_16x16x32_bf16 v[36:39], v[148:151], v[198:201], v[36:39]
	v_mfma_f32_16x16x32_bf16 v[28:31], v[156:159], v[198:201], v[28:31]
	v_mfma_f32_16x16x32_bf16 v[20:23], v[148:151], v[206:209], v[20:23]
	v_mfma_f32_16x16x32_bf16 v[12:15], v[156:159], v[206:209], v[12:15]
	v_mfma_f32_16x16x32_bf16 v[60:63], v[152:155], v[186:189], v[60:63]
	v_mfma_f32_16x16x32_bf16 v[56:59], v[160:163], v[186:189], v[56:59]
	v_mfma_f32_16x16x32_bf16 v[52:55], v[152:155], v[194:197], v[52:55]
	v_mfma_f32_16x16x32_bf16 v[44:47], v[160:163], v[194:197], v[44:47]
	v_mfma_f32_16x16x32_bf16 v[36:39], v[152:155], v[202:205], v[36:39]
	v_mfma_f32_16x16x32_bf16 v[28:31], v[160:163], v[202:205], v[28:31]
	v_mfma_f32_16x16x32_bf16 v[20:23], v[152:155], v[210:213], v[20:23]
	v_mfma_f32_16x16x32_bf16 v[12:15], v[160:163], v[210:213], v[12:15]
	s_setprio 0
	s_setprio 1
	v_mfma_f32_16x16x32_bf16 v[48:51], v[164:167], v[180:183], v[48:51]
	v_mfma_f32_16x16x32_bf16 v[40:43], v[172:175], v[180:183], v[40:43]
	v_mfma_f32_16x16x32_bf16 v[32:35], v[164:167], v[190:193], v[32:35]
	v_mfma_f32_16x16x32_bf16 v[24:27], v[172:175], v[190:193], v[24:27]
	v_mfma_f32_16x16x32_bf16 v[16:19], v[164:167], v[198:201], v[16:19]
	v_mfma_f32_16x16x32_bf16 v[8:11], v[172:175], v[198:201], v[8:11]
	v_mfma_f32_16x16x32_bf16 v[4:7], v[164:167], v[206:209], v[4:7]
	v_mfma_f32_16x16x32_bf16 v[0:3], v[172:175], v[206:209], v[0:3]
	v_mfma_f32_16x16x32_bf16 v[48:51], v[168:171], v[186:189], v[48:51]
	v_mfma_f32_16x16x32_bf16 v[40:43], v[176:179], v[186:189], v[40:43]
	v_mfma_f32_16x16x32_bf16 v[32:35], v[168:171], v[194:197], v[32:35]
	v_mfma_f32_16x16x32_bf16 v[24:27], v[176:179], v[194:197], v[24:27]
	v_mfma_f32_16x16x32_bf16 v[16:19], v[168:171], v[202:205], v[16:19]
	v_mfma_f32_16x16x32_bf16 v[8:11], v[176:179], v[202:205], v[8:11]
	v_mfma_f32_16x16x32_bf16 v[4:7], v[168:171], v[210:213], v[4:7]
	v_mfma_f32_16x16x32_bf16 v[0:3], v[176:179], v[210:213], v[0:3]
	s_setprio 0
	s_barrier
	s_add_i32 s56, 0, 0x18000
	s_add_i32 s57, 0, 0x1c000
	v_add_u32_e32 v160, s56, v143
	v_add_u32_e32 v176, s57, v143
	ds_read_b128 v[148:151], v160
	ds_read_b128 v[152:155], v160 offset:1024
	ds_read_b128 v[156:159], v160 offset:2048
	ds_read_b128 v[160:163], v160 offset:3072
	ds_read_b128 v[164:167], v176
	ds_read_b128 v[168:171], v176 offset:1024
	ds_read_b128 v[172:175], v176 offset:2048
	ds_read_b128 v[176:179], v176 offset:3072
	s_add_u32 s24, s30, 0xb0000
	s_addc_u32 s25, s31, 0
	s_mov_b32 m0, s38
	v_lshl_add_u64 v[220:221], s[24:25], 0, v[128:129]
	ds_read_b128 v[180:183], v147 offset:32768
	ds_read_b128 v[186:189], v147 offset:33792
	ds_read_b128 v[190:193], v147 offset:34816
	ds_read_b128 v[194:197], v147 offset:35840
	ds_read_b128 v[198:201], v147 offset:36864
	ds_read_b128 v[202:205], v147 offset:37888
	ds_read_b128 v[206:209], v147 offset:38912
	ds_read_b128 v[210:213], v147 offset:39936
	global_load_lds_dwordx4 v[220:221], off
	v_lshl_add_u64 v[220:221], s[24:25], 0, v[132:133]
	s_mov_b32 m0, s39
	s_nop 0
	global_load_lds_dwordx4 v[220:221], off
	s_waitcnt vmcnt(6)
	s_waitcnt lgkmcnt(0)
	s_barrier
	s_setprio 1
	s_waitcnt lgkmcnt(0)
	v_mfma_f32_16x16x32_bf16 v[124:127], v[148:151], v[180:183], v[124:127]
	v_mfma_f32_16x16x32_bf16 v[120:123], v[156:159], v[180:183], v[120:123]
	v_mfma_f32_16x16x32_bf16 v[116:119], v[148:151], v[190:193], v[116:119]
	v_mfma_f32_16x16x32_bf16 v[108:111], v[156:159], v[190:193], v[108:111]
	v_mfma_f32_16x16x32_bf16 v[100:103], v[148:151], v[198:201], v[100:103]
	v_mfma_f32_16x16x32_bf16 v[92:95], v[156:159], v[198:201], v[92:95]
	v_mfma_f32_16x16x32_bf16 v[84:87], v[148:151], v[206:209], v[84:87]
	v_mfma_f32_16x16x32_bf16 v[76:79], v[156:159], v[206:209], v[76:79]
	v_mfma_f32_16x16x32_bf16 v[124:127], v[152:155], v[186:189], v[124:127]
	v_mfma_f32_16x16x32_bf16 v[120:123], v[160:163], v[186:189], v[120:123]
	v_mfma_f32_16x16x32_bf16 v[116:119], v[152:155], v[194:197], v[116:119]
	v_mfma_f32_16x16x32_bf16 v[108:111], v[160:163], v[194:197], v[108:111]
	v_mfma_f32_16x16x32_bf16 v[100:103], v[152:155], v[202:205], v[100:103]
	v_mfma_f32_16x16x32_bf16 v[92:95], v[160:163], v[202:205], v[92:95]
	v_mfma_f32_16x16x32_bf16 v[84:87], v[152:155], v[210:213], v[84:87]
	v_mfma_f32_16x16x32_bf16 v[76:79], v[160:163], v[210:213], v[76:79]
	s_setprio 0
	s_setprio 1
	v_mfma_f32_16x16x32_bf16 v[112:115], v[164:167], v[180:183], v[112:115]
	v_mfma_f32_16x16x32_bf16 v[104:107], v[172:175], v[180:183], v[104:107]
	v_mfma_f32_16x16x32_bf16 v[96:99], v[164:167], v[190:193], v[96:99]
	v_mfma_f32_16x16x32_bf16 v[88:91], v[172:175], v[190:193], v[88:91]
	v_mfma_f32_16x16x32_bf16 v[80:83], v[164:167], v[198:201], v[80:83]
	v_mfma_f32_16x16x32_bf16 v[72:75], v[172:175], v[198:201], v[72:75]
	v_mfma_f32_16x16x32_bf16 v[68:71], v[164:167], v[206:209], v[68:71]
	v_mfma_f32_16x16x32_bf16 v[64:67], v[172:175], v[206:209], v[64:67]
	v_mfma_f32_16x16x32_bf16 v[112:115], v[168:171], v[186:189], v[112:115]
	v_mfma_f32_16x16x32_bf16 v[104:107], v[176:179], v[186:189], v[104:107]
	v_mfma_f32_16x16x32_bf16 v[96:99], v[168:171], v[194:197], v[96:99]
	v_mfma_f32_16x16x32_bf16 v[88:91], v[176:179], v[194:197], v[88:91]
	v_mfma_f32_16x16x32_bf16 v[80:83], v[168:171], v[202:205], v[80:83]
	v_mfma_f32_16x16x32_bf16 v[72:75], v[176:179], v[202:205], v[72:75]
	v_mfma_f32_16x16x32_bf16 v[68:71], v[168:171], v[210:213], v[68:71]
	v_mfma_f32_16x16x32_bf16 v[64:67], v[176:179], v[210:213], v[64:67]
	s_setprio 0
	s_barrier
; #define PG8_STAGE(bufoff, gbase, voff) do { _Pragma("unroll") for (int _i = 0; _i < 2; ++_i) \
;         __builtin_amdgcn_global_load_lds((const unsigned*)((const char*)(gbase) + (voff)[_i]), (PG8_LAS unsigned*)(lds + (bufoff) + ldsw + _i * 8192), 16, 0, 0); } while (0)
; #define PG8_LDA(dst, b, h) do { _Pragma("unroll") for (int m = 0; m < 4; ++m) _Pragma("unroll") for (int k = 0; k < 2; ++k) dst[m][k] = *(const PG8_LAS bf16x8*)(lds + PG8_SA(b, h) + aoff + m * 2048 + k * 1024); } while (0)
; #define PG8_MMA(ai, bj, At, Bt) do { __builtin_amdgcn_s_setprio(1); _Pragma("unroll") for (int m = 0; m < 4; ++m) _Pragma("unroll") for (int n = 0; n < 2; ++n) _Pragma("unroll") for (int k = 0; k < 2; ++k) \
;         acc[ai][bj][m][n] = __builtin_amdgcn_mfma_f32_16x16x32_bf16(Bt[n][k], At[m][k], acc[ai][bj][m][n], 0, 0, 0); __builtin_amdgcn_s_setprio(0); } while (0)
; #define PG8_WAIT_V(n) asm volatile("s_waitcnt vmcnt(" #n ")" ::: "memory")
; #define PG8_WAIT_L(n) asm volatile("s_waitcnt lgkmcnt(" #n ")" ::: "memory")
; #define PG8_BAR __builtin_amdgcn_s_barrier()
; #define PG8_SCHED __builtin_amdgcn_sched_barrier(0)
; template <class Epi, class Sched, bool ALIGN_EPI = false, bool SP2 = false>
; __device__ __forceinline__ void gemm_phase(PG8_LAS unsigned char* lds, const Gemm g, const Sched& S, const Epi& E) {
;     ...
;             PG8_LDA(At, 1, 1); PG8_STAGE(PG8_SB(1, 0), b3, voffB); PG8_STAGE(PG8_SB(1, 1), b3 + hstep, voffB); PG8_STAGE(PG8_SA(1, 0), a3, voffA);
;             PG8_WAIT_V(8); PG8_WAIT_L(0); PG8_BAR; PG8_MMA(1, 0, At, B0); PG8_MMA(1, 1, At, B1); PG8_BAR; PG8_SCHED;
;     ...
;         if constexpr (ALIGN_EPI) { if (wr == 0) PG8_BAR; }
	s_add_i32 s24, s56, s35
	v_lshl_add_u64 v[140:141], v[140:141], 0, s[8:9]
	s_mov_b32 m0, s24
	ds_read_b128 v[180:183], v147 offset:49152
	ds_read_b128 v[186:189], v147 offset:50176
	ds_read_b128 v[190:193], v147 offset:51200
	ds_read_b128 v[194:197], v147 offset:52224
	ds_read_b128 v[198:201], v147 offset:53248
	ds_read_b128 v[202:205], v147 offset:54272
	ds_read_b128 v[206:209], v147 offset:55296
	ds_read_b128 v[210:213], v147 offset:56320
	global_load_lds_dwordx4 v[140:141], off
	s_add_i32 m0, s24, 0x2000
	s_add_u32 s24, s28, 0xb0080
	v_lshl_add_u64 v[140:141], v[214:215], 0, s[8:9]
	s_addc_u32 s25, s29, 0
	s_add_i32 s28, s57, s35
	global_load_lds_dwordx4 v[140:141], off
	v_lshl_add_u64 v[140:141], s[24:25], 0, v[130:131]
	s_mov_b32 m0, s28
	s_nop 0
	global_load_lds_dwordx4 v[140:141], off
	v_lshl_add_u64 v[140:141], s[24:25], 0, v[134:135]
	s_add_i32 m0, s28, 0x2000
	s_nop 0
	global_load_lds_dwordx4 v[140:141], off
	v_lshl_add_u64 v[140:141], v[216:217], 0, s[8:9]
	s_mov_b32 m0, s40
	s_nop 0
	global_load_lds_dwordx4 v[140:141], off
	v_lshl_add_u64 v[140:141], v[218:219], 0, s[8:9]
	s_mov_b32 m0, s41
	s_nop 0
	global_load_lds_dwordx4 v[140:141], off
	s_waitcnt vmcnt(6)
	s_waitcnt lgkmcnt(0)
	s_barrier
	s_setprio 1
	s_waitcnt lgkmcnt(0)
	v_mfma_f32_16x16x32_bf16 v[60:63], v[148:151], v[180:183], v[60:63]
	v_mfma_f32_16x16x32_bf16 v[56:59], v[156:159], v[180:183], v[56:59]
	v_mfma_f32_16x16x32_bf16 v[52:55], v[148:151], v[190:193], v[52:55]
	v_mfma_f32_16x16x32_bf16 v[44:47], v[156:159], v[190:193], v[44:47]
	v_mfma_f32_16x16x32_bf16 v[36:39], v[148:151], v[198:201], v[36:39]
	v_mfma_f32_16x16x32_bf16 v[28:31], v[156:159], v[198:201], v[28:31]
	v_mfma_f32_16x16x32_bf16 v[20:23], v[148:151], v[206:209], v[20:23]
	v_mfma_f32_16x16x32_bf16 v[12:15], v[156:159], v[206:209], v[12:15]
	v_mfma_f32_16x16x32_bf16 v[60:63], v[152:155], v[186:189], v[60:63]
	v_mfma_f32_16x16x32_bf16 v[56:59], v[160:163], v[186:189], v[56:59]
	v_mfma_f32_16x16x32_bf16 v[52:55], v[152:155], v[194:197], v[52:55]
	v_mfma_f32_16x16x32_bf16 v[44:47], v[160:163], v[194:197], v[44:47]
	v_mfma_f32_16x16x32_bf16 v[36:39], v[152:155], v[202:205], v[36:39]
	v_mfma_f32_16x16x32_bf16 v[28:31], v[160:163], v[202:205], v[28:31]
	v_mfma_f32_16x16x32_bf16 v[20:23], v[152:155], v[210:213], v[20:23]
	v_mfma_f32_16x16x32_bf16 v[12:15], v[160:163], v[210:213], v[12:15]
	s_setprio 0
	s_setprio 1
	v_mfma_f32_16x16x32_bf16 v[48:51], v[164:167], v[180:183], v[48:51]
	v_mfma_f32_16x16x32_bf16 v[40:43], v[172:175], v[180:183], v[40:43]
	v_mfma_f32_16x16x32_bf16 v[32:35], v[164:167], v[190:193], v[32:35]
	v_mfma_f32_16x16x32_bf16 v[24:27], v[172:175], v[190:193], v[24:27]
	v_mfma_f32_16x16x32_bf16 v[16:19], v[164:167], v[198:201], v[16:19]
	v_mfma_f32_16x16x32_bf16 v[8:11], v[172:175], v[198:201], v[8:11]
	v_mfma_f32_16x16x32_bf16 v[4:7], v[164:167], v[206:209], v[4:7]
	v_mfma_f32_16x16x32_bf16 v[0:3], v[172:175], v[206:209], v[0:3]
	v_mfma_f32_16x16x32_bf16 v[48:51], v[168:171], v[186:189], v[48:51]
	v_mfma_f32_16x16x32_bf16 v[40:43], v[176:179], v[186:189], v[40:43]
	v_mfma_f32_16x16x32_bf16 v[32:35], v[168:171], v[194:197], v[32:35]
	v_mfma_f32_16x16x32_bf16 v[24:27], v[176:179], v[194:197], v[24:27]
	v_mfma_f32_16x16x32_bf16 v[16:19], v[168:171], v[202:205], v[16:19]
	v_mfma_f32_16x16x32_bf16 v[8:11], v[176:179], v[202:205], v[8:11]
	v_mfma_f32_16x16x32_bf16 v[4:7], v[168:171], v[210:213], v[4:7]
	v_mfma_f32_16x16x32_bf16 v[0:3], v[176:179], v[210:213], v[0:3]
	s_setprio 0
	s_barrier
	s_add_i32 s55, s55, 2
	s_add_u32 s53, s53, 0x100
	s_addc_u32 s54, s54, 0
	s_cmp_gt_u32 s55, 41
	s_mov_b64 s[24:25], s[26:27]
	s_cbranch_scc0 .LBB0_1158
	s_and_b64 vcc, exec, s[10:11]
	s_cbranch_vccz .LBB0_1161
	s_barrier
